# speedup vs baseline: 1.0221x; 1.0129x over previous
; #define WAIT_V(n) asm volatile("s_waitcnt vmcnt(%0)" ::"n"(n) : "memory")
; template <bool PRO>
; __device__ __forceinline__ void gemm_mainloop(const u16* __restrict__ Ab, const u16* __restrict__ Bb, int K,
;                                               f32x4 (&acc)[8][4]) {
;     ...
;   const int nt = K / BK;
;   if (PRO) GLDS_STAGE(0, 0);
;   WAIT_V(0);
;   __syncthreads();
;   for (int t = 0; t < nt; ++t) {
;     int cur = t & 1;
;     if (t + 1 < nt) GLDS_STAGE(cur ^ 1, t + 1);
;     __builtin_amdgcn_sched_barrier(0);
;     KSTEP(cur, 0);
;     KSTEP(cur, 1);
;     WAIT_V(0);
;     __syncthreads();
;   }
.LBB0_99:
	s_waitcnt lgkmcnt(7)
	v_mfma_f32_16x16x32_bf16 v[124:127], v[150:153], v[178:181], v[124:127]
	v_mfma_f32_16x16x32_bf16 v[108:111], v[154:157], v[178:181], v[108:111]
	v_lshl_add_u64 v[252:253], v[132:133], 0, s[0:1]
	v_lshl_add_u64 v[254:255], v[252:253], 0, s[30:31]
	global_load_lds_dwordx4 v[254:255], off
	s_add_u32 m0, m0, 0x2000
	v_mfma_f32_16x16x32_bf16 v[92:95], v[158:161], v[178:181], v[92:95]
	v_mfma_f32_16x16x32_bf16 v[76:79], v[162:165], v[178:181], v[76:79]
	s_waitcnt lgkmcnt(6)
	v_mfma_f32_16x16x32_bf16 v[120:123], v[150:153], v[186:189], v[120:123]
	v_lshl_add_u64 v[254:255], v[252:253], 0, s[36:37]
	global_load_lds_dwordx4 v[254:255], off
	s_add_u32 m0, m0, 0x2000
	v_mfma_f32_16x16x32_bf16 v[104:107], v[154:157], v[186:189], v[104:107]
	v_mfma_f32_16x16x32_bf16 v[88:91], v[158:161], v[186:189], v[88:91]
	v_mfma_f32_16x16x32_bf16 v[72:75], v[162:165], v[186:189], v[72:75]
	v_lshl_add_u64 v[254:255], v[252:253], 0, s[40:41]
	global_load_lds_dwordx4 v[254:255], off
	s_add_u32 m0, m0, 0x2000
	s_waitcnt lgkmcnt(5)
	v_mfma_f32_16x16x32_bf16 v[116:119], v[150:153], v[190:193], v[116:119]
	v_mfma_f32_16x16x32_bf16 v[100:103], v[154:157], v[190:193], v[100:103]
	v_mfma_f32_16x16x32_bf16 v[84:87], v[158:161], v[190:193], v[84:87]
	v_lshl_add_u64 v[254:255], v[252:253], 0, s[44:45]
	global_load_lds_dwordx4 v[254:255], off
	v_mfma_f32_16x16x32_bf16 v[68:71], v[162:165], v[190:193], v[68:71]
	s_waitcnt lgkmcnt(1)
	v_mfma_f32_16x16x32_bf16 v[112:115], v[150:153], v[194:197], v[112:115]
	ds_read_b128 v[150:153], v198 offset:1024
	v_mfma_f32_16x16x32_bf16 v[96:99], v[154:157], v[194:197], v[96:99]
	ds_read_b128 v[154:157], v199 offset:1024
	v_mfma_f32_16x16x32_bf16 v[80:83], v[158:161], v[194:197], v[80:83]
	ds_read_b128 v[158:161], v200 offset:1024
	v_mfma_f32_16x16x32_bf16 v[64:67], v[162:165], v[194:197], v[64:67]
	ds_read_b128 v[162:165], v201 offset:1024
	v_mfma_f32_16x16x32_bf16 v[60:63], v[166:169], v[178:181], v[60:63]
	v_mfma_f32_16x16x32_bf16 v[44:47], v[170:173], v[178:181], v[44:47]
	v_mfma_f32_16x16x32_bf16 v[28:31], v[174:177], v[178:181], v[28:31]
	s_waitcnt lgkmcnt(4)
	v_mfma_f32_16x16x32_bf16 v[12:15], v[182:185], v[178:181], v[12:15]
	ds_read_b128 v[178:181], v149 offset:33792
	v_mfma_f32_16x16x32_bf16 v[56:59], v[166:169], v[186:189], v[56:59]
	v_mfma_f32_16x16x32_bf16 v[40:43], v[170:173], v[186:189], v[40:43]
	v_mfma_f32_16x16x32_bf16 v[24:27], v[174:177], v[186:189], v[24:27]
	v_mfma_f32_16x16x32_bf16 v[8:11], v[182:185], v[186:189], v[8:11]
	ds_read_b128 v[186:189], v149 offset:35840
	v_mfma_f32_16x16x32_bf16 v[52:55], v[166:169], v[190:193], v[52:55]
	v_mfma_f32_16x16x32_bf16 v[36:39], v[170:173], v[190:193], v[36:39]
	v_mfma_f32_16x16x32_bf16 v[20:23], v[174:177], v[190:193], v[20:23]
	v_mfma_f32_16x16x32_bf16 v[4:7], v[182:185], v[190:193], v[4:7]
	ds_read_b128 v[190:193], v149 offset:37888
	v_mfma_f32_16x16x32_bf16 v[48:51], v[166:169], v[194:197], v[48:51]
	ds_read_b128 v[166:169], v202 offset:1024
	v_mfma_f32_16x16x32_bf16 v[32:35], v[170:173], v[194:197], v[32:35]
	ds_read_b128 v[170:173], v203 offset:1024
	v_mfma_f32_16x16x32_bf16 v[16:19], v[174:177], v[194:197], v[16:19]
	ds_read_b128 v[174:177], v206 offset:1024
	v_mfma_f32_16x16x32_bf16 v[0:3], v[182:185], v[194:197], v[0:3]
	ds_read_b128 v[194:197], v149 offset:39936
	ds_read_b128 v[182:185], v207 offset:1024
	s_waitcnt lgkmcnt(7)
	v_mfma_f32_16x16x32_bf16 v[124:127], v[150:153], v[178:181], v[124:127]
	v_mfma_f32_16x16x32_bf16 v[108:111], v[154:157], v[178:181], v[108:111]
	v_mfma_f32_16x16x32_bf16 v[92:95], v[158:161], v[178:181], v[92:95]
	v_mfma_f32_16x16x32_bf16 v[76:79], v[162:165], v[178:181], v[76:79]
	s_waitcnt lgkmcnt(6)
	v_mfma_f32_16x16x32_bf16 v[120:123], v[150:153], v[186:189], v[120:123]
	v_mfma_f32_16x16x32_bf16 v[104:107], v[154:157], v[186:189], v[104:107]
	v_mfma_f32_16x16x32_bf16 v[88:91], v[158:161], v[186:189], v[88:91]
	v_mfma_f32_16x16x32_bf16 v[72:75], v[162:165], v[186:189], v[72:75]
	s_waitcnt lgkmcnt(5)
	v_mfma_f32_16x16x32_bf16 v[116:119], v[150:153], v[190:193], v[116:119]
	v_mfma_f32_16x16x32_bf16 v[100:103], v[154:157], v[190:193], v[100:103]
	v_mfma_f32_16x16x32_bf16 v[84:87], v[158:161], v[190:193], v[84:87]
	v_mfma_f32_16x16x32_bf16 v[68:71], v[162:165], v[190:193], v[68:71]
	s_waitcnt lgkmcnt(1)
	v_mfma_f32_16x16x32_bf16 v[112:115], v[150:153], v[194:197], v[112:115]
	v_mfma_f32_16x16x32_bf16 v[96:99], v[154:157], v[194:197], v[96:99]
	v_mfma_f32_16x16x32_bf16 v[80:83], v[158:161], v[194:197], v[80:83]
	v_mfma_f32_16x16x32_bf16 v[64:67], v[162:165], v[194:197], v[64:67]
	s_add_i32 s4, s4, 0x10000
	s_add_u32 s0, s0, 0x80
	s_addc_u32 s1, s1, 0
	s_cmpk_lg_i32 s0, 0x780
	s_waitcnt vmcnt(0) lgkmcnt(0)
	s_barrier
; #define WAIT_V(n) asm volatile("s_waitcnt vmcnt(%0)" ::"n"(n) : "memory")
; template <bool PRO>
; __device__ __forceinline__ void gemm_mainloop(const u16* __restrict__ Ab, const u16* __restrict__ Bb, int K,
;                                               f32x4 (&acc)[8][4]) {
;     ...
;   const int nt = K / BK;
;   if (PRO) GLDS_STAGE(0, 0);
;   WAIT_V(0);
;   __syncthreads();
;   for (int t = 0; t < nt; ++t) {
;     int cur = t & 1;
;     if (t + 1 < nt) GLDS_STAGE(cur ^ 1, t + 1);
;     __builtin_amdgcn_sched_barrier(0);
;     KSTEP(cur, 0);
;     KSTEP(cur, 1);
;     WAIT_V(0);
;     __syncthreads();
;   }
	s_cbranch_scc0 .Lpipe_exit_99
	s_and_b32 s5, s4, 0x10000
	v_or_b32_e32 v247, s5, v139
	v_or_b32_e32 v248, s5, v140
	v_add_u32_e32 v198, v247, v147
	v_add_u32_e32 v199, v248, v145
	v_mfma_f32_16x16x32_bf16 v[60:63], v[166:169], v[178:181], v[60:63]
	v_add_u32_e32 v200, v248, v148
	v_add_u32_e32 v201, v248, v146
	v_add_u32_e32 v202, v248, v144
	v_add_u32_e32 v203, v248, v143
	v_mfma_f32_16x16x32_bf16 v[44:47], v[170:173], v[178:181], v[44:47]
	v_add_u32_e32 v206, v248, v142
	v_add_u32_e32 v207, v248, v141
	v_add_u32_e32 v249, v247, v137
	v_or_b32_e32 v149, s5, v128
	v_mfma_f32_16x16x32_bf16 v[28:31], v[174:177], v[178:181], v[28:31]
	ds_read_b128 v[150:153], v198
	ds_read_b128 v[154:157], v199
	v_mfma_f32_16x16x32_bf16 v[12:15], v[182:185], v[178:181], v[12:15]
	ds_read_b128 v[158:161], v200
	ds_read_b128 v[162:165], v201
	v_mfma_f32_16x16x32_bf16 v[56:59], v[166:169], v[186:189], v[56:59]
	ds_read_b128 v[178:181], v249 offset:32768
	s_xor_b32 s6, s5, 0x10000
	v_add_u32_e32 v250, s6, v138
	v_mfma_f32_16x16x32_bf16 v[40:43], v[170:173], v[186:189], v[40:43]
	v_lshl_add_u64 v[252:253], v[130:131], 0, s[0:1]
	v_readfirstlane_b32 s6, v250
	s_mov_b32 m0, s6
	v_mfma_f32_16x16x32_bf16 v[24:27], v[174:177], v[186:189], v[24:27]
	v_lshl_add_u64 v[254:255], v[252:253], 0, s[28:29]
	global_load_lds_dwordx4 v[254:255], off
	s_add_u32 m0, m0, 0x2000
	v_mfma_f32_16x16x32_bf16 v[8:11], v[182:185], v[186:189], v[8:11]
	ds_read_b128 v[186:189], v249 offset:34816
	v_mfma_f32_16x16x32_bf16 v[52:55], v[166:169], v[190:193], v[52:55]
	v_lshl_add_u64 v[254:255], v[252:253], 0, s[34:35]
	global_load_lds_dwordx4 v[254:255], off
	s_add_u32 m0, m0, 0x2000
	v_mfma_f32_16x16x32_bf16 v[36:39], v[170:173], v[190:193], v[36:39]
	v_mfma_f32_16x16x32_bf16 v[20:23], v[174:177], v[190:193], v[20:23]
	v_lshl_add_u64 v[254:255], v[252:253], 0, s[38:39]
	global_load_lds_dwordx4 v[254:255], off
	s_add_u32 m0, m0, 0x2000
	v_mfma_f32_16x16x32_bf16 v[4:7], v[182:185], v[190:193], v[4:7]
	ds_read_b128 v[190:193], v249 offset:36864
	v_mfma_f32_16x16x32_bf16 v[48:51], v[166:169], v[194:197], v[48:51]
	ds_read_b128 v[166:169], v202
	v_lshl_add_u64 v[254:255], v[252:253], 0, s[42:43]
	global_load_lds_dwordx4 v[254:255], off
	s_add_u32 m0, m0, 0x2000
	v_mfma_f32_16x16x32_bf16 v[32:35], v[170:173], v[194:197], v[32:35]
	ds_read_b128 v[170:173], v203
	v_mfma_f32_16x16x32_bf16 v[16:19], v[174:177], v[194:197], v[16:19]
	ds_read_b128 v[174:177], v206
	v_mfma_f32_16x16x32_bf16 v[0:3], v[182:185], v[194:197], v[0:3]
	ds_read_b128 v[194:197], v249 offset:38912
	ds_read_b128 v[182:185], v207
	s_branch .LBB0_99

; #define WAIT_V(n) asm volatile("s_waitcnt vmcnt(%0)" ::"n"(n) : "memory")
; template <bool PRO>
; __device__ __forceinline__ void gemm_mainloop(const u16* __restrict__ Ab, const u16* __restrict__ Bb, int K,
;                                               f32x4 (&acc)[8][4]) {
;     ...
;   const int nt = K / BK;
;   if (PRO) GLDS_STAGE(0, 0);
;   WAIT_V(0);
;   __syncthreads();
;   for (int t = 0; t < nt; ++t) {
;     int cur = t & 1;
;     if (t + 1 < nt) GLDS_STAGE(cur ^ 1, t + 1);
;     __builtin_amdgcn_sched_barrier(0);
;     KSTEP(cur, 0);
;     KSTEP(cur, 1);
;     WAIT_V(0);
;     __syncthreads();
;   }
.LBB0_119:
	s_waitcnt lgkmcnt(7)
	v_mfma_f32_16x16x32_bf16 v[124:127], v[150:153], v[178:181], v[124:127]
	v_mfma_f32_16x16x32_bf16 v[108:111], v[154:157], v[178:181], v[108:111]
	v_lshl_add_u64 v[252:253], v[128:129], 0, s[0:1]
	v_lshl_add_u64 v[254:255], v[252:253], 0, s[16:17]
	global_load_lds_dwordx4 v[254:255], off
	s_add_u32 m0, m0, 0x2000
	v_mfma_f32_16x16x32_bf16 v[92:95], v[158:161], v[178:181], v[92:95]
	v_mfma_f32_16x16x32_bf16 v[76:79], v[162:165], v[178:181], v[76:79]
	s_waitcnt lgkmcnt(6)
	v_mfma_f32_16x16x32_bf16 v[120:123], v[150:153], v[186:189], v[120:123]
	v_lshl_add_u64 v[254:255], v[252:253], 0, s[20:21]
	global_load_lds_dwordx4 v[254:255], off
	s_add_u32 m0, m0, 0x2000
	v_mfma_f32_16x16x32_bf16 v[104:107], v[154:157], v[186:189], v[104:107]
	v_mfma_f32_16x16x32_bf16 v[88:91], v[158:161], v[186:189], v[88:91]
	v_mfma_f32_16x16x32_bf16 v[72:75], v[162:165], v[186:189], v[72:75]
	v_lshl_add_u64 v[254:255], v[252:253], 0, s[24:25]
	global_load_lds_dwordx4 v[254:255], off
	s_add_u32 m0, m0, 0x2000
	s_waitcnt lgkmcnt(5)
	v_mfma_f32_16x16x32_bf16 v[116:119], v[150:153], v[190:193], v[116:119]
	v_mfma_f32_16x16x32_bf16 v[100:103], v[154:157], v[190:193], v[100:103]
	v_mfma_f32_16x16x32_bf16 v[84:87], v[158:161], v[190:193], v[84:87]
	v_lshl_add_u64 v[254:255], v[252:253], 0, s[28:29]
	global_load_lds_dwordx4 v[254:255], off
	v_mfma_f32_16x16x32_bf16 v[68:71], v[162:165], v[190:193], v[68:71]
	s_waitcnt lgkmcnt(1)
	v_mfma_f32_16x16x32_bf16 v[112:115], v[150:153], v[194:197], v[112:115]
	ds_read_b128 v[150:153], v198 offset:1024
	v_mfma_f32_16x16x32_bf16 v[96:99], v[154:157], v[194:197], v[96:99]
	ds_read_b128 v[154:157], v199 offset:1024
	v_mfma_f32_16x16x32_bf16 v[80:83], v[158:161], v[194:197], v[80:83]
	ds_read_b128 v[158:161], v200 offset:1024
	v_mfma_f32_16x16x32_bf16 v[64:67], v[162:165], v[194:197], v[64:67]
	ds_read_b128 v[162:165], v201 offset:1024
	v_mfma_f32_16x16x32_bf16 v[60:63], v[166:169], v[178:181], v[60:63]
	v_mfma_f32_16x16x32_bf16 v[44:47], v[170:173], v[178:181], v[44:47]
	v_mfma_f32_16x16x32_bf16 v[28:31], v[174:177], v[178:181], v[28:31]
	s_waitcnt lgkmcnt(4)
	v_mfma_f32_16x16x32_bf16 v[12:15], v[182:185], v[178:181], v[12:15]
	ds_read_b128 v[178:181], v149 offset:33792
	v_mfma_f32_16x16x32_bf16 v[56:59], v[166:169], v[186:189], v[56:59]
	v_mfma_f32_16x16x32_bf16 v[40:43], v[170:173], v[186:189], v[40:43]
	v_mfma_f32_16x16x32_bf16 v[24:27], v[174:177], v[186:189], v[24:27]
	v_mfma_f32_16x16x32_bf16 v[8:11], v[182:185], v[186:189], v[8:11]
	ds_read_b128 v[186:189], v149 offset:35840
	v_mfma_f32_16x16x32_bf16 v[52:55], v[166:169], v[190:193], v[52:55]
	v_mfma_f32_16x16x32_bf16 v[36:39], v[170:173], v[190:193], v[36:39]
	v_mfma_f32_16x16x32_bf16 v[20:23], v[174:177], v[190:193], v[20:23]
	v_mfma_f32_16x16x32_bf16 v[4:7], v[182:185], v[190:193], v[4:7]
	ds_read_b128 v[190:193], v149 offset:37888
	v_mfma_f32_16x16x32_bf16 v[48:51], v[166:169], v[194:197], v[48:51]
	ds_read_b128 v[166:169], v202 offset:1024
	v_mfma_f32_16x16x32_bf16 v[32:35], v[170:173], v[194:197], v[32:35]
	ds_read_b128 v[170:173], v203 offset:1024
	v_mfma_f32_16x16x32_bf16 v[16:19], v[174:177], v[194:197], v[16:19]
	ds_read_b128 v[174:177], v206 offset:1024
	v_mfma_f32_16x16x32_bf16 v[0:3], v[182:185], v[194:197], v[0:3]
	ds_read_b128 v[194:197], v149 offset:39936
	ds_read_b128 v[182:185], v207 offset:1024
	s_waitcnt lgkmcnt(7)
	v_mfma_f32_16x16x32_bf16 v[124:127], v[150:153], v[178:181], v[124:127]
	v_mfma_f32_16x16x32_bf16 v[108:111], v[154:157], v[178:181], v[108:111]
	v_mfma_f32_16x16x32_bf16 v[92:95], v[158:161], v[178:181], v[92:95]
	v_mfma_f32_16x16x32_bf16 v[76:79], v[162:165], v[178:181], v[76:79]
	s_waitcnt lgkmcnt(6)
	v_mfma_f32_16x16x32_bf16 v[120:123], v[150:153], v[186:189], v[120:123]
	v_mfma_f32_16x16x32_bf16 v[104:107], v[154:157], v[186:189], v[104:107]
	v_mfma_f32_16x16x32_bf16 v[88:91], v[158:161], v[186:189], v[88:91]
	v_mfma_f32_16x16x32_bf16 v[72:75], v[162:165], v[186:189], v[72:75]
	s_waitcnt lgkmcnt(5)
	v_mfma_f32_16x16x32_bf16 v[116:119], v[150:153], v[190:193], v[116:119]
	v_mfma_f32_16x16x32_bf16 v[100:103], v[154:157], v[190:193], v[100:103]
	v_mfma_f32_16x16x32_bf16 v[84:87], v[158:161], v[190:193], v[84:87]
	v_mfma_f32_16x16x32_bf16 v[68:71], v[162:165], v[190:193], v[68:71]
	s_waitcnt lgkmcnt(1)
	v_mfma_f32_16x16x32_bf16 v[112:115], v[150:153], v[194:197], v[112:115]
	v_mfma_f32_16x16x32_bf16 v[96:99], v[154:157], v[194:197], v[96:99]
	v_mfma_f32_16x16x32_bf16 v[80:83], v[158:161], v[194:197], v[80:83]
	v_mfma_f32_16x16x32_bf16 v[64:67], v[162:165], v[194:197], v[64:67]
	s_add_u32 s0, s0, 0x80
	s_addc_u32 s1, s1, 0
	s_add_i32 s38, s38, 0x10000
	s_cmpk_lg_i32 s0, 0x1580
	s_waitcnt vmcnt(0) lgkmcnt(0)
	s_barrier
; #define WAIT_V(n) asm volatile("s_waitcnt vmcnt(%0)" ::"n"(n) : "memory")
; template <bool PRO>
; __device__ __forceinline__ void gemm_mainloop(const u16* __restrict__ Ab, const u16* __restrict__ Bb, int K,
;                                               f32x4 (&acc)[8][4]) {
;     ...
;   const int nt = K / BK;
;   if (PRO) GLDS_STAGE(0, 0);
;   WAIT_V(0);
;   __syncthreads();
;   for (int t = 0; t < nt; ++t) {
;     int cur = t & 1;
;     if (t + 1 < nt) GLDS_STAGE(cur ^ 1, t + 1);
;     __builtin_amdgcn_sched_barrier(0);
;     KSTEP(cur, 0);
;     KSTEP(cur, 1);
;     WAIT_V(0);
;     __syncthreads();
;   }
	s_cbranch_scc0 .Lpipe_exit_119
	s_and_b32 s39, s38, 0x10000
	v_or_b32_e32 v247, s39, v139
	v_or_b32_e32 v248, s39, v140
	v_add_u32_e32 v198, v247, v147
	v_add_u32_e32 v199, v248, v145
	v_mfma_f32_16x16x32_bf16 v[60:63], v[166:169], v[178:181], v[60:63]
	v_add_u32_e32 v200, v248, v148
	v_add_u32_e32 v201, v248, v146
	v_add_u32_e32 v202, v248, v144
	v_add_u32_e32 v203, v248, v143
	v_mfma_f32_16x16x32_bf16 v[44:47], v[170:173], v[178:181], v[44:47]
	v_add_u32_e32 v206, v248, v142
	v_add_u32_e32 v207, v248, v141
	v_add_u32_e32 v249, v247, v137
	v_or_b32_e32 v149, s39, v136
	v_mfma_f32_16x16x32_bf16 v[28:31], v[174:177], v[178:181], v[28:31]
	ds_read_b128 v[150:153], v198
	ds_read_b128 v[154:157], v199
	v_mfma_f32_16x16x32_bf16 v[12:15], v[182:185], v[178:181], v[12:15]
	ds_read_b128 v[158:161], v200
	ds_read_b128 v[162:165], v201
	v_mfma_f32_16x16x32_bf16 v[56:59], v[166:169], v[186:189], v[56:59]
	ds_read_b128 v[178:181], v249 offset:32768
	s_xor_b32 s52, s39, 0x10000
	v_add_u32_e32 v250, s52, v138
	v_mfma_f32_16x16x32_bf16 v[40:43], v[170:173], v[186:189], v[40:43]
	v_lshl_add_u64 v[252:253], v[130:131], 0, s[0:1]
	v_readfirstlane_b32 s52, v250
	s_mov_b32 m0, s52
	v_mfma_f32_16x16x32_bf16 v[24:27], v[174:177], v[186:189], v[24:27]
	v_lshl_add_u64 v[254:255], v[252:253], 0, s[14:15]
	global_load_lds_dwordx4 v[254:255], off
	s_add_u32 m0, m0, 0x2000
	v_mfma_f32_16x16x32_bf16 v[8:11], v[182:185], v[186:189], v[8:11]
	ds_read_b128 v[186:189], v249 offset:34816
	v_mfma_f32_16x16x32_bf16 v[52:55], v[166:169], v[190:193], v[52:55]
	v_lshl_add_u64 v[254:255], v[252:253], 0, s[18:19]
	global_load_lds_dwordx4 v[254:255], off
	s_add_u32 m0, m0, 0x2000
	v_mfma_f32_16x16x32_bf16 v[36:39], v[170:173], v[190:193], v[36:39]
	v_mfma_f32_16x16x32_bf16 v[20:23], v[174:177], v[190:193], v[20:23]
	v_lshl_add_u64 v[254:255], v[252:253], 0, s[22:23]
	global_load_lds_dwordx4 v[254:255], off
	s_add_u32 m0, m0, 0x2000
	v_mfma_f32_16x16x32_bf16 v[4:7], v[182:185], v[190:193], v[4:7]
	ds_read_b128 v[190:193], v249 offset:36864
	v_mfma_f32_16x16x32_bf16 v[48:51], v[166:169], v[194:197], v[48:51]
	ds_read_b128 v[166:169], v202
	v_lshl_add_u64 v[254:255], v[252:253], 0, s[26:27]
	global_load_lds_dwordx4 v[254:255], off
	s_add_u32 m0, m0, 0x2000
	v_mfma_f32_16x16x32_bf16 v[32:35], v[170:173], v[194:197], v[32:35]
	ds_read_b128 v[170:173], v203
	v_mfma_f32_16x16x32_bf16 v[16:19], v[174:177], v[194:197], v[16:19]
	ds_read_b128 v[174:177], v206
	v_mfma_f32_16x16x32_bf16 v[0:3], v[182:185], v[194:197], v[0:3]
	ds_read_b128 v[194:197], v249 offset:38912
	ds_read_b128 v[182:185], v207
	s_branch .LBB0_119

; #define WAIT_V(n) asm volatile("s_waitcnt vmcnt(%0)" ::"n"(n) : "memory")
; template <bool PRO>
; __device__ __forceinline__ void gemm_mainloop(const u16* __restrict__ Ab, const u16* __restrict__ Bb, int K,
;                                               f32x4 (&acc)[8][4]) {
;     ...
;   const int nt = K / BK;
;   if (PRO) GLDS_STAGE(0, 0);
;   WAIT_V(0);
;   __syncthreads();
;   for (int t = 0; t < nt; ++t) {
;     int cur = t & 1;
;     if (t + 1 < nt) GLDS_STAGE(cur ^ 1, t + 1);
;     __builtin_amdgcn_sched_barrier(0);
;     KSTEP(cur, 0);
;     KSTEP(cur, 1);
;     WAIT_V(0);
;     __syncthreads();
;   }
.LBB0_221:
	s_waitcnt lgkmcnt(7)
	v_mfma_f32_16x16x32_bf16 v[124:127], v[146:149], v[174:177], v[124:127]
	v_mfma_f32_16x16x32_bf16 v[108:111], v[150:153], v[174:177], v[108:111]
	v_lshl_add_u64 v[252:253], v[132:133], 0, s[0:1]
	s_mov_b64 s[4:5], 0x32390080
	v_lshl_add_u64 v[254:255], v[252:253], 0, s[4:5]
	global_load_lds_dwordx4 v[254:255], off
	s_add_u32 m0, m0, 0x2000
	v_mfma_f32_16x16x32_bf16 v[92:95], v[154:157], v[174:177], v[92:95]
	v_mfma_f32_16x16x32_bf16 v[76:79], v[158:161], v[174:177], v[76:79]
	s_waitcnt lgkmcnt(6)
	v_mfma_f32_16x16x32_bf16 v[120:123], v[146:149], v[182:185], v[120:123]
	v_lshl_add_u64 v[254:255], v[252:253], 0, s[66:67]
	global_load_lds_dwordx4 v[254:255], off
	s_add_u32 m0, m0, 0x2000
	v_mfma_f32_16x16x32_bf16 v[104:107], v[150:153], v[182:185], v[104:107]
	v_mfma_f32_16x16x32_bf16 v[88:91], v[154:157], v[182:185], v[88:91]
	v_mfma_f32_16x16x32_bf16 v[72:75], v[158:161], v[182:185], v[72:75]
	v_lshl_add_u64 v[254:255], v[252:253], 0, s[70:71]
	global_load_lds_dwordx4 v[254:255], off
	s_add_u32 m0, m0, 0x2000
	s_waitcnt lgkmcnt(5)
	v_mfma_f32_16x16x32_bf16 v[116:119], v[146:149], v[186:189], v[116:119]
	v_mfma_f32_16x16x32_bf16 v[100:103], v[150:153], v[186:189], v[100:103]
	v_mfma_f32_16x16x32_bf16 v[84:87], v[154:157], v[186:189], v[84:87]
	v_lshl_add_u64 v[254:255], v[252:253], 0, s[74:75]
	global_load_lds_dwordx4 v[254:255], off
	v_mfma_f32_16x16x32_bf16 v[68:71], v[158:161], v[186:189], v[68:71]
	s_waitcnt lgkmcnt(1)
	v_mfma_f32_16x16x32_bf16 v[112:115], v[146:149], v[190:193], v[112:115]
	ds_read_b128 v[146:149], v194 offset:1024
	v_mfma_f32_16x16x32_bf16 v[96:99], v[150:153], v[190:193], v[96:99]
	ds_read_b128 v[150:153], v195 offset:1024
	v_mfma_f32_16x16x32_bf16 v[80:83], v[154:157], v[190:193], v[80:83]
	ds_read_b128 v[154:157], v196 offset:1024
	v_mfma_f32_16x16x32_bf16 v[64:67], v[158:161], v[190:193], v[64:67]
	ds_read_b128 v[158:161], v197 offset:1024
	v_mfma_f32_16x16x32_bf16 v[60:63], v[162:165], v[174:177], v[60:63]
	v_mfma_f32_16x16x32_bf16 v[44:47], v[166:169], v[174:177], v[44:47]
	v_mfma_f32_16x16x32_bf16 v[28:31], v[170:173], v[174:177], v[28:31]
	s_waitcnt lgkmcnt(4)
	v_mfma_f32_16x16x32_bf16 v[12:15], v[178:181], v[174:177], v[12:15]
	ds_read_b128 v[174:177], v250 offset:33792
	v_mfma_f32_16x16x32_bf16 v[56:59], v[162:165], v[182:185], v[56:59]
	v_mfma_f32_16x16x32_bf16 v[40:43], v[166:169], v[182:185], v[40:43]
	v_mfma_f32_16x16x32_bf16 v[24:27], v[170:173], v[182:185], v[24:27]
	v_mfma_f32_16x16x32_bf16 v[8:11], v[178:181], v[182:185], v[8:11]
	ds_read_b128 v[182:185], v250 offset:35840
	v_mfma_f32_16x16x32_bf16 v[52:55], v[162:165], v[186:189], v[52:55]
	v_mfma_f32_16x16x32_bf16 v[36:39], v[166:169], v[186:189], v[36:39]
	v_mfma_f32_16x16x32_bf16 v[20:23], v[170:173], v[186:189], v[20:23]
	v_mfma_f32_16x16x32_bf16 v[4:7], v[178:181], v[186:189], v[4:7]
	ds_read_b128 v[186:189], v250 offset:37888
	v_mfma_f32_16x16x32_bf16 v[48:51], v[162:165], v[190:193], v[48:51]
	ds_read_b128 v[162:165], v198 offset:1024
	v_mfma_f32_16x16x32_bf16 v[32:35], v[166:169], v[190:193], v[32:35]
	ds_read_b128 v[166:169], v199 offset:1024
	v_mfma_f32_16x16x32_bf16 v[16:19], v[170:173], v[190:193], v[16:19]
	ds_read_b128 v[170:173], v200 offset:1024
	v_mfma_f32_16x16x32_bf16 v[0:3], v[178:181], v[190:193], v[0:3]
	ds_read_b128 v[190:193], v250 offset:39936
	ds_read_b128 v[178:181], v201 offset:1024
	s_waitcnt lgkmcnt(7)
	v_mfma_f32_16x16x32_bf16 v[124:127], v[146:149], v[174:177], v[124:127]
	v_mfma_f32_16x16x32_bf16 v[108:111], v[150:153], v[174:177], v[108:111]
	v_mfma_f32_16x16x32_bf16 v[92:95], v[154:157], v[174:177], v[92:95]
	v_mfma_f32_16x16x32_bf16 v[76:79], v[158:161], v[174:177], v[76:79]
	s_waitcnt lgkmcnt(6)
	v_mfma_f32_16x16x32_bf16 v[120:123], v[146:149], v[182:185], v[120:123]
	v_mfma_f32_16x16x32_bf16 v[104:107], v[150:153], v[182:185], v[104:107]
	v_mfma_f32_16x16x32_bf16 v[88:91], v[154:157], v[182:185], v[88:91]
	v_mfma_f32_16x16x32_bf16 v[72:75], v[158:161], v[182:185], v[72:75]
	s_waitcnt lgkmcnt(5)
	v_mfma_f32_16x16x32_bf16 v[116:119], v[146:149], v[186:189], v[116:119]
	v_mfma_f32_16x16x32_bf16 v[100:103], v[150:153], v[186:189], v[100:103]
	v_mfma_f32_16x16x32_bf16 v[84:87], v[154:157], v[186:189], v[84:87]
	v_mfma_f32_16x16x32_bf16 v[68:71], v[158:161], v[186:189], v[68:71]
	s_waitcnt lgkmcnt(1)
	v_mfma_f32_16x16x32_bf16 v[112:115], v[146:149], v[190:193], v[112:115]
	v_mfma_f32_16x16x32_bf16 v[96:99], v[150:153], v[190:193], v[96:99]
	v_mfma_f32_16x16x32_bf16 v[80:83], v[154:157], v[190:193], v[80:83]
	v_mfma_f32_16x16x32_bf16 v[64:67], v[158:161], v[190:193], v[64:67]
	s_add_i32 s2, s2, 0x10000
	s_add_u32 s0, s0, 0x80
	s_addc_u32 s1, s1, 0
	s_cmpk_lg_i32 s0, 0x780
	s_waitcnt vmcnt(0) lgkmcnt(0)
	s_barrier
; #define WAIT_V(n) asm volatile("s_waitcnt vmcnt(%0)" ::"n"(n) : "memory")
; template <bool PRO>
; __device__ __forceinline__ void gemm_mainloop(const u16* __restrict__ Ab, const u16* __restrict__ Bb, int K,
;                                               f32x4 (&acc)[8][4]) {
;     ...
;   const int nt = K / BK;
;   if (PRO) GLDS_STAGE(0, 0);
;   WAIT_V(0);
;   __syncthreads();
;   for (int t = 0; t < nt; ++t) {
;     int cur = t & 1;
;     if (t + 1 < nt) GLDS_STAGE(cur ^ 1, t + 1);
;     __builtin_amdgcn_sched_barrier(0);
;     KSTEP(cur, 0);
;     KSTEP(cur, 1);
;     WAIT_V(0);
;     __syncthreads();
;   }
	s_cbranch_scc0 .Lpipe_exit_221
	s_and_b32 s3, s2, 0x10000
	v_or_b32_e32 v247, s3, v136
	v_or_b32_e32 v248, s3, v137
	v_add_u32_e32 v194, v247, v144
	v_add_u32_e32 v195, v248, v142
	v_mfma_f32_16x16x32_bf16 v[60:63], v[162:165], v[174:177], v[60:63]
	v_add_u32_e32 v196, v248, v145
	v_add_u32_e32 v197, v248, v143
	v_add_u32_e32 v198, v248, v141
	v_add_u32_e32 v199, v248, v140
	v_mfma_f32_16x16x32_bf16 v[44:47], v[166:169], v[174:177], v[44:47]
	v_add_u32_e32 v200, v248, v139
	v_add_u32_e32 v201, v248, v138
	v_add_u32_e32 v249, v247, v134
	v_or_b32_e32 v250, s3, v128
	v_mfma_f32_16x16x32_bf16 v[28:31], v[170:173], v[174:177], v[28:31]
	ds_read_b128 v[146:149], v194
	ds_read_b128 v[150:153], v195
	v_mfma_f32_16x16x32_bf16 v[12:15], v[178:181], v[174:177], v[12:15]
	ds_read_b128 v[154:157], v196
	ds_read_b128 v[158:161], v197
	v_mfma_f32_16x16x32_bf16 v[56:59], v[162:165], v[182:185], v[56:59]
	ds_read_b128 v[174:177], v249 offset:32768
	s_xor_b32 s4, s3, 0x10000
	v_add_u32_e32 v251, s4, v135
	v_mfma_f32_16x16x32_bf16 v[40:43], v[166:169], v[182:185], v[40:43]
	v_lshl_add_u64 v[252:253], v[130:131], 0, s[0:1]
	v_readfirstlane_b32 s4, v251
	s_mov_b32 m0, s4
	v_mfma_f32_16x16x32_bf16 v[24:27], v[170:173], v[182:185], v[24:27]
	s_mov_b64 s[4:5], 0x80
	v_lshl_add_u64 v[254:255], v[252:253], 0, s[4:5]
	global_load_lds_dwordx4 v[254:255], off
	s_add_u32 m0, m0, 0x2000
	v_mfma_f32_16x16x32_bf16 v[8:11], v[178:181], v[182:185], v[8:11]
	ds_read_b128 v[182:185], v249 offset:34816
	v_mfma_f32_16x16x32_bf16 v[52:55], v[162:165], v[186:189], v[52:55]
	s_mov_b64 s[4:5], 0x20080
	v_lshl_add_u64 v[254:255], v[252:253], 0, s[4:5]
	global_load_lds_dwordx4 v[254:255], off
	s_add_u32 m0, m0, 0x2000
	v_mfma_f32_16x16x32_bf16 v[36:39], v[166:169], v[186:189], v[36:39]
	v_mfma_f32_16x16x32_bf16 v[20:23], v[170:173], v[186:189], v[20:23]
	v_lshl_add_u64 v[254:255], v[252:253], 0, s[68:69]
	global_load_lds_dwordx4 v[254:255], off
	s_add_u32 m0, m0, 0x2000
	v_mfma_f32_16x16x32_bf16 v[4:7], v[178:181], v[186:189], v[4:7]
	ds_read_b128 v[186:189], v249 offset:36864
	v_mfma_f32_16x16x32_bf16 v[48:51], v[162:165], v[190:193], v[48:51]
	ds_read_b128 v[162:165], v198
	v_lshl_add_u64 v[254:255], v[252:253], 0, s[72:73]
	global_load_lds_dwordx4 v[254:255], off
	s_add_u32 m0, m0, 0x2000
	v_mfma_f32_16x16x32_bf16 v[32:35], v[166:169], v[190:193], v[32:35]
	ds_read_b128 v[166:169], v199
	v_mfma_f32_16x16x32_bf16 v[16:19], v[170:173], v[190:193], v[16:19]
	ds_read_b128 v[170:173], v200
	v_mfma_f32_16x16x32_bf16 v[0:3], v[178:181], v[190:193], v[0:3]
	ds_read_b128 v[190:193], v249 offset:38912
	ds_read_b128 v[178:181], v201
	s_branch .LBB0_221

; #define WAIT_V(n) asm volatile("s_waitcnt vmcnt(%0)" ::"n"(n) : "memory")
; template <bool PRO>
; __device__ __forceinline__ void gemm_mainloop(const u16* __restrict__ Ab, const u16* __restrict__ Bb, int K,
;                                               f32x4 (&acc)[8][4]) {
;     ...
;   const int nt = K / BK;
;   if (PRO) GLDS_STAGE(0, 0);
;   WAIT_V(0);
;   __syncthreads();
;   for (int t = 0; t < nt; ++t) {
;     int cur = t & 1;
;     if (t + 1 < nt) GLDS_STAGE(cur ^ 1, t + 1);
;     __builtin_amdgcn_sched_barrier(0);
;     KSTEP(cur, 0);
;     KSTEP(cur, 1);
;     WAIT_V(0);
;     __syncthreads();
;   }
.LBB0_1374:
	s_waitcnt lgkmcnt(7)
	v_mfma_f32_16x16x32_bf16 v[124:127], v[148:151], v[176:179], v[124:127]
	v_mfma_f32_16x16x32_bf16 v[108:111], v[152:155], v[176:179], v[108:111]
	v_lshl_add_u64 v[252:253], v[130:131], 0, s[0:1]
	v_lshl_add_u64 v[254:255], v[252:253], 0, s[26:27]
	global_load_lds_dwordx4 v[254:255], off
	s_add_u32 m0, m0, 0x2000
	v_mfma_f32_16x16x32_bf16 v[92:95], v[156:159], v[176:179], v[92:95]
	v_mfma_f32_16x16x32_bf16 v[76:79], v[160:163], v[176:179], v[76:79]
	s_waitcnt lgkmcnt(6)
	v_mfma_f32_16x16x32_bf16 v[120:123], v[148:151], v[184:187], v[120:123]
	v_lshl_add_u64 v[254:255], v[252:253], 0, s[30:31]
	global_load_lds_dwordx4 v[254:255], off
	s_add_u32 m0, m0, 0x2000
	v_mfma_f32_16x16x32_bf16 v[104:107], v[152:155], v[184:187], v[104:107]
	v_mfma_f32_16x16x32_bf16 v[88:91], v[156:159], v[184:187], v[88:91]
	v_mfma_f32_16x16x32_bf16 v[72:75], v[160:163], v[184:187], v[72:75]
	v_lshl_add_u64 v[254:255], v[252:253], 0, s[36:37]
	global_load_lds_dwordx4 v[254:255], off
	s_add_u32 m0, m0, 0x2000
	s_waitcnt lgkmcnt(5)
	v_mfma_f32_16x16x32_bf16 v[116:119], v[148:151], v[188:191], v[116:119]
	v_mfma_f32_16x16x32_bf16 v[100:103], v[152:155], v[188:191], v[100:103]
	v_mfma_f32_16x16x32_bf16 v[84:87], v[156:159], v[188:191], v[84:87]
	v_lshl_add_u64 v[254:255], v[252:253], 0, s[40:41]
	global_load_lds_dwordx4 v[254:255], off
	v_mfma_f32_16x16x32_bf16 v[68:71], v[160:163], v[188:191], v[68:71]
	s_waitcnt lgkmcnt(1)
	v_mfma_f32_16x16x32_bf16 v[112:115], v[148:151], v[192:195], v[112:115]
	ds_read_b128 v[148:151], v196 offset:1024
	v_mfma_f32_16x16x32_bf16 v[96:99], v[152:155], v[192:195], v[96:99]
	ds_read_b128 v[152:155], v197 offset:1024
	v_mfma_f32_16x16x32_bf16 v[80:83], v[156:159], v[192:195], v[80:83]
	ds_read_b128 v[156:159], v198 offset:1024
	v_mfma_f32_16x16x32_bf16 v[64:67], v[160:163], v[192:195], v[64:67]
	ds_read_b128 v[160:163], v199 offset:1024
	v_mfma_f32_16x16x32_bf16 v[60:63], v[164:167], v[176:179], v[60:63]
	v_mfma_f32_16x16x32_bf16 v[44:47], v[168:171], v[176:179], v[44:47]
	v_mfma_f32_16x16x32_bf16 v[28:31], v[172:175], v[176:179], v[28:31]
	s_waitcnt lgkmcnt(4)
	v_mfma_f32_16x16x32_bf16 v[12:15], v[180:183], v[176:179], v[12:15]
	ds_read_b128 v[176:179], v147 offset:33792
	v_mfma_f32_16x16x32_bf16 v[56:59], v[164:167], v[184:187], v[56:59]
	v_mfma_f32_16x16x32_bf16 v[40:43], v[168:171], v[184:187], v[40:43]
	v_mfma_f32_16x16x32_bf16 v[24:27], v[172:175], v[184:187], v[24:27]
	v_mfma_f32_16x16x32_bf16 v[8:11], v[180:183], v[184:187], v[8:11]
	ds_read_b128 v[184:187], v147 offset:35840
	v_mfma_f32_16x16x32_bf16 v[52:55], v[164:167], v[188:191], v[52:55]
	v_mfma_f32_16x16x32_bf16 v[36:39], v[168:171], v[188:191], v[36:39]
	v_mfma_f32_16x16x32_bf16 v[20:23], v[172:175], v[188:191], v[20:23]
	v_mfma_f32_16x16x32_bf16 v[4:7], v[180:183], v[188:191], v[4:7]
	ds_read_b128 v[188:191], v147 offset:37888
	v_mfma_f32_16x16x32_bf16 v[48:51], v[164:167], v[192:195], v[48:51]
	ds_read_b128 v[164:167], v200 offset:1024
	v_mfma_f32_16x16x32_bf16 v[32:35], v[168:171], v[192:195], v[32:35]
	ds_read_b128 v[168:171], v201 offset:1024
	v_mfma_f32_16x16x32_bf16 v[16:19], v[172:175], v[192:195], v[16:19]
	ds_read_b128 v[172:175], v202 offset:1024
	v_mfma_f32_16x16x32_bf16 v[0:3], v[180:183], v[192:195], v[0:3]
	ds_read_b128 v[192:195], v147 offset:39936
	ds_read_b128 v[180:183], v203 offset:1024
	s_waitcnt lgkmcnt(7)
	v_mfma_f32_16x16x32_bf16 v[124:127], v[148:151], v[176:179], v[124:127]
	v_mfma_f32_16x16x32_bf16 v[108:111], v[152:155], v[176:179], v[108:111]
	v_mfma_f32_16x16x32_bf16 v[92:95], v[156:159], v[176:179], v[92:95]
	v_mfma_f32_16x16x32_bf16 v[76:79], v[160:163], v[176:179], v[76:79]
	s_waitcnt lgkmcnt(6)
	v_mfma_f32_16x16x32_bf16 v[120:123], v[148:151], v[184:187], v[120:123]
	v_mfma_f32_16x16x32_bf16 v[104:107], v[152:155], v[184:187], v[104:107]
	v_mfma_f32_16x16x32_bf16 v[88:91], v[156:159], v[184:187], v[88:91]
	v_mfma_f32_16x16x32_bf16 v[72:75], v[160:163], v[184:187], v[72:75]
	s_waitcnt lgkmcnt(5)
	v_mfma_f32_16x16x32_bf16 v[116:119], v[148:151], v[188:191], v[116:119]
	v_mfma_f32_16x16x32_bf16 v[100:103], v[152:155], v[188:191], v[100:103]
	v_mfma_f32_16x16x32_bf16 v[84:87], v[156:159], v[188:191], v[84:87]
	v_mfma_f32_16x16x32_bf16 v[68:71], v[160:163], v[188:191], v[68:71]
	s_waitcnt lgkmcnt(1)
	v_mfma_f32_16x16x32_bf16 v[112:115], v[148:151], v[192:195], v[112:115]
	v_mfma_f32_16x16x32_bf16 v[96:99], v[152:155], v[192:195], v[96:99]
	v_mfma_f32_16x16x32_bf16 v[80:83], v[156:159], v[192:195], v[80:83]
	v_mfma_f32_16x16x32_bf16 v[64:67], v[160:163], v[192:195], v[64:67]
	s_add_i32 s13, s13, 0x10000
	s_add_u32 s0, s0, 0x80
	s_addc_u32 s1, s1, 0
	s_cmpk_lg_i32 s0, 0x780
	s_waitcnt vmcnt(0) lgkmcnt(0)
	s_barrier
; #define WAIT_V(n) asm volatile("s_waitcnt vmcnt(%0)" ::"n"(n) : "memory")
; template <bool PRO>
; __device__ __forceinline__ void gemm_mainloop(const u16* __restrict__ Ab, const u16* __restrict__ Bb, int K,
;                                               f32x4 (&acc)[8][4]) {
;     ...
;   const int nt = K / BK;
;   if (PRO) GLDS_STAGE(0, 0);
;   WAIT_V(0);
;   __syncthreads();
;   for (int t = 0; t < nt; ++t) {
;     int cur = t & 1;
;     if (t + 1 < nt) GLDS_STAGE(cur ^ 1, t + 1);
;     __builtin_amdgcn_sched_barrier(0);
;     KSTEP(cur, 0);
;     KSTEP(cur, 1);
;     WAIT_V(0);
;     __syncthreads();
;   }
	s_cbranch_scc0 .Lpipe_exit_1374
	s_and_b32 s17, s13, 0x10000
	v_or_b32_e32 v247, s17, v137
	v_or_b32_e32 v248, s17, v138
	v_add_u32_e32 v196, v247, v145
	v_add_u32_e32 v197, v248, v143
	v_mfma_f32_16x16x32_bf16 v[60:63], v[164:167], v[176:179], v[60:63]
	v_add_u32_e32 v198, v248, v146
	v_add_u32_e32 v199, v248, v144
	v_add_u32_e32 v200, v248, v142
	v_add_u32_e32 v201, v248, v141
	v_mfma_f32_16x16x32_bf16 v[44:47], v[168:171], v[176:179], v[44:47]
	v_add_u32_e32 v202, v248, v140
	v_add_u32_e32 v203, v248, v139
	v_add_u32_e32 v249, v247, v135
	v_or_b32_e32 v147, s17, v134
	v_mfma_f32_16x16x32_bf16 v[28:31], v[172:175], v[176:179], v[28:31]
	ds_read_b128 v[148:151], v196
	ds_read_b128 v[152:155], v197
	v_mfma_f32_16x16x32_bf16 v[12:15], v[180:183], v[176:179], v[12:15]
	ds_read_b128 v[156:159], v198
	ds_read_b128 v[160:163], v199
	v_mfma_f32_16x16x32_bf16 v[56:59], v[164:167], v[184:187], v[56:59]
	ds_read_b128 v[176:179], v249 offset:32768
	s_xor_b32 s42, s17, 0x10000
	v_add_u32_e32 v250, s42, v136
	v_mfma_f32_16x16x32_bf16 v[40:43], v[168:171], v[184:187], v[40:43]
	v_lshl_add_u64 v[252:253], v[128:129], 0, s[0:1]
	v_readfirstlane_b32 s42, v250
	s_mov_b32 m0, s42
	v_mfma_f32_16x16x32_bf16 v[24:27], v[172:175], v[184:187], v[24:27]
	v_lshl_add_u64 v[254:255], v[252:253], 0, s[24:25]
	global_load_lds_dwordx4 v[254:255], off
	s_add_u32 m0, m0, 0x2000
	v_mfma_f32_16x16x32_bf16 v[8:11], v[180:183], v[184:187], v[8:11]
	ds_read_b128 v[184:187], v249 offset:34816
	v_mfma_f32_16x16x32_bf16 v[52:55], v[164:167], v[188:191], v[52:55]
	v_lshl_add_u64 v[254:255], v[252:253], 0, s[28:29]
	global_load_lds_dwordx4 v[254:255], off
	s_add_u32 m0, m0, 0x2000
	v_mfma_f32_16x16x32_bf16 v[36:39], v[168:171], v[188:191], v[36:39]
	v_mfma_f32_16x16x32_bf16 v[20:23], v[172:175], v[188:191], v[20:23]
	v_lshl_add_u64 v[254:255], v[252:253], 0, s[34:35]
	global_load_lds_dwordx4 v[254:255], off
	s_add_u32 m0, m0, 0x2000
	v_mfma_f32_16x16x32_bf16 v[4:7], v[180:183], v[188:191], v[4:7]
	ds_read_b128 v[188:191], v249 offset:36864
	v_mfma_f32_16x16x32_bf16 v[48:51], v[164:167], v[192:195], v[48:51]
	ds_read_b128 v[164:167], v200
	v_lshl_add_u64 v[254:255], v[252:253], 0, s[38:39]
	global_load_lds_dwordx4 v[254:255], off
	s_add_u32 m0, m0, 0x2000
	v_mfma_f32_16x16x32_bf16 v[32:35], v[168:171], v[192:195], v[32:35]
	ds_read_b128 v[168:171], v201
	v_mfma_f32_16x16x32_bf16 v[16:19], v[172:175], v[192:195], v[16:19]
	ds_read_b128 v[172:175], v202
	v_mfma_f32_16x16x32_bf16 v[0:3], v[180:183], v[192:195], v[0:3]
	ds_read_b128 v[192:195], v249 offset:38912
	ds_read_b128 v[180:183], v203
	s_branch .LBB0_1374

; #define WAIT_V(n) asm volatile("s_waitcnt vmcnt(%0)" ::"n"(n) : "memory")
; template <bool PRO>
; __device__ __forceinline__ void gemm_mainloop(const u16* __restrict__ Ab, const u16* __restrict__ Bb, int K,
;                                               f32x4 (&acc)[8][4]) {
;     ...
;   const int nt = K / BK;
;   if (PRO) GLDS_STAGE(0, 0);
;   WAIT_V(0);
;   __syncthreads();
;   for (int t = 0; t < nt; ++t) {
;     int cur = t & 1;
;     if (t + 1 < nt) GLDS_STAGE(cur ^ 1, t + 1);
;     __builtin_amdgcn_sched_barrier(0);
;     KSTEP(cur, 0);
;     KSTEP(cur, 1);
;     WAIT_V(0);
;     __syncthreads();
;   }
.LBB0_1386:
	s_waitcnt lgkmcnt(7)
	v_mfma_f32_16x16x32_bf16 v[124:127], v[148:151], v[176:179], v[124:127]
	v_mfma_f32_16x16x32_bf16 v[108:111], v[152:155], v[176:179], v[108:111]
	v_lshl_add_u64 v[252:253], v[130:131], 0, s[0:1]
	v_lshl_add_u64 v[254:255], v[252:253], 0, s[30:31]
	global_load_lds_dwordx4 v[254:255], off
	s_add_u32 m0, m0, 0x2000
	v_mfma_f32_16x16x32_bf16 v[92:95], v[156:159], v[176:179], v[92:95]
	v_mfma_f32_16x16x32_bf16 v[76:79], v[160:163], v[176:179], v[76:79]
	s_waitcnt lgkmcnt(6)
	v_mfma_f32_16x16x32_bf16 v[120:123], v[148:151], v[184:187], v[120:123]
	v_lshl_add_u64 v[254:255], v[252:253], 0, s[36:37]
	global_load_lds_dwordx4 v[254:255], off
	s_add_u32 m0, m0, 0x2000
	v_mfma_f32_16x16x32_bf16 v[104:107], v[152:155], v[184:187], v[104:107]
	v_mfma_f32_16x16x32_bf16 v[88:91], v[156:159], v[184:187], v[88:91]
	v_mfma_f32_16x16x32_bf16 v[72:75], v[160:163], v[184:187], v[72:75]
	v_lshl_add_u64 v[254:255], v[252:253], 0, s[40:41]
	global_load_lds_dwordx4 v[254:255], off
	s_add_u32 m0, m0, 0x2000
	s_waitcnt lgkmcnt(5)
	v_mfma_f32_16x16x32_bf16 v[116:119], v[148:151], v[188:191], v[116:119]
	v_mfma_f32_16x16x32_bf16 v[100:103], v[152:155], v[188:191], v[100:103]
	v_mfma_f32_16x16x32_bf16 v[84:87], v[156:159], v[188:191], v[84:87]
	v_lshl_add_u64 v[254:255], v[252:253], 0, s[44:45]
	global_load_lds_dwordx4 v[254:255], off
	v_mfma_f32_16x16x32_bf16 v[68:71], v[160:163], v[188:191], v[68:71]
	s_waitcnt lgkmcnt(1)
	v_mfma_f32_16x16x32_bf16 v[112:115], v[148:151], v[192:195], v[112:115]
	ds_read_b128 v[148:151], v196 offset:1024
	v_mfma_f32_16x16x32_bf16 v[96:99], v[152:155], v[192:195], v[96:99]
	ds_read_b128 v[152:155], v197 offset:1024
	v_mfma_f32_16x16x32_bf16 v[80:83], v[156:159], v[192:195], v[80:83]
	ds_read_b128 v[156:159], v198 offset:1024
	v_mfma_f32_16x16x32_bf16 v[64:67], v[160:163], v[192:195], v[64:67]
	ds_read_b128 v[160:163], v199 offset:1024
	v_mfma_f32_16x16x32_bf16 v[60:63], v[164:167], v[176:179], v[60:63]
	v_mfma_f32_16x16x32_bf16 v[44:47], v[168:171], v[176:179], v[44:47]
	v_mfma_f32_16x16x32_bf16 v[28:31], v[172:175], v[176:179], v[28:31]
	s_waitcnt lgkmcnt(4)
	v_mfma_f32_16x16x32_bf16 v[12:15], v[180:183], v[176:179], v[12:15]
	ds_read_b128 v[176:179], v147 offset:33792
	v_mfma_f32_16x16x32_bf16 v[56:59], v[164:167], v[184:187], v[56:59]
	v_mfma_f32_16x16x32_bf16 v[40:43], v[168:171], v[184:187], v[40:43]
	v_mfma_f32_16x16x32_bf16 v[24:27], v[172:175], v[184:187], v[24:27]
	v_mfma_f32_16x16x32_bf16 v[8:11], v[180:183], v[184:187], v[8:11]
	ds_read_b128 v[184:187], v147 offset:35840
	v_mfma_f32_16x16x32_bf16 v[52:55], v[164:167], v[188:191], v[52:55]
	v_mfma_f32_16x16x32_bf16 v[36:39], v[168:171], v[188:191], v[36:39]
	v_mfma_f32_16x16x32_bf16 v[20:23], v[172:175], v[188:191], v[20:23]
	v_mfma_f32_16x16x32_bf16 v[4:7], v[180:183], v[188:191], v[4:7]
	ds_read_b128 v[188:191], v147 offset:37888
	v_mfma_f32_16x16x32_bf16 v[48:51], v[164:167], v[192:195], v[48:51]
	ds_read_b128 v[164:167], v200 offset:1024
	v_mfma_f32_16x16x32_bf16 v[32:35], v[168:171], v[192:195], v[32:35]
	ds_read_b128 v[168:171], v201 offset:1024
	v_mfma_f32_16x16x32_bf16 v[16:19], v[172:175], v[192:195], v[16:19]
	ds_read_b128 v[172:175], v202 offset:1024
	v_mfma_f32_16x16x32_bf16 v[0:3], v[180:183], v[192:195], v[0:3]
	ds_read_b128 v[192:195], v147 offset:39936
	ds_read_b128 v[180:183], v203 offset:1024
	s_waitcnt lgkmcnt(7)
	v_mfma_f32_16x16x32_bf16 v[124:127], v[148:151], v[176:179], v[124:127]
	v_mfma_f32_16x16x32_bf16 v[108:111], v[152:155], v[176:179], v[108:111]
	v_mfma_f32_16x16x32_bf16 v[92:95], v[156:159], v[176:179], v[92:95]
	v_mfma_f32_16x16x32_bf16 v[76:79], v[160:163], v[176:179], v[76:79]
	s_waitcnt lgkmcnt(6)
	v_mfma_f32_16x16x32_bf16 v[120:123], v[148:151], v[184:187], v[120:123]
	v_mfma_f32_16x16x32_bf16 v[104:107], v[152:155], v[184:187], v[104:107]
	v_mfma_f32_16x16x32_bf16 v[88:91], v[156:159], v[184:187], v[88:91]
	v_mfma_f32_16x16x32_bf16 v[72:75], v[160:163], v[184:187], v[72:75]
	s_waitcnt lgkmcnt(5)
	v_mfma_f32_16x16x32_bf16 v[116:119], v[148:151], v[188:191], v[116:119]
	v_mfma_f32_16x16x32_bf16 v[100:103], v[152:155], v[188:191], v[100:103]
	v_mfma_f32_16x16x32_bf16 v[84:87], v[156:159], v[188:191], v[84:87]
	v_mfma_f32_16x16x32_bf16 v[68:71], v[160:163], v[188:191], v[68:71]
	s_waitcnt lgkmcnt(1)
	v_mfma_f32_16x16x32_bf16 v[112:115], v[148:151], v[192:195], v[112:115]
	v_mfma_f32_16x16x32_bf16 v[96:99], v[152:155], v[192:195], v[96:99]
	v_mfma_f32_16x16x32_bf16 v[80:83], v[156:159], v[192:195], v[80:83]
	v_mfma_f32_16x16x32_bf16 v[64:67], v[160:163], v[192:195], v[64:67]
	s_add_i32 s19, s19, 0x10000
	s_add_u32 s0, s0, 0x80
	s_addc_u32 s1, s1, 0
	s_cmpk_lg_i32 s0, 0x780
	s_waitcnt vmcnt(0) lgkmcnt(0)
	s_barrier
; #define WAIT_V(n) asm volatile("s_waitcnt vmcnt(%0)" ::"n"(n) : "memory")
; template <bool PRO>
; __device__ __forceinline__ void gemm_mainloop(const u16* __restrict__ Ab, const u16* __restrict__ Bb, int K,
;                                               f32x4 (&acc)[8][4]) {
;     ...
;   const int nt = K / BK;
;   if (PRO) GLDS_STAGE(0, 0);
;   WAIT_V(0);
;   __syncthreads();
;   for (int t = 0; t < nt; ++t) {
;     int cur = t & 1;
;     if (t + 1 < nt) GLDS_STAGE(cur ^ 1, t + 1);
;     __builtin_amdgcn_sched_barrier(0);
;     KSTEP(cur, 0);
;     KSTEP(cur, 1);
;     WAIT_V(0);
;     __syncthreads();
;   }
	s_cbranch_scc0 .Lpipe_exit_1386
	s_and_b32 s21, s19, 0x10000
	v_or_b32_e32 v247, s21, v137
	v_or_b32_e32 v248, s21, v138
	v_add_u32_e32 v196, v247, v145
	v_add_u32_e32 v197, v248, v143
	v_mfma_f32_16x16x32_bf16 v[60:63], v[164:167], v[176:179], v[60:63]
	v_add_u32_e32 v198, v248, v146
	v_add_u32_e32 v199, v248, v144
	v_add_u32_e32 v200, v248, v142
	v_add_u32_e32 v201, v248, v141
	v_mfma_f32_16x16x32_bf16 v[44:47], v[168:171], v[176:179], v[44:47]
	v_add_u32_e32 v202, v248, v140
	v_add_u32_e32 v203, v248, v139
	v_add_u32_e32 v249, v247, v135
	v_or_b32_e32 v147, s21, v134
	v_mfma_f32_16x16x32_bf16 v[28:31], v[172:175], v[176:179], v[28:31]
	ds_read_b128 v[148:151], v196
	ds_read_b128 v[152:155], v197
	v_mfma_f32_16x16x32_bf16 v[12:15], v[180:183], v[176:179], v[12:15]
	ds_read_b128 v[156:159], v198
	ds_read_b128 v[160:163], v199
	v_mfma_f32_16x16x32_bf16 v[56:59], v[164:167], v[184:187], v[56:59]
	ds_read_b128 v[176:179], v249 offset:32768
	s_xor_b32 s64, s21, 0x10000
	v_add_u32_e32 v250, s64, v136
	v_mfma_f32_16x16x32_bf16 v[40:43], v[168:171], v[184:187], v[40:43]
	v_lshl_add_u64 v[252:253], v[128:129], 0, s[0:1]
	v_readfirstlane_b32 s64, v250
	s_mov_b32 m0, s64
	v_mfma_f32_16x16x32_bf16 v[24:27], v[172:175], v[184:187], v[24:27]
	v_lshl_add_u64 v[254:255], v[252:253], 0, s[28:29]
	global_load_lds_dwordx4 v[254:255], off
	s_add_u32 m0, m0, 0x2000
	v_mfma_f32_16x16x32_bf16 v[8:11], v[180:183], v[184:187], v[8:11]
	ds_read_b128 v[184:187], v249 offset:34816
	v_mfma_f32_16x16x32_bf16 v[52:55], v[164:167], v[188:191], v[52:55]
	v_lshl_add_u64 v[254:255], v[252:253], 0, s[34:35]
	global_load_lds_dwordx4 v[254:255], off
	s_add_u32 m0, m0, 0x2000
	v_mfma_f32_16x16x32_bf16 v[36:39], v[168:171], v[188:191], v[36:39]
	v_mfma_f32_16x16x32_bf16 v[20:23], v[172:175], v[188:191], v[20:23]
	v_lshl_add_u64 v[254:255], v[252:253], 0, s[38:39]
	global_load_lds_dwordx4 v[254:255], off
	s_add_u32 m0, m0, 0x2000
	v_mfma_f32_16x16x32_bf16 v[4:7], v[180:183], v[188:191], v[4:7]
	ds_read_b128 v[188:191], v249 offset:36864
	v_mfma_f32_16x16x32_bf16 v[48:51], v[164:167], v[192:195], v[48:51]
	ds_read_b128 v[164:167], v200
	v_lshl_add_u64 v[254:255], v[252:253], 0, s[42:43]
	global_load_lds_dwordx4 v[254:255], off
	s_add_u32 m0, m0, 0x2000
	v_mfma_f32_16x16x32_bf16 v[32:35], v[168:171], v[192:195], v[32:35]
	ds_read_b128 v[168:171], v201
	v_mfma_f32_16x16x32_bf16 v[16:19], v[172:175], v[192:195], v[16:19]
	ds_read_b128 v[172:175], v202
	v_mfma_f32_16x16x32_bf16 v[0:3], v[180:183], v[192:195], v[0:3]
	ds_read_b128 v[192:195], v249 offset:38912
	ds_read_b128 v[180:183], v203
	s_branch .LBB0_1386

; #define WAIT_V(n) asm volatile("s_waitcnt vmcnt(%0)" ::"n"(n) : "memory")
; template <bool PRO>
; __device__ __forceinline__ void gemm_mainloop(const u16* __restrict__ Ab, const u16* __restrict__ Bb, int K,
;                                               f32x4 (&acc)[8][4]) {
;     ...
;   const int nt = K / BK;
;   if (PRO) GLDS_STAGE(0, 0);
;   WAIT_V(0);
;   __syncthreads();
;   for (int t = 0; t < nt; ++t) {
;     int cur = t & 1;
;     if (t + 1 < nt) GLDS_STAGE(cur ^ 1, t + 1);
;     __builtin_amdgcn_sched_barrier(0);
;     KSTEP(cur, 0);
;     KSTEP(cur, 1);
;     WAIT_V(0);
;     __syncthreads();
;   }
.LBB0_1406:
	s_waitcnt lgkmcnt(7)
	v_mfma_f32_16x16x32_bf16 v[124:127], v[148:151], v[176:179], v[124:127]
	v_mfma_f32_16x16x32_bf16 v[108:111], v[152:155], v[176:179], v[108:111]
	v_lshl_add_u64 v[252:253], v[130:131], 0, s[0:1]
	v_lshl_add_u64 v[254:255], v[252:253], 0, s[22:23]
	global_load_lds_dwordx4 v[254:255], off
	s_add_u32 m0, m0, 0x2000
	v_mfma_f32_16x16x32_bf16 v[92:95], v[156:159], v[176:179], v[92:95]
	v_mfma_f32_16x16x32_bf16 v[76:79], v[160:163], v[176:179], v[76:79]
	s_waitcnt lgkmcnt(6)
	v_mfma_f32_16x16x32_bf16 v[120:123], v[148:151], v[184:187], v[120:123]
	v_lshl_add_u64 v[254:255], v[252:253], 0, s[26:27]
	global_load_lds_dwordx4 v[254:255], off
	s_add_u32 m0, m0, 0x2000
	v_mfma_f32_16x16x32_bf16 v[104:107], v[152:155], v[184:187], v[104:107]
	v_mfma_f32_16x16x32_bf16 v[88:91], v[156:159], v[184:187], v[88:91]
	v_mfma_f32_16x16x32_bf16 v[72:75], v[160:163], v[184:187], v[72:75]
	v_lshl_add_u64 v[254:255], v[252:253], 0, s[30:31]
	global_load_lds_dwordx4 v[254:255], off
	s_add_u32 m0, m0, 0x2000
	s_waitcnt lgkmcnt(5)
	v_mfma_f32_16x16x32_bf16 v[116:119], v[148:151], v[188:191], v[116:119]
	v_mfma_f32_16x16x32_bf16 v[100:103], v[152:155], v[188:191], v[100:103]
	v_mfma_f32_16x16x32_bf16 v[84:87], v[156:159], v[188:191], v[84:87]
	v_lshl_add_u64 v[254:255], v[252:253], 0, s[36:37]
	global_load_lds_dwordx4 v[254:255], off
	v_mfma_f32_16x16x32_bf16 v[68:71], v[160:163], v[188:191], v[68:71]
	s_waitcnt lgkmcnt(1)
	v_mfma_f32_16x16x32_bf16 v[112:115], v[148:151], v[192:195], v[112:115]
	ds_read_b128 v[148:151], v196 offset:1024
	v_mfma_f32_16x16x32_bf16 v[96:99], v[152:155], v[192:195], v[96:99]
	ds_read_b128 v[152:155], v197 offset:1024
	v_mfma_f32_16x16x32_bf16 v[80:83], v[156:159], v[192:195], v[80:83]
	ds_read_b128 v[156:159], v198 offset:1024
	v_mfma_f32_16x16x32_bf16 v[64:67], v[160:163], v[192:195], v[64:67]
	ds_read_b128 v[160:163], v199 offset:1024
	v_mfma_f32_16x16x32_bf16 v[60:63], v[164:167], v[176:179], v[60:63]
	v_mfma_f32_16x16x32_bf16 v[44:47], v[168:171], v[176:179], v[44:47]
	v_mfma_f32_16x16x32_bf16 v[28:31], v[172:175], v[176:179], v[28:31]
	s_waitcnt lgkmcnt(4)
	v_mfma_f32_16x16x32_bf16 v[12:15], v[180:183], v[176:179], v[12:15]
	ds_read_b128 v[176:179], v250 offset:33792
	v_mfma_f32_16x16x32_bf16 v[56:59], v[164:167], v[184:187], v[56:59]
	v_mfma_f32_16x16x32_bf16 v[40:43], v[168:171], v[184:187], v[40:43]
	v_mfma_f32_16x16x32_bf16 v[24:27], v[172:175], v[184:187], v[24:27]
	v_mfma_f32_16x16x32_bf16 v[8:11], v[180:183], v[184:187], v[8:11]
	ds_read_b128 v[184:187], v250 offset:35840
	v_mfma_f32_16x16x32_bf16 v[52:55], v[164:167], v[188:191], v[52:55]
	v_mfma_f32_16x16x32_bf16 v[36:39], v[168:171], v[188:191], v[36:39]
	v_mfma_f32_16x16x32_bf16 v[20:23], v[172:175], v[188:191], v[20:23]
	v_mfma_f32_16x16x32_bf16 v[4:7], v[180:183], v[188:191], v[4:7]
	ds_read_b128 v[188:191], v250 offset:37888
	v_mfma_f32_16x16x32_bf16 v[48:51], v[164:167], v[192:195], v[48:51]
	ds_read_b128 v[164:167], v200 offset:1024
	v_mfma_f32_16x16x32_bf16 v[32:35], v[168:171], v[192:195], v[32:35]
	ds_read_b128 v[168:171], v201 offset:1024
	v_mfma_f32_16x16x32_bf16 v[16:19], v[172:175], v[192:195], v[16:19]
	ds_read_b128 v[172:175], v202 offset:1024
	v_mfma_f32_16x16x32_bf16 v[0:3], v[180:183], v[192:195], v[0:3]
	ds_read_b128 v[192:195], v250 offset:39936
	ds_read_b128 v[180:183], v203 offset:1024
	s_waitcnt lgkmcnt(7)
	v_mfma_f32_16x16x32_bf16 v[124:127], v[148:151], v[176:179], v[124:127]
	v_mfma_f32_16x16x32_bf16 v[108:111], v[152:155], v[176:179], v[108:111]
	v_mfma_f32_16x16x32_bf16 v[92:95], v[156:159], v[176:179], v[92:95]
	v_mfma_f32_16x16x32_bf16 v[76:79], v[160:163], v[176:179], v[76:79]
	s_waitcnt lgkmcnt(6)
	v_mfma_f32_16x16x32_bf16 v[120:123], v[148:151], v[184:187], v[120:123]
	v_mfma_f32_16x16x32_bf16 v[104:107], v[152:155], v[184:187], v[104:107]
	v_mfma_f32_16x16x32_bf16 v[88:91], v[156:159], v[184:187], v[88:91]
	v_mfma_f32_16x16x32_bf16 v[72:75], v[160:163], v[184:187], v[72:75]
	s_waitcnt lgkmcnt(5)
	v_mfma_f32_16x16x32_bf16 v[116:119], v[148:151], v[188:191], v[116:119]
	v_mfma_f32_16x16x32_bf16 v[100:103], v[152:155], v[188:191], v[100:103]
	v_mfma_f32_16x16x32_bf16 v[84:87], v[156:159], v[188:191], v[84:87]
	v_mfma_f32_16x16x32_bf16 v[68:71], v[160:163], v[188:191], v[68:71]
	s_waitcnt lgkmcnt(1)
	v_mfma_f32_16x16x32_bf16 v[112:115], v[148:151], v[192:195], v[112:115]
	v_mfma_f32_16x16x32_bf16 v[96:99], v[152:155], v[192:195], v[96:99]
	v_mfma_f32_16x16x32_bf16 v[80:83], v[156:159], v[192:195], v[80:83]
	v_mfma_f32_16x16x32_bf16 v[64:67], v[160:163], v[192:195], v[64:67]
	s_add_u32 s0, s0, 0x80
	s_addc_u32 s1, s1, 0
	s_add_i32 s11, s11, 0x10000
	s_cmpk_lg_i32 s0, 0x780
	s_waitcnt vmcnt(0) lgkmcnt(0)
	s_barrier
; #define WAIT_V(n) asm volatile("s_waitcnt vmcnt(%0)" ::"n"(n) : "memory")
; template <bool PRO>
; __device__ __forceinline__ void gemm_mainloop(const u16* __restrict__ Ab, const u16* __restrict__ Bb, int K,
;                                               f32x4 (&acc)[8][4]) {
;     ...
;   const int nt = K / BK;
;   if (PRO) GLDS_STAGE(0, 0);
;   WAIT_V(0);
;   __syncthreads();
;   for (int t = 0; t < nt; ++t) {
;     int cur = t & 1;
;     if (t + 1 < nt) GLDS_STAGE(cur ^ 1, t + 1);
;     __builtin_amdgcn_sched_barrier(0);
;     KSTEP(cur, 0);
;     KSTEP(cur, 1);
;     WAIT_V(0);
;     __syncthreads();
;   }
	s_cbranch_scc0 .Lpipe_exit_1406
	s_and_b32 s17, s11, 0x10000
	v_or_b32_e32 v247, s17, v138
	v_or_b32_e32 v248, s17, v139
	v_add_u32_e32 v196, v247, v146
	v_add_u32_e32 v197, v248, v144
	v_mfma_f32_16x16x32_bf16 v[60:63], v[164:167], v[176:179], v[60:63]
	v_add_u32_e32 v198, v248, v147
	v_add_u32_e32 v199, v248, v145
	v_add_u32_e32 v200, v248, v143
	v_add_u32_e32 v201, v248, v142
	v_mfma_f32_16x16x32_bf16 v[44:47], v[168:171], v[176:179], v[44:47]
	v_add_u32_e32 v202, v248, v141
	v_add_u32_e32 v203, v248, v140
	v_add_u32_e32 v249, v247, v136
	v_or_b32_e32 v250, s17, v135
	v_mfma_f32_16x16x32_bf16 v[28:31], v[172:175], v[176:179], v[28:31]
	ds_read_b128 v[148:151], v196
	ds_read_b128 v[152:155], v197
	v_mfma_f32_16x16x32_bf16 v[12:15], v[180:183], v[176:179], v[12:15]
	ds_read_b128 v[156:159], v198
	ds_read_b128 v[160:163], v199
	v_mfma_f32_16x16x32_bf16 v[56:59], v[164:167], v[184:187], v[56:59]
	ds_read_b128 v[176:179], v249 offset:32768
	s_xor_b32 s44, s17, 0x10000
	v_add_u32_e32 v251, s44, v137
	v_mfma_f32_16x16x32_bf16 v[40:43], v[168:171], v[184:187], v[40:43]
	v_lshl_add_u64 v[252:253], v[128:129], 0, s[0:1]
	v_readfirstlane_b32 s44, v251
	s_mov_b32 m0, s44
	v_mfma_f32_16x16x32_bf16 v[24:27], v[172:175], v[184:187], v[24:27]
	v_lshl_add_u64 v[254:255], v[252:253], 0, s[20:21]
	global_load_lds_dwordx4 v[254:255], off
	s_add_u32 m0, m0, 0x2000
	v_mfma_f32_16x16x32_bf16 v[8:11], v[180:183], v[184:187], v[8:11]
	ds_read_b128 v[184:187], v249 offset:34816
	v_mfma_f32_16x16x32_bf16 v[52:55], v[164:167], v[188:191], v[52:55]
	v_lshl_add_u64 v[254:255], v[252:253], 0, s[24:25]
	global_load_lds_dwordx4 v[254:255], off
	s_add_u32 m0, m0, 0x2000
	v_mfma_f32_16x16x32_bf16 v[36:39], v[168:171], v[188:191], v[36:39]
	v_mfma_f32_16x16x32_bf16 v[20:23], v[172:175], v[188:191], v[20:23]
	v_lshl_add_u64 v[254:255], v[252:253], 0, s[28:29]
	global_load_lds_dwordx4 v[254:255], off
	s_add_u32 m0, m0, 0x2000
	v_mfma_f32_16x16x32_bf16 v[4:7], v[180:183], v[188:191], v[4:7]
	ds_read_b128 v[188:191], v249 offset:36864
	v_mfma_f32_16x16x32_bf16 v[48:51], v[164:167], v[192:195], v[48:51]
	ds_read_b128 v[164:167], v200
	v_lshl_add_u64 v[254:255], v[252:253], 0, s[34:35]
	global_load_lds_dwordx4 v[254:255], off
	s_add_u32 m0, m0, 0x2000
	v_mfma_f32_16x16x32_bf16 v[32:35], v[168:171], v[192:195], v[32:35]
	ds_read_b128 v[168:171], v201
	v_mfma_f32_16x16x32_bf16 v[16:19], v[172:175], v[192:195], v[16:19]
	ds_read_b128 v[172:175], v202
	v_mfma_f32_16x16x32_bf16 v[0:3], v[180:183], v[192:195], v[0:3]
	ds_read_b128 v[192:195], v249 offset:38912
	ds_read_b128 v[180:183], v203
	s_branch .LBB0_1406

; #define WAIT_V(n) asm volatile("s_waitcnt vmcnt(%0)" ::"n"(n) : "memory")
; template <bool PRO>
; __device__ __forceinline__ void gemm_mainloop(const u16* __restrict__ Ab, const u16* __restrict__ Bb, int K,
;                                               f32x4 (&acc)[8][4]) {
;     ...
;   const int nt = K / BK;
;   if (PRO) GLDS_STAGE(0, 0);
;   WAIT_V(0);
;   __syncthreads();
;   for (int t = 0; t < nt; ++t) {
;     int cur = t & 1;
;     if (t + 1 < nt) GLDS_STAGE(cur ^ 1, t + 1);
;     __builtin_amdgcn_sched_barrier(0);
;     KSTEP(cur, 0);
;     KSTEP(cur, 1);
;     WAIT_V(0);
;     __syncthreads();
;   }
.LBB0_1504:
	s_waitcnt lgkmcnt(7)
	v_mfma_f32_16x16x32_bf16 v[124:127], v[150:153], v[178:181], v[124:127]
	v_mfma_f32_16x16x32_bf16 v[108:111], v[154:157], v[178:181], v[108:111]
	v_lshl_add_u64 v[252:253], v[132:133], 0, s[0:1]
	v_lshl_add_u64 v[254:255], v[252:253], 0, s[38:39]
	global_load_lds_dwordx4 v[254:255], off
	s_add_u32 m0, m0, 0x2000
	v_mfma_f32_16x16x32_bf16 v[92:95], v[158:161], v[178:181], v[92:95]
	v_mfma_f32_16x16x32_bf16 v[76:79], v[162:165], v[178:181], v[76:79]
	s_waitcnt lgkmcnt(6)
	v_mfma_f32_16x16x32_bf16 v[120:123], v[150:153], v[186:189], v[120:123]
	v_lshl_add_u64 v[254:255], v[252:253], 0, s[42:43]
	global_load_lds_dwordx4 v[254:255], off
	s_add_u32 m0, m0, 0x2000
	v_mfma_f32_16x16x32_bf16 v[104:107], v[154:157], v[186:189], v[104:107]
	v_mfma_f32_16x16x32_bf16 v[88:91], v[158:161], v[186:189], v[88:91]
	v_mfma_f32_16x16x32_bf16 v[72:75], v[162:165], v[186:189], v[72:75]
	v_lshl_add_u64 v[254:255], v[252:253], 0, s[60:61]
	global_load_lds_dwordx4 v[254:255], off
	s_add_u32 m0, m0, 0x2000
	s_waitcnt lgkmcnt(5)
	v_mfma_f32_16x16x32_bf16 v[116:119], v[150:153], v[190:193], v[116:119]
	v_mfma_f32_16x16x32_bf16 v[100:103], v[154:157], v[190:193], v[100:103]
	v_mfma_f32_16x16x32_bf16 v[84:87], v[158:161], v[190:193], v[84:87]
	v_lshl_add_u64 v[254:255], v[252:253], 0, s[66:67]
	global_load_lds_dwordx4 v[254:255], off
	v_mfma_f32_16x16x32_bf16 v[68:71], v[162:165], v[190:193], v[68:71]
	s_waitcnt lgkmcnt(1)
	v_mfma_f32_16x16x32_bf16 v[112:115], v[150:153], v[194:197], v[112:115]
	ds_read_b128 v[150:153], v198 offset:1024
	v_mfma_f32_16x16x32_bf16 v[96:99], v[154:157], v[194:197], v[96:99]
	ds_read_b128 v[154:157], v199 offset:1024
	v_mfma_f32_16x16x32_bf16 v[80:83], v[158:161], v[194:197], v[80:83]
	ds_read_b128 v[158:161], v200 offset:1024
	v_mfma_f32_16x16x32_bf16 v[64:67], v[162:165], v[194:197], v[64:67]
	ds_read_b128 v[162:165], v201 offset:1024
	v_mfma_f32_16x16x32_bf16 v[60:63], v[166:169], v[178:181], v[60:63]
	v_mfma_f32_16x16x32_bf16 v[44:47], v[170:173], v[178:181], v[44:47]
	v_mfma_f32_16x16x32_bf16 v[28:31], v[174:177], v[178:181], v[28:31]
	s_waitcnt lgkmcnt(4)
	v_mfma_f32_16x16x32_bf16 v[12:15], v[182:185], v[178:181], v[12:15]
	ds_read_b128 v[178:181], v149 offset:33792
	v_mfma_f32_16x16x32_bf16 v[56:59], v[166:169], v[186:189], v[56:59]
	v_mfma_f32_16x16x32_bf16 v[40:43], v[170:173], v[186:189], v[40:43]
	v_mfma_f32_16x16x32_bf16 v[24:27], v[174:177], v[186:189], v[24:27]
	v_mfma_f32_16x16x32_bf16 v[8:11], v[182:185], v[186:189], v[8:11]
	ds_read_b128 v[186:189], v149 offset:35840
	v_mfma_f32_16x16x32_bf16 v[52:55], v[166:169], v[190:193], v[52:55]
	v_mfma_f32_16x16x32_bf16 v[36:39], v[170:173], v[190:193], v[36:39]
	v_mfma_f32_16x16x32_bf16 v[20:23], v[174:177], v[190:193], v[20:23]
	v_mfma_f32_16x16x32_bf16 v[4:7], v[182:185], v[190:193], v[4:7]
	ds_read_b128 v[190:193], v149 offset:37888
	v_mfma_f32_16x16x32_bf16 v[48:51], v[166:169], v[194:197], v[48:51]
	ds_read_b128 v[166:169], v202 offset:1024
	v_mfma_f32_16x16x32_bf16 v[32:35], v[170:173], v[194:197], v[32:35]
	ds_read_b128 v[170:173], v203 offset:1024
	v_mfma_f32_16x16x32_bf16 v[16:19], v[174:177], v[194:197], v[16:19]
	ds_read_b128 v[174:177], v206 offset:1024
	v_mfma_f32_16x16x32_bf16 v[0:3], v[182:185], v[194:197], v[0:3]
	ds_read_b128 v[194:197], v149 offset:39936
	ds_read_b128 v[182:185], v207 offset:1024
	s_waitcnt lgkmcnt(7)
	v_mfma_f32_16x16x32_bf16 v[124:127], v[150:153], v[178:181], v[124:127]
	v_mfma_f32_16x16x32_bf16 v[108:111], v[154:157], v[178:181], v[108:111]
	v_mfma_f32_16x16x32_bf16 v[92:95], v[158:161], v[178:181], v[92:95]
	v_mfma_f32_16x16x32_bf16 v[76:79], v[162:165], v[178:181], v[76:79]
	s_waitcnt lgkmcnt(6)
	v_mfma_f32_16x16x32_bf16 v[120:123], v[150:153], v[186:189], v[120:123]
	v_mfma_f32_16x16x32_bf16 v[104:107], v[154:157], v[186:189], v[104:107]
	v_mfma_f32_16x16x32_bf16 v[88:91], v[158:161], v[186:189], v[88:91]
	v_mfma_f32_16x16x32_bf16 v[72:75], v[162:165], v[186:189], v[72:75]
	s_waitcnt lgkmcnt(5)
	v_mfma_f32_16x16x32_bf16 v[116:119], v[150:153], v[190:193], v[116:119]
	v_mfma_f32_16x16x32_bf16 v[100:103], v[154:157], v[190:193], v[100:103]
	v_mfma_f32_16x16x32_bf16 v[84:87], v[158:161], v[190:193], v[84:87]
	v_mfma_f32_16x16x32_bf16 v[68:71], v[162:165], v[190:193], v[68:71]
	s_waitcnt lgkmcnt(1)
	v_mfma_f32_16x16x32_bf16 v[112:115], v[150:153], v[194:197], v[112:115]
	v_mfma_f32_16x16x32_bf16 v[96:99], v[154:157], v[194:197], v[96:99]
	v_mfma_f32_16x16x32_bf16 v[80:83], v[158:161], v[194:197], v[80:83]
	v_mfma_f32_16x16x32_bf16 v[64:67], v[162:165], v[194:197], v[64:67]
	s_add_i32 s10, s10, 0x10000
	s_add_u32 s0, s0, 0x80
	s_addc_u32 s1, s1, 0
	s_cmpk_lg_i32 s0, 0x780
	s_waitcnt vmcnt(0) lgkmcnt(0)
	s_barrier
; #define WAIT_V(n) asm volatile("s_waitcnt vmcnt(%0)" ::"n"(n) : "memory")
; template <bool PRO>
; __device__ __forceinline__ void gemm_mainloop(const u16* __restrict__ Ab, const u16* __restrict__ Bb, int K,
;                                               f32x4 (&acc)[8][4]) {
;     ...
;   const int nt = K / BK;
;   if (PRO) GLDS_STAGE(0, 0);
;   WAIT_V(0);
;   __syncthreads();
;   for (int t = 0; t < nt; ++t) {
;     int cur = t & 1;
;     if (t + 1 < nt) GLDS_STAGE(cur ^ 1, t + 1);
;     __builtin_amdgcn_sched_barrier(0);
;     KSTEP(cur, 0);
;     KSTEP(cur, 1);
;     WAIT_V(0);
;     __syncthreads();
;   }
	s_cbranch_scc0 .Lpipe_exit_1504
	s_and_b32 s11, s10, 0x10000
	v_or_b32_e32 v247, s11, v139
	v_or_b32_e32 v248, s11, v140
	v_add_u32_e32 v198, v247, v147
	v_add_u32_e32 v199, v248, v145
	v_mfma_f32_16x16x32_bf16 v[60:63], v[166:169], v[178:181], v[60:63]
	v_add_u32_e32 v200, v248, v148
	v_add_u32_e32 v201, v248, v146
	v_add_u32_e32 v202, v248, v144
	v_add_u32_e32 v203, v248, v143
	v_mfma_f32_16x16x32_bf16 v[44:47], v[170:173], v[178:181], v[44:47]
	v_add_u32_e32 v206, v248, v142
	v_add_u32_e32 v207, v248, v141
	v_add_u32_e32 v249, v247, v137
	v_or_b32_e32 v149, s11, v128
	v_mfma_f32_16x16x32_bf16 v[28:31], v[174:177], v[178:181], v[28:31]
	ds_read_b128 v[150:153], v198
	ds_read_b128 v[154:157], v199
	v_mfma_f32_16x16x32_bf16 v[12:15], v[182:185], v[178:181], v[12:15]
	ds_read_b128 v[158:161], v200
	ds_read_b128 v[162:165], v201
	v_mfma_f32_16x16x32_bf16 v[56:59], v[166:169], v[186:189], v[56:59]
	ds_read_b128 v[178:181], v249 offset:32768
	s_xor_b32 s12, s11, 0x10000
	v_add_u32_e32 v250, s12, v138
	v_mfma_f32_16x16x32_bf16 v[40:43], v[170:173], v[186:189], v[40:43]
	v_lshl_add_u64 v[252:253], v[130:131], 0, s[0:1]
	v_readfirstlane_b32 s12, v250
	s_mov_b32 m0, s12
	v_mfma_f32_16x16x32_bf16 v[24:27], v[174:177], v[186:189], v[24:27]
	v_lshl_add_u64 v[254:255], v[252:253], 0, s[36:37]
	global_load_lds_dwordx4 v[254:255], off
	s_add_u32 m0, m0, 0x2000
	v_mfma_f32_16x16x32_bf16 v[8:11], v[182:185], v[186:189], v[8:11]
	ds_read_b128 v[186:189], v249 offset:34816
	v_mfma_f32_16x16x32_bf16 v[52:55], v[166:169], v[190:193], v[52:55]
	v_lshl_add_u64 v[254:255], v[252:253], 0, s[40:41]
	global_load_lds_dwordx4 v[254:255], off
	s_add_u32 m0, m0, 0x2000
	v_mfma_f32_16x16x32_bf16 v[36:39], v[170:173], v[190:193], v[36:39]
	v_mfma_f32_16x16x32_bf16 v[20:23], v[174:177], v[190:193], v[20:23]
	v_lshl_add_u64 v[254:255], v[252:253], 0, s[44:45]
	global_load_lds_dwordx4 v[254:255], off
	s_add_u32 m0, m0, 0x2000
	v_mfma_f32_16x16x32_bf16 v[4:7], v[182:185], v[190:193], v[4:7]
	ds_read_b128 v[190:193], v249 offset:36864
	v_mfma_f32_16x16x32_bf16 v[48:51], v[166:169], v[194:197], v[48:51]
	ds_read_b128 v[166:169], v202
	v_lshl_add_u64 v[254:255], v[252:253], 0, s[64:65]
	global_load_lds_dwordx4 v[254:255], off
	s_add_u32 m0, m0, 0x2000
	v_mfma_f32_16x16x32_bf16 v[32:35], v[170:173], v[194:197], v[32:35]
	ds_read_b128 v[170:173], v203
	v_mfma_f32_16x16x32_bf16 v[16:19], v[174:177], v[194:197], v[16:19]
	ds_read_b128 v[174:177], v206
	v_mfma_f32_16x16x32_bf16 v[0:3], v[182:185], v[194:197], v[0:3]
	ds_read_b128 v[194:197], v249 offset:38912
	ds_read_b128 v[182:185], v207
	s_branch .LBB0_1504

; #define WAIT_V(n) asm volatile("s_waitcnt vmcnt(%0)" ::"n"(n) : "memory")
; template <bool PRO>
; __device__ __forceinline__ void gemm_mainloop(const u16* __restrict__ Ab, const u16* __restrict__ Bb, int K,
;                                               f32x4 (&acc)[8][4]) {
;     ...
;   const int nt = K / BK;
;   if (PRO) GLDS_STAGE(0, 0);
;   WAIT_V(0);
;   __syncthreads();
;   for (int t = 0; t < nt; ++t) {
;     int cur = t & 1;
;     if (t + 1 < nt) GLDS_STAGE(cur ^ 1, t + 1);
;     __builtin_amdgcn_sched_barrier(0);
;     KSTEP(cur, 0);
;     KSTEP(cur, 1);
;     WAIT_V(0);
;     __syncthreads();
;   }
.LBB0_1526:
	s_waitcnt lgkmcnt(7)
	v_mfma_f32_16x16x32_bf16 v[124:127], v[150:153], v[178:181], v[124:127]
	v_mfma_f32_16x16x32_bf16 v[108:111], v[154:157], v[178:181], v[108:111]
	v_lshl_add_u64 v[252:253], v[130:131], 0, s[0:1]
	v_lshl_add_u64 v[254:255], v[252:253], 0, s[18:19]
	global_load_lds_dwordx4 v[254:255], off
	s_add_u32 m0, m0, 0x2000
	v_mfma_f32_16x16x32_bf16 v[92:95], v[158:161], v[178:181], v[92:95]
	v_mfma_f32_16x16x32_bf16 v[76:79], v[162:165], v[178:181], v[76:79]
	s_waitcnt lgkmcnt(6)
	v_mfma_f32_16x16x32_bf16 v[120:123], v[150:153], v[186:189], v[120:123]
	v_lshl_add_u64 v[254:255], v[252:253], 0, s[22:23]
	global_load_lds_dwordx4 v[254:255], off
	s_add_u32 m0, m0, 0x2000
	v_mfma_f32_16x16x32_bf16 v[104:107], v[154:157], v[186:189], v[104:107]
	v_mfma_f32_16x16x32_bf16 v[88:91], v[158:161], v[186:189], v[88:91]
	v_mfma_f32_16x16x32_bf16 v[72:75], v[162:165], v[186:189], v[72:75]
	v_lshl_add_u64 v[254:255], v[252:253], 0, s[26:27]
	global_load_lds_dwordx4 v[254:255], off
	s_add_u32 m0, m0, 0x2000
	s_waitcnt lgkmcnt(5)
	v_mfma_f32_16x16x32_bf16 v[116:119], v[150:153], v[190:193], v[116:119]
	v_mfma_f32_16x16x32_bf16 v[100:103], v[154:157], v[190:193], v[100:103]
	v_mfma_f32_16x16x32_bf16 v[84:87], v[158:161], v[190:193], v[84:87]
	v_lshl_add_u64 v[254:255], v[252:253], 0, s[30:31]
	global_load_lds_dwordx4 v[254:255], off
	v_mfma_f32_16x16x32_bf16 v[68:71], v[162:165], v[190:193], v[68:71]
	s_waitcnt lgkmcnt(1)
	v_mfma_f32_16x16x32_bf16 v[112:115], v[150:153], v[194:197], v[112:115]
	ds_read_b128 v[150:153], v198 offset:1024
	v_mfma_f32_16x16x32_bf16 v[96:99], v[154:157], v[194:197], v[96:99]
	ds_read_b128 v[154:157], v199 offset:1024
	v_mfma_f32_16x16x32_bf16 v[80:83], v[158:161], v[194:197], v[80:83]
	ds_read_b128 v[158:161], v200 offset:1024
	v_mfma_f32_16x16x32_bf16 v[64:67], v[162:165], v[194:197], v[64:67]
	ds_read_b128 v[162:165], v201 offset:1024
	v_mfma_f32_16x16x32_bf16 v[60:63], v[166:169], v[178:181], v[60:63]
	v_mfma_f32_16x16x32_bf16 v[44:47], v[170:173], v[178:181], v[44:47]
	v_mfma_f32_16x16x32_bf16 v[28:31], v[174:177], v[178:181], v[28:31]
	s_waitcnt lgkmcnt(4)
	v_mfma_f32_16x16x32_bf16 v[12:15], v[182:185], v[178:181], v[12:15]
	ds_read_b128 v[178:181], v149 offset:33792
	v_mfma_f32_16x16x32_bf16 v[56:59], v[166:169], v[186:189], v[56:59]
	v_mfma_f32_16x16x32_bf16 v[40:43], v[170:173], v[186:189], v[40:43]
	v_mfma_f32_16x16x32_bf16 v[24:27], v[174:177], v[186:189], v[24:27]
	v_mfma_f32_16x16x32_bf16 v[8:11], v[182:185], v[186:189], v[8:11]
	ds_read_b128 v[186:189], v149 offset:35840
	v_mfma_f32_16x16x32_bf16 v[52:55], v[166:169], v[190:193], v[52:55]
	v_mfma_f32_16x16x32_bf16 v[36:39], v[170:173], v[190:193], v[36:39]
	v_mfma_f32_16x16x32_bf16 v[20:23], v[174:177], v[190:193], v[20:23]
	v_mfma_f32_16x16x32_bf16 v[4:7], v[182:185], v[190:193], v[4:7]
	ds_read_b128 v[190:193], v149 offset:37888
	v_mfma_f32_16x16x32_bf16 v[48:51], v[166:169], v[194:197], v[48:51]
	ds_read_b128 v[166:169], v202 offset:1024
	v_mfma_f32_16x16x32_bf16 v[32:35], v[170:173], v[194:197], v[32:35]
	ds_read_b128 v[170:173], v203 offset:1024
	v_mfma_f32_16x16x32_bf16 v[16:19], v[174:177], v[194:197], v[16:19]
	ds_read_b128 v[174:177], v206 offset:1024
	v_mfma_f32_16x16x32_bf16 v[0:3], v[182:185], v[194:197], v[0:3]
	ds_read_b128 v[194:197], v149 offset:39936
	ds_read_b128 v[182:185], v207 offset:1024
	s_waitcnt lgkmcnt(7)
	v_mfma_f32_16x16x32_bf16 v[124:127], v[150:153], v[178:181], v[124:127]
	v_mfma_f32_16x16x32_bf16 v[108:111], v[154:157], v[178:181], v[108:111]
	v_mfma_f32_16x16x32_bf16 v[92:95], v[158:161], v[178:181], v[92:95]
	v_mfma_f32_16x16x32_bf16 v[76:79], v[162:165], v[178:181], v[76:79]
	s_waitcnt lgkmcnt(6)
	v_mfma_f32_16x16x32_bf16 v[120:123], v[150:153], v[186:189], v[120:123]
	v_mfma_f32_16x16x32_bf16 v[104:107], v[154:157], v[186:189], v[104:107]
	v_mfma_f32_16x16x32_bf16 v[88:91], v[158:161], v[186:189], v[88:91]
	v_mfma_f32_16x16x32_bf16 v[72:75], v[162:165], v[186:189], v[72:75]
	s_waitcnt lgkmcnt(5)
	v_mfma_f32_16x16x32_bf16 v[116:119], v[150:153], v[190:193], v[116:119]
	v_mfma_f32_16x16x32_bf16 v[100:103], v[154:157], v[190:193], v[100:103]
	v_mfma_f32_16x16x32_bf16 v[84:87], v[158:161], v[190:193], v[84:87]
	v_mfma_f32_16x16x32_bf16 v[68:71], v[162:165], v[190:193], v[68:71]
	s_waitcnt lgkmcnt(1)
	v_mfma_f32_16x16x32_bf16 v[112:115], v[150:153], v[194:197], v[112:115]
	v_mfma_f32_16x16x32_bf16 v[96:99], v[154:157], v[194:197], v[96:99]
	v_mfma_f32_16x16x32_bf16 v[80:83], v[158:161], v[194:197], v[80:83]
	v_mfma_f32_16x16x32_bf16 v[64:67], v[162:165], v[194:197], v[64:67]
	s_add_u32 s0, s0, 0x80
	s_addc_u32 s1, s1, 0
	s_add_i32 s40, s40, 0x10000
	s_cmpk_lg_i32 s0, 0x1580
	s_waitcnt vmcnt(0) lgkmcnt(0)
	s_barrier
; #define WAIT_V(n) asm volatile("s_waitcnt vmcnt(%0)" ::"n"(n) : "memory")
; template <bool PRO>
; __device__ __forceinline__ void gemm_mainloop(const u16* __restrict__ Ab, const u16* __restrict__ Bb, int K,
;                                               f32x4 (&acc)[8][4]) {
;     ...
;   const int nt = K / BK;
;   if (PRO) GLDS_STAGE(0, 0);
;   WAIT_V(0);
;   __syncthreads();
;   for (int t = 0; t < nt; ++t) {
;     int cur = t & 1;
;     if (t + 1 < nt) GLDS_STAGE(cur ^ 1, t + 1);
;     __builtin_amdgcn_sched_barrier(0);
;     KSTEP(cur, 0);
;     KSTEP(cur, 1);
;     WAIT_V(0);
;     __syncthreads();
;   }
	s_cbranch_scc0 .Lpipe_exit_1526
	s_and_b32 s41, s40, 0x10000
	v_or_b32_e32 v247, s41, v139
	v_or_b32_e32 v248, s41, v140
	v_add_u32_e32 v198, v247, v147
	v_add_u32_e32 v199, v248, v145
	v_mfma_f32_16x16x32_bf16 v[60:63], v[166:169], v[178:181], v[60:63]
	v_add_u32_e32 v200, v248, v148
	v_add_u32_e32 v201, v248, v146
	v_add_u32_e32 v202, v248, v144
	v_add_u32_e32 v203, v248, v143
	v_mfma_f32_16x16x32_bf16 v[44:47], v[170:173], v[178:181], v[44:47]
	v_add_u32_e32 v206, v248, v142
	v_add_u32_e32 v207, v248, v141
	v_add_u32_e32 v249, v247, v137
	v_or_b32_e32 v149, s41, v136
	v_mfma_f32_16x16x32_bf16 v[28:31], v[174:177], v[178:181], v[28:31]
	ds_read_b128 v[150:153], v198
	ds_read_b128 v[154:157], v199
	v_mfma_f32_16x16x32_bf16 v[12:15], v[182:185], v[178:181], v[12:15]
	ds_read_b128 v[158:161], v200
	ds_read_b128 v[162:165], v201
	v_mfma_f32_16x16x32_bf16 v[56:59], v[166:169], v[186:189], v[56:59]
	ds_read_b128 v[178:181], v249 offset:32768
	s_xor_b32 s62, s41, 0x10000
	v_add_u32_e32 v250, s62, v138
	v_mfma_f32_16x16x32_bf16 v[40:43], v[170:173], v[186:189], v[40:43]
	v_lshl_add_u64 v[252:253], v[128:129], 0, s[0:1]
	v_readfirstlane_b32 s62, v250
	s_mov_b32 m0, s62
	v_mfma_f32_16x16x32_bf16 v[24:27], v[174:177], v[186:189], v[24:27]
	v_lshl_add_u64 v[254:255], v[252:253], 0, s[16:17]
	global_load_lds_dwordx4 v[254:255], off
	s_add_u32 m0, m0, 0x2000
	v_mfma_f32_16x16x32_bf16 v[8:11], v[182:185], v[186:189], v[8:11]
	ds_read_b128 v[186:189], v249 offset:34816
	v_mfma_f32_16x16x32_bf16 v[52:55], v[166:169], v[190:193], v[52:55]
	v_lshl_add_u64 v[254:255], v[252:253], 0, s[20:21]
	global_load_lds_dwordx4 v[254:255], off
	s_add_u32 m0, m0, 0x2000
	v_mfma_f32_16x16x32_bf16 v[36:39], v[170:173], v[190:193], v[36:39]
	v_mfma_f32_16x16x32_bf16 v[20:23], v[174:177], v[190:193], v[20:23]
	v_lshl_add_u64 v[254:255], v[252:253], 0, s[24:25]
	global_load_lds_dwordx4 v[254:255], off
	s_add_u32 m0, m0, 0x2000
	v_mfma_f32_16x16x32_bf16 v[4:7], v[182:185], v[190:193], v[4:7]
	ds_read_b128 v[190:193], v249 offset:36864
	v_mfma_f32_16x16x32_bf16 v[48:51], v[166:169], v[194:197], v[48:51]
	ds_read_b128 v[166:169], v202
	v_lshl_add_u64 v[254:255], v[252:253], 0, s[28:29]
	global_load_lds_dwordx4 v[254:255], off
	s_add_u32 m0, m0, 0x2000
	v_mfma_f32_16x16x32_bf16 v[32:35], v[170:173], v[194:197], v[32:35]
	ds_read_b128 v[170:173], v203
	v_mfma_f32_16x16x32_bf16 v[16:19], v[174:177], v[194:197], v[16:19]
	ds_read_b128 v[174:177], v206
	v_mfma_f32_16x16x32_bf16 v[0:3], v[182:185], v[194:197], v[0:3]
	ds_read_b128 v[194:197], v249 offset:38912
	ds_read_b128 v[182:185], v207
	s_branch .LBB0_1526

; #define WAIT_V(n) asm volatile("s_waitcnt vmcnt(%0)" ::"n"(n) : "memory")
; template <bool PRO>
; __device__ __forceinline__ void gemm_mainloop(const u16* __restrict__ Ab, const u16* __restrict__ Bb, int K,
;                                               f32x4 (&acc)[8][4]) {
;     ...
;   const int nt = K / BK;
;   if (PRO) GLDS_STAGE(0, 0);
;   WAIT_V(0);
;   __syncthreads();
;   for (int t = 0; t < nt; ++t) {
;     int cur = t & 1;
;     if (t + 1 < nt) GLDS_STAGE(cur ^ 1, t + 1);
;     __builtin_amdgcn_sched_barrier(0);
;     KSTEP(cur, 0);
;     KSTEP(cur, 1);
;     WAIT_V(0);
;     __syncthreads();
;   }
.LBB0_1638:
	s_waitcnt lgkmcnt(7)
	v_mfma_f32_16x16x32_bf16 v[124:127], v[150:153], v[178:181], v[124:127]
	v_mfma_f32_16x16x32_bf16 v[108:111], v[154:157], v[178:181], v[108:111]
	v_lshl_add_u64 v[252:253], v[130:131], 0, s[0:1]
	v_lshl_add_u64 v[254:255], v[252:253], 0, s[36:37]
	global_load_lds_dwordx4 v[254:255], off
	s_add_u32 m0, m0, 0x2000
	v_mfma_f32_16x16x32_bf16 v[92:95], v[158:161], v[178:181], v[92:95]
	v_mfma_f32_16x16x32_bf16 v[76:79], v[162:165], v[178:181], v[76:79]
	s_waitcnt lgkmcnt(6)
	v_mfma_f32_16x16x32_bf16 v[120:123], v[150:153], v[186:189], v[120:123]
	v_lshl_add_u64 v[254:255], v[252:253], 0, s[40:41]
	global_load_lds_dwordx4 v[254:255], off
	s_add_u32 m0, m0, 0x2000
	v_mfma_f32_16x16x32_bf16 v[104:107], v[154:157], v[186:189], v[104:107]
	v_mfma_f32_16x16x32_bf16 v[88:91], v[158:161], v[186:189], v[88:91]
	v_mfma_f32_16x16x32_bf16 v[72:75], v[162:165], v[186:189], v[72:75]
	v_lshl_add_u64 v[254:255], v[252:253], 0, s[44:45]
	global_load_lds_dwordx4 v[254:255], off
	s_add_u32 m0, m0, 0x2000
	s_waitcnt lgkmcnt(5)
	v_mfma_f32_16x16x32_bf16 v[116:119], v[150:153], v[190:193], v[116:119]
	v_mfma_f32_16x16x32_bf16 v[100:103], v[154:157], v[190:193], v[100:103]
	v_mfma_f32_16x16x32_bf16 v[84:87], v[158:161], v[190:193], v[84:87]
	v_lshl_add_u64 v[254:255], v[252:253], 0, s[62:63]
	global_load_lds_dwordx4 v[254:255], off
	v_mfma_f32_16x16x32_bf16 v[68:71], v[162:165], v[190:193], v[68:71]
	s_waitcnt lgkmcnt(1)
	v_mfma_f32_16x16x32_bf16 v[112:115], v[150:153], v[194:197], v[112:115]
	ds_read_b128 v[150:153], v198 offset:1024
	v_mfma_f32_16x16x32_bf16 v[96:99], v[154:157], v[194:197], v[96:99]
	ds_read_b128 v[154:157], v199 offset:1024
	v_mfma_f32_16x16x32_bf16 v[80:83], v[158:161], v[194:197], v[80:83]
	ds_read_b128 v[158:161], v200 offset:1024
	v_mfma_f32_16x16x32_bf16 v[64:67], v[162:165], v[194:197], v[64:67]
	ds_read_b128 v[162:165], v201 offset:1024
	v_mfma_f32_16x16x32_bf16 v[60:63], v[166:169], v[178:181], v[60:63]
	v_mfma_f32_16x16x32_bf16 v[44:47], v[170:173], v[178:181], v[44:47]
	v_mfma_f32_16x16x32_bf16 v[28:31], v[174:177], v[178:181], v[28:31]
	s_waitcnt lgkmcnt(4)
	v_mfma_f32_16x16x32_bf16 v[12:15], v[182:185], v[178:181], v[12:15]
	ds_read_b128 v[178:181], v149 offset:33792
	v_mfma_f32_16x16x32_bf16 v[56:59], v[166:169], v[186:189], v[56:59]
	v_mfma_f32_16x16x32_bf16 v[40:43], v[170:173], v[186:189], v[40:43]
	v_mfma_f32_16x16x32_bf16 v[24:27], v[174:177], v[186:189], v[24:27]
	v_mfma_f32_16x16x32_bf16 v[8:11], v[182:185], v[186:189], v[8:11]
	ds_read_b128 v[186:189], v149 offset:35840
	v_mfma_f32_16x16x32_bf16 v[52:55], v[166:169], v[190:193], v[52:55]
	v_mfma_f32_16x16x32_bf16 v[36:39], v[170:173], v[190:193], v[36:39]
	v_mfma_f32_16x16x32_bf16 v[20:23], v[174:177], v[190:193], v[20:23]
	v_mfma_f32_16x16x32_bf16 v[4:7], v[182:185], v[190:193], v[4:7]
	ds_read_b128 v[190:193], v149 offset:37888
	v_mfma_f32_16x16x32_bf16 v[48:51], v[166:169], v[194:197], v[48:51]
	ds_read_b128 v[166:169], v202 offset:1024
	v_mfma_f32_16x16x32_bf16 v[32:35], v[170:173], v[194:197], v[32:35]
	ds_read_b128 v[170:173], v203 offset:1024
	v_mfma_f32_16x16x32_bf16 v[16:19], v[174:177], v[194:197], v[16:19]
	ds_read_b128 v[174:177], v206 offset:1024
	v_mfma_f32_16x16x32_bf16 v[0:3], v[182:185], v[194:197], v[0:3]
	ds_read_b128 v[194:197], v149 offset:39936
	ds_read_b128 v[182:185], v207 offset:1024
	s_waitcnt lgkmcnt(7)
	v_mfma_f32_16x16x32_bf16 v[124:127], v[150:153], v[178:181], v[124:127]
	v_mfma_f32_16x16x32_bf16 v[108:111], v[154:157], v[178:181], v[108:111]
	v_mfma_f32_16x16x32_bf16 v[92:95], v[158:161], v[178:181], v[92:95]
	v_mfma_f32_16x16x32_bf16 v[76:79], v[162:165], v[178:181], v[76:79]
	s_waitcnt lgkmcnt(6)
	v_mfma_f32_16x16x32_bf16 v[120:123], v[150:153], v[186:189], v[120:123]
	v_mfma_f32_16x16x32_bf16 v[104:107], v[154:157], v[186:189], v[104:107]
	v_mfma_f32_16x16x32_bf16 v[88:91], v[158:161], v[186:189], v[88:91]
	v_mfma_f32_16x16x32_bf16 v[72:75], v[162:165], v[186:189], v[72:75]
	s_waitcnt lgkmcnt(5)
	v_mfma_f32_16x16x32_bf16 v[116:119], v[150:153], v[190:193], v[116:119]
	v_mfma_f32_16x16x32_bf16 v[100:103], v[154:157], v[190:193], v[100:103]
	v_mfma_f32_16x16x32_bf16 v[84:87], v[158:161], v[190:193], v[84:87]
	v_mfma_f32_16x16x32_bf16 v[68:71], v[162:165], v[190:193], v[68:71]
	s_waitcnt lgkmcnt(1)
	v_mfma_f32_16x16x32_bf16 v[112:115], v[150:153], v[194:197], v[112:115]
	v_mfma_f32_16x16x32_bf16 v[96:99], v[154:157], v[194:197], v[96:99]
	v_mfma_f32_16x16x32_bf16 v[80:83], v[158:161], v[194:197], v[80:83]
	v_mfma_f32_16x16x32_bf16 v[64:67], v[162:165], v[194:197], v[64:67]
	s_add_i32 s10, s10, 0x10000
	s_add_u32 s0, s0, 0x80
	s_addc_u32 s1, s1, 0
	s_cmpk_lg_i32 s0, 0x780
	s_waitcnt vmcnt(0) lgkmcnt(0)
	s_barrier
; #define WAIT_V(n) asm volatile("s_waitcnt vmcnt(%0)" ::"n"(n) : "memory")
; template <bool PRO>
; __device__ __forceinline__ void gemm_mainloop(const u16* __restrict__ Ab, const u16* __restrict__ Bb, int K,
;                                               f32x4 (&acc)[8][4]) {
;     ...
;   const int nt = K / BK;
;   if (PRO) GLDS_STAGE(0, 0);
;   WAIT_V(0);
;   __syncthreads();
;   for (int t = 0; t < nt; ++t) {
;     int cur = t & 1;
;     if (t + 1 < nt) GLDS_STAGE(cur ^ 1, t + 1);
;     __builtin_amdgcn_sched_barrier(0);
;     KSTEP(cur, 0);
;     KSTEP(cur, 1);
;     WAIT_V(0);
;     __syncthreads();
;   }
	s_cbranch_scc0 .Lpipe_exit_1638
	s_and_b32 s11, s10, 0x10000
	v_or_b32_e32 v247, s11, v139
	v_or_b32_e32 v248, s11, v140
	v_add_u32_e32 v198, v247, v147
	v_add_u32_e32 v199, v248, v145
	v_mfma_f32_16x16x32_bf16 v[60:63], v[166:169], v[178:181], v[60:63]
	v_add_u32_e32 v200, v248, v148
	v_add_u32_e32 v201, v248, v146
	v_add_u32_e32 v202, v248, v144
	v_add_u32_e32 v203, v248, v143
	v_mfma_f32_16x16x32_bf16 v[44:47], v[170:173], v[178:181], v[44:47]
	v_add_u32_e32 v206, v248, v142
	v_add_u32_e32 v207, v248, v141
	v_add_u32_e32 v249, v247, v137
	v_or_b32_e32 v149, s11, v136
	v_mfma_f32_16x16x32_bf16 v[28:31], v[174:177], v[178:181], v[28:31]
	ds_read_b128 v[150:153], v198
	ds_read_b128 v[154:157], v199
	v_mfma_f32_16x16x32_bf16 v[12:15], v[182:185], v[178:181], v[12:15]
	ds_read_b128 v[158:161], v200
	ds_read_b128 v[162:165], v201
	v_mfma_f32_16x16x32_bf16 v[56:59], v[166:169], v[186:189], v[56:59]
	ds_read_b128 v[178:181], v249 offset:32768
	s_xor_b32 s23, s11, 0x10000
	v_add_u32_e32 v250, s23, v138
	v_mfma_f32_16x16x32_bf16 v[40:43], v[170:173], v[186:189], v[40:43]
	v_lshl_add_u64 v[252:253], v[128:129], 0, s[0:1]
	v_readfirstlane_b32 s23, v250
	s_mov_b32 m0, s23
	v_mfma_f32_16x16x32_bf16 v[24:27], v[174:177], v[186:189], v[24:27]
	v_lshl_add_u64 v[254:255], v[252:253], 0, s[34:35]
	global_load_lds_dwordx4 v[254:255], off
	s_add_u32 m0, m0, 0x2000
	v_mfma_f32_16x16x32_bf16 v[8:11], v[182:185], v[186:189], v[8:11]
	ds_read_b128 v[186:189], v249 offset:34816
	v_mfma_f32_16x16x32_bf16 v[52:55], v[166:169], v[190:193], v[52:55]
	v_lshl_add_u64 v[254:255], v[252:253], 0, s[38:39]
	global_load_lds_dwordx4 v[254:255], off
	s_add_u32 m0, m0, 0x2000
	v_mfma_f32_16x16x32_bf16 v[36:39], v[170:173], v[190:193], v[36:39]
	v_mfma_f32_16x16x32_bf16 v[20:23], v[174:177], v[190:193], v[20:23]
	v_lshl_add_u64 v[254:255], v[252:253], 0, s[42:43]
	global_load_lds_dwordx4 v[254:255], off
	s_add_u32 m0, m0, 0x2000
	v_mfma_f32_16x16x32_bf16 v[4:7], v[182:185], v[190:193], v[4:7]
	ds_read_b128 v[190:193], v249 offset:36864
	v_mfma_f32_16x16x32_bf16 v[48:51], v[166:169], v[194:197], v[48:51]
	ds_read_b128 v[166:169], v202
	v_lshl_add_u64 v[254:255], v[252:253], 0, s[60:61]
	global_load_lds_dwordx4 v[254:255], off
	s_add_u32 m0, m0, 0x2000
	v_mfma_f32_16x16x32_bf16 v[32:35], v[170:173], v[194:197], v[32:35]
	ds_read_b128 v[170:173], v203
	v_mfma_f32_16x16x32_bf16 v[16:19], v[174:177], v[194:197], v[16:19]
	ds_read_b128 v[174:177], v206
	v_mfma_f32_16x16x32_bf16 v[0:3], v[182:185], v[194:197], v[0:3]
	ds_read_b128 v[194:197], v249 offset:38912
	ds_read_b128 v[182:185], v207
	s_branch .LBB0_1638

; #define WAIT_V(n) asm volatile("s_waitcnt vmcnt(%0)" ::"n"(n) : "memory")
; template <bool PRO>
; __device__ __forceinline__ void gemm_mainloop(const u16* __restrict__ Ab, const u16* __restrict__ Bb, int K,
;                                               f32x4 (&acc)[8][4]) {
;     ...
;   const int nt = K / BK;
;   if (PRO) GLDS_STAGE(0, 0);
;   WAIT_V(0);
;   __syncthreads();
;   for (int t = 0; t < nt; ++t) {
;     int cur = t & 1;
;     if (t + 1 < nt) GLDS_STAGE(cur ^ 1, t + 1);
;     __builtin_amdgcn_sched_barrier(0);
;     KSTEP(cur, 0);
;     KSTEP(cur, 1);
;     WAIT_V(0);
;     __syncthreads();
;   }
.LBB0_1736:
	s_waitcnt lgkmcnt(7)
	v_mfma_f32_16x16x32_bf16 v[124:127], v[150:153], v[178:181], v[124:127]
	v_mfma_f32_16x16x32_bf16 v[108:111], v[154:157], v[178:181], v[108:111]
	v_lshl_add_u64 v[252:253], v[132:133], 0, s[0:1]
	v_lshl_add_u64 v[254:255], v[252:253], 0, s[38:39]
	global_load_lds_dwordx4 v[254:255], off
	s_add_u32 m0, m0, 0x2000
	v_mfma_f32_16x16x32_bf16 v[92:95], v[158:161], v[178:181], v[92:95]
	v_mfma_f32_16x16x32_bf16 v[76:79], v[162:165], v[178:181], v[76:79]
	s_waitcnt lgkmcnt(6)
	v_mfma_f32_16x16x32_bf16 v[120:123], v[150:153], v[186:189], v[120:123]
	v_lshl_add_u64 v[254:255], v[252:253], 0, s[42:43]
	global_load_lds_dwordx4 v[254:255], off
	s_add_u32 m0, m0, 0x2000
	v_mfma_f32_16x16x32_bf16 v[104:107], v[154:157], v[186:189], v[104:107]
	v_mfma_f32_16x16x32_bf16 v[88:91], v[158:161], v[186:189], v[88:91]
	v_mfma_f32_16x16x32_bf16 v[72:75], v[162:165], v[186:189], v[72:75]
	v_lshl_add_u64 v[254:255], v[252:253], 0, s[60:61]
	global_load_lds_dwordx4 v[254:255], off
	s_add_u32 m0, m0, 0x2000
	s_waitcnt lgkmcnt(5)
	v_mfma_f32_16x16x32_bf16 v[116:119], v[150:153], v[190:193], v[116:119]
	v_mfma_f32_16x16x32_bf16 v[100:103], v[154:157], v[190:193], v[100:103]
	v_mfma_f32_16x16x32_bf16 v[84:87], v[158:161], v[190:193], v[84:87]
	v_lshl_add_u64 v[254:255], v[252:253], 0, s[64:65]
	global_load_lds_dwordx4 v[254:255], off
	v_mfma_f32_16x16x32_bf16 v[68:71], v[162:165], v[190:193], v[68:71]
	s_waitcnt lgkmcnt(1)
	v_mfma_f32_16x16x32_bf16 v[112:115], v[150:153], v[194:197], v[112:115]
	ds_read_b128 v[150:153], v198 offset:1024
	v_mfma_f32_16x16x32_bf16 v[96:99], v[154:157], v[194:197], v[96:99]
	ds_read_b128 v[154:157], v199 offset:1024
	v_mfma_f32_16x16x32_bf16 v[80:83], v[158:161], v[194:197], v[80:83]
	ds_read_b128 v[158:161], v200 offset:1024
	v_mfma_f32_16x16x32_bf16 v[64:67], v[162:165], v[194:197], v[64:67]
	ds_read_b128 v[162:165], v201 offset:1024
	v_mfma_f32_16x16x32_bf16 v[60:63], v[166:169], v[178:181], v[60:63]
	v_mfma_f32_16x16x32_bf16 v[44:47], v[170:173], v[178:181], v[44:47]
	v_mfma_f32_16x16x32_bf16 v[28:31], v[174:177], v[178:181], v[28:31]
	s_waitcnt lgkmcnt(4)
	v_mfma_f32_16x16x32_bf16 v[12:15], v[182:185], v[178:181], v[12:15]
	ds_read_b128 v[178:181], v149 offset:33792
	v_mfma_f32_16x16x32_bf16 v[56:59], v[166:169], v[186:189], v[56:59]
	v_mfma_f32_16x16x32_bf16 v[40:43], v[170:173], v[186:189], v[40:43]
	v_mfma_f32_16x16x32_bf16 v[24:27], v[174:177], v[186:189], v[24:27]
	v_mfma_f32_16x16x32_bf16 v[8:11], v[182:185], v[186:189], v[8:11]
	ds_read_b128 v[186:189], v149 offset:35840
	v_mfma_f32_16x16x32_bf16 v[52:55], v[166:169], v[190:193], v[52:55]
	v_mfma_f32_16x16x32_bf16 v[36:39], v[170:173], v[190:193], v[36:39]
	v_mfma_f32_16x16x32_bf16 v[20:23], v[174:177], v[190:193], v[20:23]
	v_mfma_f32_16x16x32_bf16 v[4:7], v[182:185], v[190:193], v[4:7]
	ds_read_b128 v[190:193], v149 offset:37888
	v_mfma_f32_16x16x32_bf16 v[48:51], v[166:169], v[194:197], v[48:51]
	ds_read_b128 v[166:169], v202 offset:1024
	v_mfma_f32_16x16x32_bf16 v[32:35], v[170:173], v[194:197], v[32:35]
	ds_read_b128 v[170:173], v203 offset:1024
	v_mfma_f32_16x16x32_bf16 v[16:19], v[174:177], v[194:197], v[16:19]
	ds_read_b128 v[174:177], v206 offset:1024
	v_mfma_f32_16x16x32_bf16 v[0:3], v[182:185], v[194:197], v[0:3]
	ds_read_b128 v[194:197], v149 offset:39936
	ds_read_b128 v[182:185], v207 offset:1024
	s_waitcnt lgkmcnt(7)
	v_mfma_f32_16x16x32_bf16 v[124:127], v[150:153], v[178:181], v[124:127]
	v_mfma_f32_16x16x32_bf16 v[108:111], v[154:157], v[178:181], v[108:111]
	v_mfma_f32_16x16x32_bf16 v[92:95], v[158:161], v[178:181], v[92:95]
	v_mfma_f32_16x16x32_bf16 v[76:79], v[162:165], v[178:181], v[76:79]
	s_waitcnt lgkmcnt(6)
	v_mfma_f32_16x16x32_bf16 v[120:123], v[150:153], v[186:189], v[120:123]
	v_mfma_f32_16x16x32_bf16 v[104:107], v[154:157], v[186:189], v[104:107]
	v_mfma_f32_16x16x32_bf16 v[88:91], v[158:161], v[186:189], v[88:91]
	v_mfma_f32_16x16x32_bf16 v[72:75], v[162:165], v[186:189], v[72:75]
	s_waitcnt lgkmcnt(5)
	v_mfma_f32_16x16x32_bf16 v[116:119], v[150:153], v[190:193], v[116:119]
	v_mfma_f32_16x16x32_bf16 v[100:103], v[154:157], v[190:193], v[100:103]
	v_mfma_f32_16x16x32_bf16 v[84:87], v[158:161], v[190:193], v[84:87]
	v_mfma_f32_16x16x32_bf16 v[68:71], v[162:165], v[190:193], v[68:71]
	s_waitcnt lgkmcnt(1)
	v_mfma_f32_16x16x32_bf16 v[112:115], v[150:153], v[194:197], v[112:115]
	v_mfma_f32_16x16x32_bf16 v[96:99], v[154:157], v[194:197], v[96:99]
	v_mfma_f32_16x16x32_bf16 v[80:83], v[158:161], v[194:197], v[80:83]
	v_mfma_f32_16x16x32_bf16 v[64:67], v[162:165], v[194:197], v[64:67]
	s_add_i32 s10, s10, 0x10000
	s_add_u32 s0, s0, 0x80
	s_addc_u32 s1, s1, 0
	s_cmpk_lg_i32 s0, 0x780
	s_waitcnt vmcnt(0) lgkmcnt(0)
	s_barrier
; #define WAIT_V(n) asm volatile("s_waitcnt vmcnt(%0)" ::"n"(n) : "memory")
; template <bool PRO>
; __device__ __forceinline__ void gemm_mainloop(const u16* __restrict__ Ab, const u16* __restrict__ Bb, int K,
;                                               f32x4 (&acc)[8][4]) {
;     ...
;   const int nt = K / BK;
;   if (PRO) GLDS_STAGE(0, 0);
;   WAIT_V(0);
;   __syncthreads();
;   for (int t = 0; t < nt; ++t) {
;     int cur = t & 1;
;     if (t + 1 < nt) GLDS_STAGE(cur ^ 1, t + 1);
;     __builtin_amdgcn_sched_barrier(0);
;     KSTEP(cur, 0);
;     KSTEP(cur, 1);
;     WAIT_V(0);
;     __syncthreads();
;   }
	s_cbranch_scc0 .Lpipe_exit_1736
	s_and_b32 s11, s10, 0x10000
	v_or_b32_e32 v247, s11, v139
	v_or_b32_e32 v248, s11, v140
	v_add_u32_e32 v198, v247, v147
	v_add_u32_e32 v199, v248, v145
	v_mfma_f32_16x16x32_bf16 v[60:63], v[166:169], v[178:181], v[60:63]
	v_add_u32_e32 v200, v248, v148
	v_add_u32_e32 v201, v248, v146
	v_add_u32_e32 v202, v248, v144
	v_add_u32_e32 v203, v248, v143
	v_mfma_f32_16x16x32_bf16 v[44:47], v[170:173], v[178:181], v[44:47]
	v_add_u32_e32 v206, v248, v142
	v_add_u32_e32 v207, v248, v141
	v_add_u32_e32 v249, v247, v137
	v_or_b32_e32 v149, s11, v128
	v_mfma_f32_16x16x32_bf16 v[28:31], v[174:177], v[178:181], v[28:31]
	ds_read_b128 v[150:153], v198
	ds_read_b128 v[154:157], v199
	v_mfma_f32_16x16x32_bf16 v[12:15], v[182:185], v[178:181], v[12:15]
	ds_read_b128 v[158:161], v200
	ds_read_b128 v[162:165], v201
	v_mfma_f32_16x16x32_bf16 v[56:59], v[166:169], v[186:189], v[56:59]
	ds_read_b128 v[178:181], v249 offset:32768
	s_xor_b32 s12, s11, 0x10000
	v_add_u32_e32 v250, s12, v138
	v_mfma_f32_16x16x32_bf16 v[40:43], v[170:173], v[186:189], v[40:43]
	v_lshl_add_u64 v[252:253], v[130:131], 0, s[0:1]
	v_readfirstlane_b32 s12, v250
	s_mov_b32 m0, s12
	v_mfma_f32_16x16x32_bf16 v[24:27], v[174:177], v[186:189], v[24:27]
	v_lshl_add_u64 v[254:255], v[252:253], 0, s[36:37]
	global_load_lds_dwordx4 v[254:255], off
	s_add_u32 m0, m0, 0x2000
	v_mfma_f32_16x16x32_bf16 v[8:11], v[182:185], v[186:189], v[8:11]
	ds_read_b128 v[186:189], v249 offset:34816
	v_mfma_f32_16x16x32_bf16 v[52:55], v[166:169], v[190:193], v[52:55]
	v_lshl_add_u64 v[254:255], v[252:253], 0, s[40:41]
	global_load_lds_dwordx4 v[254:255], off
	s_add_u32 m0, m0, 0x2000
	v_mfma_f32_16x16x32_bf16 v[36:39], v[170:173], v[190:193], v[36:39]
	v_mfma_f32_16x16x32_bf16 v[20:23], v[174:177], v[190:193], v[20:23]
	v_lshl_add_u64 v[254:255], v[252:253], 0, s[44:45]
	global_load_lds_dwordx4 v[254:255], off
	s_add_u32 m0, m0, 0x2000
	v_mfma_f32_16x16x32_bf16 v[4:7], v[182:185], v[190:193], v[4:7]
	ds_read_b128 v[190:193], v249 offset:36864
	v_mfma_f32_16x16x32_bf16 v[48:51], v[166:169], v[194:197], v[48:51]
	ds_read_b128 v[166:169], v202
	v_lshl_add_u64 v[254:255], v[252:253], 0, s[62:63]
	global_load_lds_dwordx4 v[254:255], off
	s_add_u32 m0, m0, 0x2000
	v_mfma_f32_16x16x32_bf16 v[32:35], v[170:173], v[194:197], v[32:35]
	ds_read_b128 v[170:173], v203
	v_mfma_f32_16x16x32_bf16 v[16:19], v[174:177], v[194:197], v[16:19]
	ds_read_b128 v[174:177], v206
	v_mfma_f32_16x16x32_bf16 v[0:3], v[182:185], v[194:197], v[0:3]
	ds_read_b128 v[194:197], v249 offset:38912
	ds_read_b128 v[182:185], v207
	s_branch .LBB0_1736

; #define WAIT_V(n) asm volatile("s_waitcnt vmcnt(%0)" ::"n"(n) : "memory")
; template <bool PRO>
; __device__ __forceinline__ void gemm_mainloop(const u16* __restrict__ Ab, const u16* __restrict__ Bb, int K,
;                                               f32x4 (&acc)[8][4]) {
;     ...
;   const int nt = K / BK;
;   if (PRO) GLDS_STAGE(0, 0);
;   WAIT_V(0);
;   __syncthreads();
;   for (int t = 0; t < nt; ++t) {
;     int cur = t & 1;
;     if (t + 1 < nt) GLDS_STAGE(cur ^ 1, t + 1);
;     __builtin_amdgcn_sched_barrier(0);
;     KSTEP(cur, 0);
;     KSTEP(cur, 1);
;     WAIT_V(0);
;     __syncthreads();
;   }
.LBB0_1756:
	s_waitcnt lgkmcnt(7)
	v_mfma_f32_16x16x32_bf16 v[124:127], v[150:153], v[178:181], v[124:127]
	v_mfma_f32_16x16x32_bf16 v[108:111], v[154:157], v[178:181], v[108:111]
	v_lshl_add_u64 v[252:253], v[128:129], 0, s[0:1]
	v_lshl_add_u64 v[254:255], v[252:253], 0, s[22:23]
	global_load_lds_dwordx4 v[254:255], off
	s_add_u32 m0, m0, 0x2000
	v_mfma_f32_16x16x32_bf16 v[92:95], v[158:161], v[178:181], v[92:95]
	v_mfma_f32_16x16x32_bf16 v[76:79], v[162:165], v[178:181], v[76:79]
	s_waitcnt lgkmcnt(6)
	v_mfma_f32_16x16x32_bf16 v[120:123], v[150:153], v[186:189], v[120:123]
	v_lshl_add_u64 v[254:255], v[252:253], 0, s[26:27]
	global_load_lds_dwordx4 v[254:255], off
	s_add_u32 m0, m0, 0x2000
	v_mfma_f32_16x16x32_bf16 v[104:107], v[154:157], v[186:189], v[104:107]
	v_mfma_f32_16x16x32_bf16 v[88:91], v[158:161], v[186:189], v[88:91]
	v_mfma_f32_16x16x32_bf16 v[72:75], v[162:165], v[186:189], v[72:75]
	v_lshl_add_u64 v[254:255], v[252:253], 0, s[30:31]
	global_load_lds_dwordx4 v[254:255], off
	s_add_u32 m0, m0, 0x2000
	s_waitcnt lgkmcnt(5)
	v_mfma_f32_16x16x32_bf16 v[116:119], v[150:153], v[190:193], v[116:119]
	v_mfma_f32_16x16x32_bf16 v[100:103], v[154:157], v[190:193], v[100:103]
	v_mfma_f32_16x16x32_bf16 v[84:87], v[158:161], v[190:193], v[84:87]
	v_lshl_add_u64 v[254:255], v[252:253], 0, s[36:37]
	global_load_lds_dwordx4 v[254:255], off
	v_mfma_f32_16x16x32_bf16 v[68:71], v[162:165], v[190:193], v[68:71]
	s_waitcnt lgkmcnt(1)
	v_mfma_f32_16x16x32_bf16 v[112:115], v[150:153], v[194:197], v[112:115]
	ds_read_b128 v[150:153], v198 offset:1024
	v_mfma_f32_16x16x32_bf16 v[96:99], v[154:157], v[194:197], v[96:99]
	ds_read_b128 v[154:157], v199 offset:1024
	v_mfma_f32_16x16x32_bf16 v[80:83], v[158:161], v[194:197], v[80:83]
	ds_read_b128 v[158:161], v200 offset:1024
	v_mfma_f32_16x16x32_bf16 v[64:67], v[162:165], v[194:197], v[64:67]
	ds_read_b128 v[162:165], v201 offset:1024
	v_mfma_f32_16x16x32_bf16 v[60:63], v[166:169], v[178:181], v[60:63]
	v_mfma_f32_16x16x32_bf16 v[44:47], v[170:173], v[178:181], v[44:47]
	v_mfma_f32_16x16x32_bf16 v[28:31], v[174:177], v[178:181], v[28:31]
	s_waitcnt lgkmcnt(4)
	v_mfma_f32_16x16x32_bf16 v[12:15], v[182:185], v[178:181], v[12:15]
	ds_read_b128 v[178:181], v149 offset:33792
	v_mfma_f32_16x16x32_bf16 v[56:59], v[166:169], v[186:189], v[56:59]
	v_mfma_f32_16x16x32_bf16 v[40:43], v[170:173], v[186:189], v[40:43]
	v_mfma_f32_16x16x32_bf16 v[24:27], v[174:177], v[186:189], v[24:27]
	v_mfma_f32_16x16x32_bf16 v[8:11], v[182:185], v[186:189], v[8:11]
	ds_read_b128 v[186:189], v149 offset:35840
	v_mfma_f32_16x16x32_bf16 v[52:55], v[166:169], v[190:193], v[52:55]
	v_mfma_f32_16x16x32_bf16 v[36:39], v[170:173], v[190:193], v[36:39]
	v_mfma_f32_16x16x32_bf16 v[20:23], v[174:177], v[190:193], v[20:23]
	v_mfma_f32_16x16x32_bf16 v[4:7], v[182:185], v[190:193], v[4:7]
	ds_read_b128 v[190:193], v149 offset:37888
	v_mfma_f32_16x16x32_bf16 v[48:51], v[166:169], v[194:197], v[48:51]
	ds_read_b128 v[166:169], v202 offset:1024
	v_mfma_f32_16x16x32_bf16 v[32:35], v[170:173], v[194:197], v[32:35]
	ds_read_b128 v[170:173], v203 offset:1024
	v_mfma_f32_16x16x32_bf16 v[16:19], v[174:177], v[194:197], v[16:19]
	ds_read_b128 v[174:177], v206 offset:1024
	v_mfma_f32_16x16x32_bf16 v[0:3], v[182:185], v[194:197], v[0:3]
	ds_read_b128 v[194:197], v149 offset:39936
	ds_read_b128 v[182:185], v207 offset:1024
	s_waitcnt lgkmcnt(7)
	v_mfma_f32_16x16x32_bf16 v[124:127], v[150:153], v[178:181], v[124:127]
	v_mfma_f32_16x16x32_bf16 v[108:111], v[154:157], v[178:181], v[108:111]
	v_mfma_f32_16x16x32_bf16 v[92:95], v[158:161], v[178:181], v[92:95]
	v_mfma_f32_16x16x32_bf16 v[76:79], v[162:165], v[178:181], v[76:79]
	s_waitcnt lgkmcnt(6)
	v_mfma_f32_16x16x32_bf16 v[120:123], v[150:153], v[186:189], v[120:123]
	v_mfma_f32_16x16x32_bf16 v[104:107], v[154:157], v[186:189], v[104:107]
	v_mfma_f32_16x16x32_bf16 v[88:91], v[158:161], v[186:189], v[88:91]
	v_mfma_f32_16x16x32_bf16 v[72:75], v[162:165], v[186:189], v[72:75]
	s_waitcnt lgkmcnt(5)
	v_mfma_f32_16x16x32_bf16 v[116:119], v[150:153], v[190:193], v[116:119]
	v_mfma_f32_16x16x32_bf16 v[100:103], v[154:157], v[190:193], v[100:103]
	v_mfma_f32_16x16x32_bf16 v[84:87], v[158:161], v[190:193], v[84:87]
	v_mfma_f32_16x16x32_bf16 v[68:71], v[162:165], v[190:193], v[68:71]
	s_waitcnt lgkmcnt(1)
	v_mfma_f32_16x16x32_bf16 v[112:115], v[150:153], v[194:197], v[112:115]
	v_mfma_f32_16x16x32_bf16 v[96:99], v[154:157], v[194:197], v[96:99]
	v_mfma_f32_16x16x32_bf16 v[80:83], v[158:161], v[194:197], v[80:83]
	v_mfma_f32_16x16x32_bf16 v[64:67], v[162:165], v[194:197], v[64:67]
	s_add_u32 s0, s0, 0x80
	s_addc_u32 s1, s1, 0
	s_add_i32 s44, s44, 0x10000
	s_cmpk_lg_i32 s0, 0x1580
	s_waitcnt vmcnt(0) lgkmcnt(0)
	s_barrier
; #define WAIT_V(n) asm volatile("s_waitcnt vmcnt(%0)" ::"n"(n) : "memory")
; template <bool PRO>
; __device__ __forceinline__ void gemm_mainloop(const u16* __restrict__ Ab, const u16* __restrict__ Bb, int K,
;                                               f32x4 (&acc)[8][4]) {
;     ...
;   const int nt = K / BK;
;   if (PRO) GLDS_STAGE(0, 0);
;   WAIT_V(0);
;   __syncthreads();
;   for (int t = 0; t < nt; ++t) {
;     int cur = t & 1;
;     if (t + 1 < nt) GLDS_STAGE(cur ^ 1, t + 1);
;     __builtin_amdgcn_sched_barrier(0);
;     KSTEP(cur, 0);
;     KSTEP(cur, 1);
;     WAIT_V(0);
;     __syncthreads();
;   }
	s_cbranch_scc0 .Lpipe_exit_1756
	s_and_b32 s45, s44, 0x10000
	v_or_b32_e32 v247, s45, v139
	v_or_b32_e32 v248, s45, v140
	v_add_u32_e32 v198, v247, v147
	v_add_u32_e32 v199, v248, v145
	v_mfma_f32_16x16x32_bf16 v[60:63], v[166:169], v[178:181], v[60:63]
	v_add_u32_e32 v200, v248, v148
	v_add_u32_e32 v201, v248, v146
	v_add_u32_e32 v202, v248, v144
	v_add_u32_e32 v203, v248, v143
	v_mfma_f32_16x16x32_bf16 v[44:47], v[170:173], v[178:181], v[44:47]
	v_add_u32_e32 v206, v248, v142
	v_add_u32_e32 v207, v248, v141
	v_add_u32_e32 v249, v247, v137
	v_or_b32_e32 v149, s45, v136
	v_mfma_f32_16x16x32_bf16 v[28:31], v[174:177], v[178:181], v[28:31]
	ds_read_b128 v[150:153], v198
	ds_read_b128 v[154:157], v199
	v_mfma_f32_16x16x32_bf16 v[12:15], v[182:185], v[178:181], v[12:15]
	ds_read_b128 v[158:161], v200
	ds_read_b128 v[162:165], v201
	v_mfma_f32_16x16x32_bf16 v[56:59], v[166:169], v[186:189], v[56:59]
	ds_read_b128 v[178:181], v249 offset:32768
	s_xor_b32 s64, s45, 0x10000
	v_add_u32_e32 v250, s64, v138
	v_mfma_f32_16x16x32_bf16 v[40:43], v[170:173], v[186:189], v[40:43]
	v_lshl_add_u64 v[252:253], v[130:131], 0, s[0:1]
	v_readfirstlane_b32 s64, v250
	s_mov_b32 m0, s64
	v_mfma_f32_16x16x32_bf16 v[24:27], v[174:177], v[186:189], v[24:27]
	v_lshl_add_u64 v[254:255], v[252:253], 0, s[20:21]
	global_load_lds_dwordx4 v[254:255], off
	s_add_u32 m0, m0, 0x2000
	v_mfma_f32_16x16x32_bf16 v[8:11], v[182:185], v[186:189], v[8:11]
	ds_read_b128 v[186:189], v249 offset:34816
	v_mfma_f32_16x16x32_bf16 v[52:55], v[166:169], v[190:193], v[52:55]
	v_lshl_add_u64 v[254:255], v[252:253], 0, s[24:25]
	global_load_lds_dwordx4 v[254:255], off
	s_add_u32 m0, m0, 0x2000
	v_mfma_f32_16x16x32_bf16 v[36:39], v[170:173], v[190:193], v[36:39]
	v_mfma_f32_16x16x32_bf16 v[20:23], v[174:177], v[190:193], v[20:23]
	v_lshl_add_u64 v[254:255], v[252:253], 0, s[28:29]
	global_load_lds_dwordx4 v[254:255], off
	s_add_u32 m0, m0, 0x2000
	v_mfma_f32_16x16x32_bf16 v[4:7], v[182:185], v[190:193], v[4:7]
	ds_read_b128 v[190:193], v249 offset:36864
	v_mfma_f32_16x16x32_bf16 v[48:51], v[166:169], v[194:197], v[48:51]
	ds_read_b128 v[166:169], v202
	v_lshl_add_u64 v[254:255], v[252:253], 0, s[34:35]
	global_load_lds_dwordx4 v[254:255], off
	s_add_u32 m0, m0, 0x2000
	v_mfma_f32_16x16x32_bf16 v[32:35], v[170:173], v[194:197], v[32:35]
	ds_read_b128 v[170:173], v203
	v_mfma_f32_16x16x32_bf16 v[16:19], v[174:177], v[194:197], v[16:19]
	ds_read_b128 v[174:177], v206
	v_mfma_f32_16x16x32_bf16 v[0:3], v[182:185], v[194:197], v[0:3]
	ds_read_b128 v[194:197], v249 offset:38912
	ds_read_b128 v[182:185], v207
	s_branch .LBB0_1756

; #define WAIT_V(n) asm volatile("s_waitcnt vmcnt(%0)" ::"n"(n) : "memory")
; template <bool PRO>
; __device__ __forceinline__ void gemm_mainloop(const u16* __restrict__ Ab, const u16* __restrict__ Bb, int K,
;                                               f32x4 (&acc)[8][4]) {
;     ...
;   const int nt = K / BK;
;   if (PRO) GLDS_STAGE(0, 0);
;   WAIT_V(0);
;   __syncthreads();
;   for (int t = 0; t < nt; ++t) {
;     int cur = t & 1;
;     if (t + 1 < nt) GLDS_STAGE(cur ^ 1, t + 1);
;     __builtin_amdgcn_sched_barrier(0);
;     KSTEP(cur, 0);
;     KSTEP(cur, 1);
;     WAIT_V(0);
;     __syncthreads();
;   }
.LBB0_1858:
	s_waitcnt lgkmcnt(7)
	v_mfma_f32_16x16x32_bf16 v[124:127], v[146:149], v[174:177], v[124:127]
	v_mfma_f32_16x16x32_bf16 v[108:111], v[150:153], v[174:177], v[108:111]
	v_lshl_add_u64 v[252:253], v[132:133], 0, s[0:1]
	s_mov_b64 s[8:9], 0x35b50080
	v_lshl_add_u64 v[254:255], v[252:253], 0, s[8:9]
	global_load_lds_dwordx4 v[254:255], off
	s_add_u32 m0, m0, 0x2000
	v_mfma_f32_16x16x32_bf16 v[92:95], v[154:157], v[174:177], v[92:95]
	v_mfma_f32_16x16x32_bf16 v[76:79], v[158:161], v[174:177], v[76:79]
	s_waitcnt lgkmcnt(6)
	v_mfma_f32_16x16x32_bf16 v[120:123], v[146:149], v[182:185], v[120:123]
	s_mov_b64 s[8:9], 0x35b70080
	v_lshl_add_u64 v[254:255], v[252:253], 0, s[8:9]
	global_load_lds_dwordx4 v[254:255], off
	s_add_u32 m0, m0, 0x2000
	v_mfma_f32_16x16x32_bf16 v[104:107], v[150:153], v[182:185], v[104:107]
	v_mfma_f32_16x16x32_bf16 v[88:91], v[154:157], v[182:185], v[88:91]
	v_mfma_f32_16x16x32_bf16 v[72:75], v[158:161], v[182:185], v[72:75]
	v_lshl_add_u64 v[254:255], v[252:253], 0, s[66:67]
	global_load_lds_dwordx4 v[254:255], off
	s_add_u32 m0, m0, 0x2000
	s_waitcnt lgkmcnt(5)
	v_mfma_f32_16x16x32_bf16 v[116:119], v[146:149], v[186:189], v[116:119]
	v_mfma_f32_16x16x32_bf16 v[100:103], v[150:153], v[186:189], v[100:103]
	v_mfma_f32_16x16x32_bf16 v[84:87], v[154:157], v[186:189], v[84:87]
	v_lshl_add_u64 v[254:255], v[252:253], 0, s[70:71]
	global_load_lds_dwordx4 v[254:255], off
	v_mfma_f32_16x16x32_bf16 v[68:71], v[158:161], v[186:189], v[68:71]
	s_waitcnt lgkmcnt(1)
	v_mfma_f32_16x16x32_bf16 v[112:115], v[146:149], v[190:193], v[112:115]
	ds_read_b128 v[146:149], v194 offset:1024
	v_mfma_f32_16x16x32_bf16 v[96:99], v[150:153], v[190:193], v[96:99]
	ds_read_b128 v[150:153], v195 offset:1024
	v_mfma_f32_16x16x32_bf16 v[80:83], v[154:157], v[190:193], v[80:83]
	ds_read_b128 v[154:157], v196 offset:1024
	v_mfma_f32_16x16x32_bf16 v[64:67], v[158:161], v[190:193], v[64:67]
	ds_read_b128 v[158:161], v197 offset:1024
	v_mfma_f32_16x16x32_bf16 v[60:63], v[162:165], v[174:177], v[60:63]
	v_mfma_f32_16x16x32_bf16 v[44:47], v[166:169], v[174:177], v[44:47]
	v_mfma_f32_16x16x32_bf16 v[28:31], v[170:173], v[174:177], v[28:31]
	s_waitcnt lgkmcnt(4)
	v_mfma_f32_16x16x32_bf16 v[12:15], v[178:181], v[174:177], v[12:15]
	ds_read_b128 v[174:177], v250 offset:33792
	v_mfma_f32_16x16x32_bf16 v[56:59], v[162:165], v[182:185], v[56:59]
	v_mfma_f32_16x16x32_bf16 v[40:43], v[166:169], v[182:185], v[40:43]
	v_mfma_f32_16x16x32_bf16 v[24:27], v[170:173], v[182:185], v[24:27]
	v_mfma_f32_16x16x32_bf16 v[8:11], v[178:181], v[182:185], v[8:11]
	ds_read_b128 v[182:185], v250 offset:35840
	v_mfma_f32_16x16x32_bf16 v[52:55], v[162:165], v[186:189], v[52:55]
	v_mfma_f32_16x16x32_bf16 v[36:39], v[166:169], v[186:189], v[36:39]
	v_mfma_f32_16x16x32_bf16 v[20:23], v[170:173], v[186:189], v[20:23]
	v_mfma_f32_16x16x32_bf16 v[4:7], v[178:181], v[186:189], v[4:7]
	ds_read_b128 v[186:189], v250 offset:37888
	v_mfma_f32_16x16x32_bf16 v[48:51], v[162:165], v[190:193], v[48:51]
	ds_read_b128 v[162:165], v198 offset:1024
	v_mfma_f32_16x16x32_bf16 v[32:35], v[166:169], v[190:193], v[32:35]
	ds_read_b128 v[166:169], v199 offset:1024
	v_mfma_f32_16x16x32_bf16 v[16:19], v[170:173], v[190:193], v[16:19]
	ds_read_b128 v[170:173], v200 offset:1024
	v_mfma_f32_16x16x32_bf16 v[0:3], v[178:181], v[190:193], v[0:3]
	ds_read_b128 v[190:193], v250 offset:39936
	ds_read_b128 v[178:181], v201 offset:1024
	s_waitcnt lgkmcnt(7)
	v_mfma_f32_16x16x32_bf16 v[124:127], v[146:149], v[174:177], v[124:127]
	v_mfma_f32_16x16x32_bf16 v[108:111], v[150:153], v[174:177], v[108:111]
	v_mfma_f32_16x16x32_bf16 v[92:95], v[154:157], v[174:177], v[92:95]
	v_mfma_f32_16x16x32_bf16 v[76:79], v[158:161], v[174:177], v[76:79]
	s_waitcnt lgkmcnt(6)
	v_mfma_f32_16x16x32_bf16 v[120:123], v[146:149], v[182:185], v[120:123]
	v_mfma_f32_16x16x32_bf16 v[104:107], v[150:153], v[182:185], v[104:107]
	v_mfma_f32_16x16x32_bf16 v[88:91], v[154:157], v[182:185], v[88:91]
	v_mfma_f32_16x16x32_bf16 v[72:75], v[158:161], v[182:185], v[72:75]
	s_waitcnt lgkmcnt(5)
	v_mfma_f32_16x16x32_bf16 v[116:119], v[146:149], v[186:189], v[116:119]
	v_mfma_f32_16x16x32_bf16 v[100:103], v[150:153], v[186:189], v[100:103]
	v_mfma_f32_16x16x32_bf16 v[84:87], v[154:157], v[186:189], v[84:87]
	v_mfma_f32_16x16x32_bf16 v[68:71], v[158:161], v[186:189], v[68:71]
	s_waitcnt lgkmcnt(1)
	v_mfma_f32_16x16x32_bf16 v[112:115], v[146:149], v[190:193], v[112:115]
	v_mfma_f32_16x16x32_bf16 v[96:99], v[150:153], v[190:193], v[96:99]
	v_mfma_f32_16x16x32_bf16 v[80:83], v[154:157], v[190:193], v[80:83]
	v_mfma_f32_16x16x32_bf16 v[64:67], v[158:161], v[190:193], v[64:67]
	s_add_i32 s2, s2, 0x10000
	s_add_u32 s0, s0, 0x80
	s_addc_u32 s1, s1, 0
	s_cmpk_lg_i32 s0, 0x780
	s_waitcnt vmcnt(0) lgkmcnt(0)
	s_barrier
; #define WAIT_V(n) asm volatile("s_waitcnt vmcnt(%0)" ::"n"(n) : "memory")
; template <bool PRO>
; __device__ __forceinline__ void gemm_mainloop(const u16* __restrict__ Ab, const u16* __restrict__ Bb, int K,
;                                               f32x4 (&acc)[8][4]) {
;     ...
;   const int nt = K / BK;
;   if (PRO) GLDS_STAGE(0, 0);
;   WAIT_V(0);
;   __syncthreads();
;   for (int t = 0; t < nt; ++t) {
;     int cur = t & 1;
;     if (t + 1 < nt) GLDS_STAGE(cur ^ 1, t + 1);
;     __builtin_amdgcn_sched_barrier(0);
;     KSTEP(cur, 0);
;     KSTEP(cur, 1);
;     WAIT_V(0);
;     __syncthreads();
;   }
	s_cbranch_scc0 .Lpipe_exit_1858
	s_and_b32 s3, s2, 0x10000
	v_or_b32_e32 v247, s3, v136
	v_or_b32_e32 v248, s3, v137
	v_add_u32_e32 v194, v247, v144
	v_add_u32_e32 v195, v248, v142
	v_mfma_f32_16x16x32_bf16 v[60:63], v[162:165], v[174:177], v[60:63]
	v_add_u32_e32 v196, v248, v145
	v_add_u32_e32 v197, v248, v143
	v_add_u32_e32 v198, v248, v141
	v_add_u32_e32 v199, v248, v140
	v_mfma_f32_16x16x32_bf16 v[44:47], v[166:169], v[174:177], v[44:47]
	v_add_u32_e32 v200, v248, v139
	v_add_u32_e32 v201, v248, v138
	v_add_u32_e32 v249, v247, v134
	v_or_b32_e32 v250, s3, v128
	v_mfma_f32_16x16x32_bf16 v[28:31], v[170:173], v[174:177], v[28:31]
	ds_read_b128 v[146:149], v194
	ds_read_b128 v[150:153], v195
	v_mfma_f32_16x16x32_bf16 v[12:15], v[178:181], v[174:177], v[12:15]
	ds_read_b128 v[154:157], v196
	ds_read_b128 v[158:161], v197
	v_mfma_f32_16x16x32_bf16 v[56:59], v[162:165], v[182:185], v[56:59]
	ds_read_b128 v[174:177], v249 offset:32768
	s_xor_b32 s8, s3, 0x10000
	v_add_u32_e32 v251, s8, v135
	v_mfma_f32_16x16x32_bf16 v[40:43], v[166:169], v[182:185], v[40:43]
	v_lshl_add_u64 v[252:253], v[130:131], 0, s[0:1]
	v_readfirstlane_b32 s8, v251
	s_mov_b32 m0, s8
	v_mfma_f32_16x16x32_bf16 v[24:27], v[170:173], v[182:185], v[24:27]
	s_mov_b64 s[8:9], 0x387b3380
	v_lshl_add_u64 v[254:255], v[252:253], 0, s[8:9]
	global_load_lds_dwordx4 v[254:255], off
	s_add_u32 m0, m0, 0x2000
	v_mfma_f32_16x16x32_bf16 v[8:11], v[178:181], v[182:185], v[8:11]
	ds_read_b128 v[182:185], v249 offset:34816
	v_mfma_f32_16x16x32_bf16 v[52:55], v[162:165], v[186:189], v[52:55]
	s_mov_b64 s[8:9], 0x387d3380
	v_lshl_add_u64 v[254:255], v[252:253], 0, s[8:9]
	global_load_lds_dwordx4 v[254:255], off
	s_add_u32 m0, m0, 0x2000
	v_mfma_f32_16x16x32_bf16 v[36:39], v[166:169], v[186:189], v[36:39]
	v_mfma_f32_16x16x32_bf16 v[20:23], v[170:173], v[186:189], v[20:23]
	s_mov_b64 s[8:9], 0x387f3380
	v_lshl_add_u64 v[254:255], v[252:253], 0, s[8:9]
	global_load_lds_dwordx4 v[254:255], off
	s_add_u32 m0, m0, 0x2000
	v_mfma_f32_16x16x32_bf16 v[4:7], v[178:181], v[186:189], v[4:7]
	ds_read_b128 v[186:189], v249 offset:36864
	v_mfma_f32_16x16x32_bf16 v[48:51], v[162:165], v[190:193], v[48:51]
	ds_read_b128 v[162:165], v198
	v_lshl_add_u64 v[254:255], v[252:253], 0, s[68:69]
	global_load_lds_dwordx4 v[254:255], off
	s_add_u32 m0, m0, 0x2000
	v_mfma_f32_16x16x32_bf16 v[32:35], v[166:169], v[190:193], v[32:35]
	ds_read_b128 v[166:169], v199
	v_mfma_f32_16x16x32_bf16 v[16:19], v[170:173], v[190:193], v[16:19]
	ds_read_b128 v[170:173], v200
	v_mfma_f32_16x16x32_bf16 v[0:3], v[178:181], v[190:193], v[0:3]
	ds_read_b128 v[190:193], v249 offset:38912
	ds_read_b128 v[178:181], v201
	s_branch .LBB0_1858

; #define WAIT_V(n) asm volatile("s_waitcnt vmcnt(%0)" ::"n"(n) : "memory")
; template <bool PRO>
; __device__ __forceinline__ void gemm_mainloop(const u16* __restrict__ Ab, const u16* __restrict__ Bb, int K,
;                                               f32x4 (&acc)[8][4]) {
;     ...
;   const int nt = K / BK;
;   if (PRO) GLDS_STAGE(0, 0);
;   WAIT_V(0);
;   __syncthreads();
;   for (int t = 0; t < nt; ++t) {
;     int cur = t & 1;
;     if (t + 1 < nt) GLDS_STAGE(cur ^ 1, t + 1);
;     __builtin_amdgcn_sched_barrier(0);
;     KSTEP(cur, 0);
;     KSTEP(cur, 1);
;     WAIT_V(0);
;     __syncthreads();
;   }
.LBB0_3011:
	s_waitcnt lgkmcnt(7)
	v_mfma_f32_16x16x32_bf16 v[124:127], v[148:151], v[176:179], v[124:127]
	v_mfma_f32_16x16x32_bf16 v[108:111], v[152:155], v[176:179], v[108:111]
	v_lshl_add_u64 v[252:253], v[130:131], 0, s[0:1]
	v_lshl_add_u64 v[254:255], v[252:253], 0, s[30:31]
	global_load_lds_dwordx4 v[254:255], off
	s_add_u32 m0, m0, 0x2000
	v_mfma_f32_16x16x32_bf16 v[92:95], v[156:159], v[176:179], v[92:95]
	v_mfma_f32_16x16x32_bf16 v[76:79], v[160:163], v[176:179], v[76:79]
	s_waitcnt lgkmcnt(6)
	v_mfma_f32_16x16x32_bf16 v[120:123], v[148:151], v[184:187], v[120:123]
	v_lshl_add_u64 v[254:255], v[252:253], 0, s[36:37]
	global_load_lds_dwordx4 v[254:255], off
	s_add_u32 m0, m0, 0x2000
	v_mfma_f32_16x16x32_bf16 v[104:107], v[152:155], v[184:187], v[104:107]
	v_mfma_f32_16x16x32_bf16 v[88:91], v[156:159], v[184:187], v[88:91]
	v_mfma_f32_16x16x32_bf16 v[72:75], v[160:163], v[184:187], v[72:75]
	v_lshl_add_u64 v[254:255], v[252:253], 0, s[40:41]
	global_load_lds_dwordx4 v[254:255], off
	s_add_u32 m0, m0, 0x2000
	s_waitcnt lgkmcnt(5)
	v_mfma_f32_16x16x32_bf16 v[116:119], v[148:151], v[188:191], v[116:119]
	v_mfma_f32_16x16x32_bf16 v[100:103], v[152:155], v[188:191], v[100:103]
	v_mfma_f32_16x16x32_bf16 v[84:87], v[156:159], v[188:191], v[84:87]
	v_lshl_add_u64 v[254:255], v[252:253], 0, s[44:45]
	global_load_lds_dwordx4 v[254:255], off
	v_mfma_f32_16x16x32_bf16 v[68:71], v[160:163], v[188:191], v[68:71]
	s_waitcnt lgkmcnt(1)
	v_mfma_f32_16x16x32_bf16 v[112:115], v[148:151], v[192:195], v[112:115]
	ds_read_b128 v[148:151], v196 offset:1024
	v_mfma_f32_16x16x32_bf16 v[96:99], v[152:155], v[192:195], v[96:99]
	ds_read_b128 v[152:155], v197 offset:1024
	v_mfma_f32_16x16x32_bf16 v[80:83], v[156:159], v[192:195], v[80:83]
	ds_read_b128 v[156:159], v198 offset:1024
	v_mfma_f32_16x16x32_bf16 v[64:67], v[160:163], v[192:195], v[64:67]
	ds_read_b128 v[160:163], v199 offset:1024
	v_mfma_f32_16x16x32_bf16 v[60:63], v[164:167], v[176:179], v[60:63]
	v_mfma_f32_16x16x32_bf16 v[44:47], v[168:171], v[176:179], v[44:47]
	v_mfma_f32_16x16x32_bf16 v[28:31], v[172:175], v[176:179], v[28:31]
	s_waitcnt lgkmcnt(4)
	v_mfma_f32_16x16x32_bf16 v[12:15], v[180:183], v[176:179], v[12:15]
	ds_read_b128 v[176:179], v147 offset:33792
	v_mfma_f32_16x16x32_bf16 v[56:59], v[164:167], v[184:187], v[56:59]
	v_mfma_f32_16x16x32_bf16 v[40:43], v[168:171], v[184:187], v[40:43]
	v_mfma_f32_16x16x32_bf16 v[24:27], v[172:175], v[184:187], v[24:27]
	v_mfma_f32_16x16x32_bf16 v[8:11], v[180:183], v[184:187], v[8:11]
	ds_read_b128 v[184:187], v147 offset:35840
	v_mfma_f32_16x16x32_bf16 v[52:55], v[164:167], v[188:191], v[52:55]
	v_mfma_f32_16x16x32_bf16 v[36:39], v[168:171], v[188:191], v[36:39]
	v_mfma_f32_16x16x32_bf16 v[20:23], v[172:175], v[188:191], v[20:23]
	v_mfma_f32_16x16x32_bf16 v[4:7], v[180:183], v[188:191], v[4:7]
	ds_read_b128 v[188:191], v147 offset:37888
	v_mfma_f32_16x16x32_bf16 v[48:51], v[164:167], v[192:195], v[48:51]
	ds_read_b128 v[164:167], v200 offset:1024
	v_mfma_f32_16x16x32_bf16 v[32:35], v[168:171], v[192:195], v[32:35]
	ds_read_b128 v[168:171], v201 offset:1024
	v_mfma_f32_16x16x32_bf16 v[16:19], v[172:175], v[192:195], v[16:19]
	ds_read_b128 v[172:175], v202 offset:1024
	v_mfma_f32_16x16x32_bf16 v[0:3], v[180:183], v[192:195], v[0:3]
	ds_read_b128 v[192:195], v147 offset:39936
	ds_read_b128 v[180:183], v203 offset:1024
	s_waitcnt lgkmcnt(7)
	v_mfma_f32_16x16x32_bf16 v[124:127], v[148:151], v[176:179], v[124:127]
	v_mfma_f32_16x16x32_bf16 v[108:111], v[152:155], v[176:179], v[108:111]
	v_mfma_f32_16x16x32_bf16 v[92:95], v[156:159], v[176:179], v[92:95]
	v_mfma_f32_16x16x32_bf16 v[76:79], v[160:163], v[176:179], v[76:79]
	s_waitcnt lgkmcnt(6)
	v_mfma_f32_16x16x32_bf16 v[120:123], v[148:151], v[184:187], v[120:123]
	v_mfma_f32_16x16x32_bf16 v[104:107], v[152:155], v[184:187], v[104:107]
	v_mfma_f32_16x16x32_bf16 v[88:91], v[156:159], v[184:187], v[88:91]
	v_mfma_f32_16x16x32_bf16 v[72:75], v[160:163], v[184:187], v[72:75]
	s_waitcnt lgkmcnt(5)
	v_mfma_f32_16x16x32_bf16 v[116:119], v[148:151], v[188:191], v[116:119]
	v_mfma_f32_16x16x32_bf16 v[100:103], v[152:155], v[188:191], v[100:103]
	v_mfma_f32_16x16x32_bf16 v[84:87], v[156:159], v[188:191], v[84:87]
	v_mfma_f32_16x16x32_bf16 v[68:71], v[160:163], v[188:191], v[68:71]
	s_waitcnt lgkmcnt(1)
	v_mfma_f32_16x16x32_bf16 v[112:115], v[148:151], v[192:195], v[112:115]
	v_mfma_f32_16x16x32_bf16 v[96:99], v[152:155], v[192:195], v[96:99]
	v_mfma_f32_16x16x32_bf16 v[80:83], v[156:159], v[192:195], v[80:83]
	v_mfma_f32_16x16x32_bf16 v[64:67], v[160:163], v[192:195], v[64:67]
	s_add_i32 s19, s19, 0x10000
	s_add_u32 s0, s0, 0x80
	s_addc_u32 s1, s1, 0
	s_cmpk_lg_i32 s0, 0x780
	s_waitcnt vmcnt(0) lgkmcnt(0)
	s_barrier
; #define WAIT_V(n) asm volatile("s_waitcnt vmcnt(%0)" ::"n"(n) : "memory")
; template <bool PRO>
; __device__ __forceinline__ void gemm_mainloop(const u16* __restrict__ Ab, const u16* __restrict__ Bb, int K,
;                                               f32x4 (&acc)[8][4]) {
;     ...
;   const int nt = K / BK;
;   if (PRO) GLDS_STAGE(0, 0);
;   WAIT_V(0);
;   __syncthreads();
;   for (int t = 0; t < nt; ++t) {
;     int cur = t & 1;
;     if (t + 1 < nt) GLDS_STAGE(cur ^ 1, t + 1);
;     __builtin_amdgcn_sched_barrier(0);
;     KSTEP(cur, 0);
;     KSTEP(cur, 1);
;     WAIT_V(0);
;     __syncthreads();
;   }
	s_cbranch_scc0 .Lpipe_exit_3011
	s_and_b32 s21, s19, 0x10000
	v_or_b32_e32 v247, s21, v137
	v_or_b32_e32 v248, s21, v138
	v_add_u32_e32 v196, v247, v145
	v_add_u32_e32 v197, v248, v143
	v_mfma_f32_16x16x32_bf16 v[60:63], v[164:167], v[176:179], v[60:63]
	v_add_u32_e32 v198, v248, v146
	v_add_u32_e32 v199, v248, v144
	v_add_u32_e32 v200, v248, v142
	v_add_u32_e32 v201, v248, v141
	v_mfma_f32_16x16x32_bf16 v[44:47], v[168:171], v[176:179], v[44:47]
	v_add_u32_e32 v202, v248, v140
	v_add_u32_e32 v203, v248, v139
	v_add_u32_e32 v249, v247, v135
	v_or_b32_e32 v147, s21, v134
	v_mfma_f32_16x16x32_bf16 v[28:31], v[172:175], v[176:179], v[28:31]
	ds_read_b128 v[148:151], v196
	ds_read_b128 v[152:155], v197
	v_mfma_f32_16x16x32_bf16 v[12:15], v[180:183], v[176:179], v[12:15]
	ds_read_b128 v[156:159], v198
	ds_read_b128 v[160:163], v199
	v_mfma_f32_16x16x32_bf16 v[56:59], v[164:167], v[184:187], v[56:59]
	ds_read_b128 v[176:179], v249 offset:32768
	s_xor_b32 s46, s21, 0x10000
	v_add_u32_e32 v250, s46, v136
	v_mfma_f32_16x16x32_bf16 v[40:43], v[168:171], v[184:187], v[40:43]
	v_lshl_add_u64 v[252:253], v[128:129], 0, s[0:1]
	v_readfirstlane_b32 s46, v250
	s_mov_b32 m0, s46
	v_mfma_f32_16x16x32_bf16 v[24:27], v[172:175], v[184:187], v[24:27]
	v_lshl_add_u64 v[254:255], v[252:253], 0, s[28:29]
	global_load_lds_dwordx4 v[254:255], off
	s_add_u32 m0, m0, 0x2000
	v_mfma_f32_16x16x32_bf16 v[8:11], v[180:183], v[184:187], v[8:11]
	ds_read_b128 v[184:187], v249 offset:34816
	v_mfma_f32_16x16x32_bf16 v[52:55], v[164:167], v[188:191], v[52:55]
	v_lshl_add_u64 v[254:255], v[252:253], 0, s[34:35]
	global_load_lds_dwordx4 v[254:255], off
	s_add_u32 m0, m0, 0x2000
	v_mfma_f32_16x16x32_bf16 v[36:39], v[168:171], v[188:191], v[36:39]
	v_mfma_f32_16x16x32_bf16 v[20:23], v[172:175], v[188:191], v[20:23]
	v_lshl_add_u64 v[254:255], v[252:253], 0, s[38:39]
	global_load_lds_dwordx4 v[254:255], off
	s_add_u32 m0, m0, 0x2000
	v_mfma_f32_16x16x32_bf16 v[4:7], v[180:183], v[188:191], v[4:7]
	ds_read_b128 v[188:191], v249 offset:36864
	v_mfma_f32_16x16x32_bf16 v[48:51], v[164:167], v[192:195], v[48:51]
	ds_read_b128 v[164:167], v200
	v_lshl_add_u64 v[254:255], v[252:253], 0, s[42:43]
	global_load_lds_dwordx4 v[254:255], off
	s_add_u32 m0, m0, 0x2000
	v_mfma_f32_16x16x32_bf16 v[32:35], v[168:171], v[192:195], v[32:35]
	ds_read_b128 v[168:171], v201
	v_mfma_f32_16x16x32_bf16 v[16:19], v[172:175], v[192:195], v[16:19]
	ds_read_b128 v[172:175], v202
	v_mfma_f32_16x16x32_bf16 v[0:3], v[180:183], v[192:195], v[0:3]
	ds_read_b128 v[192:195], v249 offset:38912
	ds_read_b128 v[180:183], v203
	s_branch .LBB0_3011

; #define WAIT_V(n) asm volatile("s_waitcnt vmcnt(%0)" ::"n"(n) : "memory")
; template <bool PRO>
; __device__ __forceinline__ void gemm_mainloop(const u16* __restrict__ Ab, const u16* __restrict__ Bb, int K,
;                                               f32x4 (&acc)[8][4]) {
;     ...
;   const int nt = K / BK;
;   if (PRO) GLDS_STAGE(0, 0);
;   WAIT_V(0);
;   __syncthreads();
;   for (int t = 0; t < nt; ++t) {
;     int cur = t & 1;
;     if (t + 1 < nt) GLDS_STAGE(cur ^ 1, t + 1);
;     __builtin_amdgcn_sched_barrier(0);
;     KSTEP(cur, 0);
;     KSTEP(cur, 1);
;     WAIT_V(0);
;     __syncthreads();
;   }
.LBB0_3023:
	s_waitcnt lgkmcnt(7)
	v_mfma_f32_16x16x32_bf16 v[124:127], v[148:151], v[176:179], v[124:127]
	v_mfma_f32_16x16x32_bf16 v[108:111], v[152:155], v[176:179], v[108:111]
	v_lshl_add_u64 v[252:253], v[130:131], 0, s[0:1]
	v_lshl_add_u64 v[254:255], v[252:253], 0, s[34:35]
	global_load_lds_dwordx4 v[254:255], off
	s_add_u32 m0, m0, 0x2000
	v_mfma_f32_16x16x32_bf16 v[92:95], v[156:159], v[176:179], v[92:95]
	v_mfma_f32_16x16x32_bf16 v[76:79], v[160:163], v[176:179], v[76:79]
	s_waitcnt lgkmcnt(6)
	v_mfma_f32_16x16x32_bf16 v[120:123], v[148:151], v[184:187], v[120:123]
	v_lshl_add_u64 v[254:255], v[252:253], 0, s[38:39]
	global_load_lds_dwordx4 v[254:255], off
	s_add_u32 m0, m0, 0x2000
	v_mfma_f32_16x16x32_bf16 v[104:107], v[152:155], v[184:187], v[104:107]
	v_mfma_f32_16x16x32_bf16 v[88:91], v[156:159], v[184:187], v[88:91]
	v_mfma_f32_16x16x32_bf16 v[72:75], v[160:163], v[184:187], v[72:75]
	v_lshl_add_u64 v[254:255], v[252:253], 0, s[42:43]
	global_load_lds_dwordx4 v[254:255], off
	s_add_u32 m0, m0, 0x2000
	s_waitcnt lgkmcnt(5)
	v_mfma_f32_16x16x32_bf16 v[116:119], v[148:151], v[188:191], v[116:119]
	v_mfma_f32_16x16x32_bf16 v[100:103], v[152:155], v[188:191], v[100:103]
	v_mfma_f32_16x16x32_bf16 v[84:87], v[156:159], v[188:191], v[84:87]
	v_lshl_add_u64 v[254:255], v[252:253], 0, s[46:47]
	global_load_lds_dwordx4 v[254:255], off
	v_mfma_f32_16x16x32_bf16 v[68:71], v[160:163], v[188:191], v[68:71]
	s_waitcnt lgkmcnt(1)
	v_mfma_f32_16x16x32_bf16 v[112:115], v[148:151], v[192:195], v[112:115]
	ds_read_b128 v[148:151], v196 offset:1024
	v_mfma_f32_16x16x32_bf16 v[96:99], v[152:155], v[192:195], v[96:99]
	ds_read_b128 v[152:155], v197 offset:1024
	v_mfma_f32_16x16x32_bf16 v[80:83], v[156:159], v[192:195], v[80:83]
	ds_read_b128 v[156:159], v198 offset:1024
	v_mfma_f32_16x16x32_bf16 v[64:67], v[160:163], v[192:195], v[64:67]
	ds_read_b128 v[160:163], v199 offset:1024
	v_mfma_f32_16x16x32_bf16 v[60:63], v[164:167], v[176:179], v[60:63]
	v_mfma_f32_16x16x32_bf16 v[44:47], v[168:171], v[176:179], v[44:47]
	v_mfma_f32_16x16x32_bf16 v[28:31], v[172:175], v[176:179], v[28:31]
	s_waitcnt lgkmcnt(4)
	v_mfma_f32_16x16x32_bf16 v[12:15], v[180:183], v[176:179], v[12:15]
	ds_read_b128 v[176:179], v147 offset:33792
	v_mfma_f32_16x16x32_bf16 v[56:59], v[164:167], v[184:187], v[56:59]
	v_mfma_f32_16x16x32_bf16 v[40:43], v[168:171], v[184:187], v[40:43]
	v_mfma_f32_16x16x32_bf16 v[24:27], v[172:175], v[184:187], v[24:27]
	v_mfma_f32_16x16x32_bf16 v[8:11], v[180:183], v[184:187], v[8:11]
	ds_read_b128 v[184:187], v147 offset:35840
	v_mfma_f32_16x16x32_bf16 v[52:55], v[164:167], v[188:191], v[52:55]
	v_mfma_f32_16x16x32_bf16 v[36:39], v[168:171], v[188:191], v[36:39]
	v_mfma_f32_16x16x32_bf16 v[20:23], v[172:175], v[188:191], v[20:23]
	v_mfma_f32_16x16x32_bf16 v[4:7], v[180:183], v[188:191], v[4:7]
	ds_read_b128 v[188:191], v147 offset:37888
	v_mfma_f32_16x16x32_bf16 v[48:51], v[164:167], v[192:195], v[48:51]
	ds_read_b128 v[164:167], v200 offset:1024
	v_mfma_f32_16x16x32_bf16 v[32:35], v[168:171], v[192:195], v[32:35]
	ds_read_b128 v[168:171], v201 offset:1024
	v_mfma_f32_16x16x32_bf16 v[16:19], v[172:175], v[192:195], v[16:19]
	ds_read_b128 v[172:175], v202 offset:1024
	v_mfma_f32_16x16x32_bf16 v[0:3], v[180:183], v[192:195], v[0:3]
	ds_read_b128 v[192:195], v147 offset:39936
	ds_read_b128 v[180:183], v203 offset:1024
	s_waitcnt lgkmcnt(7)
	v_mfma_f32_16x16x32_bf16 v[124:127], v[148:151], v[176:179], v[124:127]
	v_mfma_f32_16x16x32_bf16 v[108:111], v[152:155], v[176:179], v[108:111]
	v_mfma_f32_16x16x32_bf16 v[92:95], v[156:159], v[176:179], v[92:95]
	v_mfma_f32_16x16x32_bf16 v[76:79], v[160:163], v[176:179], v[76:79]
	s_waitcnt lgkmcnt(6)
	v_mfma_f32_16x16x32_bf16 v[120:123], v[148:151], v[184:187], v[120:123]
	v_mfma_f32_16x16x32_bf16 v[104:107], v[152:155], v[184:187], v[104:107]
	v_mfma_f32_16x16x32_bf16 v[88:91], v[156:159], v[184:187], v[88:91]
	v_mfma_f32_16x16x32_bf16 v[72:75], v[160:163], v[184:187], v[72:75]
	s_waitcnt lgkmcnt(5)
	v_mfma_f32_16x16x32_bf16 v[116:119], v[148:151], v[188:191], v[116:119]
	v_mfma_f32_16x16x32_bf16 v[100:103], v[152:155], v[188:191], v[100:103]
	v_mfma_f32_16x16x32_bf16 v[84:87], v[156:159], v[188:191], v[84:87]
	v_mfma_f32_16x16x32_bf16 v[68:71], v[160:163], v[188:191], v[68:71]
	s_waitcnt lgkmcnt(1)
	v_mfma_f32_16x16x32_bf16 v[112:115], v[148:151], v[192:195], v[112:115]
	v_mfma_f32_16x16x32_bf16 v[96:99], v[152:155], v[192:195], v[96:99]
	v_mfma_f32_16x16x32_bf16 v[80:83], v[156:159], v[192:195], v[80:83]
	v_mfma_f32_16x16x32_bf16 v[64:67], v[160:163], v[192:195], v[64:67]
	s_add_i32 s21, s21, 0x10000
	s_add_u32 s0, s0, 0x80
	s_addc_u32 s1, s1, 0
	s_cmpk_lg_i32 s0, 0x780
	s_waitcnt vmcnt(0) lgkmcnt(0)
	s_barrier
; #define WAIT_V(n) asm volatile("s_waitcnt vmcnt(%0)" ::"n"(n) : "memory")
; template <bool PRO>
; __device__ __forceinline__ void gemm_mainloop(const u16* __restrict__ Ab, const u16* __restrict__ Bb, int K,
;                                               f32x4 (&acc)[8][4]) {
;     ...
;   const int nt = K / BK;
;   if (PRO) GLDS_STAGE(0, 0);
;   WAIT_V(0);
;   __syncthreads();
;   for (int t = 0; t < nt; ++t) {
;     int cur = t & 1;
;     if (t + 1 < nt) GLDS_STAGE(cur ^ 1, t + 1);
;     __builtin_amdgcn_sched_barrier(0);
;     KSTEP(cur, 0);
;     KSTEP(cur, 1);
;     WAIT_V(0);
;     __syncthreads();
;   }
	s_cbranch_scc0 .Lpipe_exit_3023
	s_and_b32 s23, s21, 0x10000
	v_or_b32_e32 v247, s23, v137
	v_or_b32_e32 v248, s23, v138
	v_add_u32_e32 v196, v247, v145
	v_add_u32_e32 v197, v248, v143
	v_mfma_f32_16x16x32_bf16 v[60:63], v[164:167], v[176:179], v[60:63]
	v_add_u32_e32 v198, v248, v146
	v_add_u32_e32 v199, v248, v144
	v_add_u32_e32 v200, v248, v142
	v_add_u32_e32 v201, v248, v141
	v_mfma_f32_16x16x32_bf16 v[44:47], v[168:171], v[176:179], v[44:47]
	v_add_u32_e32 v202, v248, v140
	v_add_u32_e32 v203, v248, v139
	v_add_u32_e32 v249, v247, v135
	v_or_b32_e32 v147, s23, v134
	v_mfma_f32_16x16x32_bf16 v[28:31], v[172:175], v[176:179], v[28:31]
	ds_read_b128 v[148:151], v196
	ds_read_b128 v[152:155], v197
	v_mfma_f32_16x16x32_bf16 v[12:15], v[180:183], v[176:179], v[12:15]
	ds_read_b128 v[156:159], v198
	ds_read_b128 v[160:163], v199
	v_mfma_f32_16x16x32_bf16 v[56:59], v[164:167], v[184:187], v[56:59]
	ds_read_b128 v[176:179], v249 offset:32768
	s_xor_b32 s50, s23, 0x10000
	v_add_u32_e32 v250, s50, v136
	v_mfma_f32_16x16x32_bf16 v[40:43], v[168:171], v[184:187], v[40:43]
	v_lshl_add_u64 v[252:253], v[128:129], 0, s[0:1]
	v_readfirstlane_b32 s50, v250
	s_mov_b32 m0, s50
	v_mfma_f32_16x16x32_bf16 v[24:27], v[172:175], v[184:187], v[24:27]
	v_lshl_add_u64 v[254:255], v[252:253], 0, s[30:31]
	global_load_lds_dwordx4 v[254:255], off
	s_add_u32 m0, m0, 0x2000
	v_mfma_f32_16x16x32_bf16 v[8:11], v[180:183], v[184:187], v[8:11]
	ds_read_b128 v[184:187], v249 offset:34816
	v_mfma_f32_16x16x32_bf16 v[52:55], v[164:167], v[188:191], v[52:55]
	v_lshl_add_u64 v[254:255], v[252:253], 0, s[36:37]
	global_load_lds_dwordx4 v[254:255], off
	s_add_u32 m0, m0, 0x2000
	v_mfma_f32_16x16x32_bf16 v[36:39], v[168:171], v[188:191], v[36:39]
	v_mfma_f32_16x16x32_bf16 v[20:23], v[172:175], v[188:191], v[20:23]
	v_lshl_add_u64 v[254:255], v[252:253], 0, s[40:41]
	global_load_lds_dwordx4 v[254:255], off
	s_add_u32 m0, m0, 0x2000
	v_mfma_f32_16x16x32_bf16 v[4:7], v[180:183], v[188:191], v[4:7]
	ds_read_b128 v[188:191], v249 offset:36864
	v_mfma_f32_16x16x32_bf16 v[48:51], v[164:167], v[192:195], v[48:51]
	ds_read_b128 v[164:167], v200
	v_lshl_add_u64 v[254:255], v[252:253], 0, s[44:45]
	global_load_lds_dwordx4 v[254:255], off
	s_add_u32 m0, m0, 0x2000
	v_mfma_f32_16x16x32_bf16 v[32:35], v[168:171], v[192:195], v[32:35]
	ds_read_b128 v[168:171], v201
	v_mfma_f32_16x16x32_bf16 v[16:19], v[172:175], v[192:195], v[16:19]
	ds_read_b128 v[172:175], v202
	v_mfma_f32_16x16x32_bf16 v[0:3], v[180:183], v[192:195], v[0:3]
	ds_read_b128 v[192:195], v249 offset:38912
	ds_read_b128 v[180:183], v203
	s_branch .LBB0_3023

; #define WAIT_V(n) asm volatile("s_waitcnt vmcnt(%0)" ::"n"(n) : "memory")
; template <bool PRO>
; __device__ __forceinline__ void gemm_mainloop(const u16* __restrict__ Ab, const u16* __restrict__ Bb, int K,
;                                               f32x4 (&acc)[8][4]) {
;     ...
;   const int nt = K / BK;
;   if (PRO) GLDS_STAGE(0, 0);
;   WAIT_V(0);
;   __syncthreads();
;   for (int t = 0; t < nt; ++t) {
;     int cur = t & 1;
;     if (t + 1 < nt) GLDS_STAGE(cur ^ 1, t + 1);
;     __builtin_amdgcn_sched_barrier(0);
;     KSTEP(cur, 0);
;     KSTEP(cur, 1);
;     WAIT_V(0);
;     __syncthreads();
;   }
.LBB0_3045:
	s_waitcnt lgkmcnt(7)
	v_mfma_f32_16x16x32_bf16 v[124:127], v[148:151], v[176:179], v[124:127]
	v_mfma_f32_16x16x32_bf16 v[108:111], v[152:155], v[176:179], v[108:111]
	v_lshl_add_u64 v[252:253], v[130:131], 0, s[0:1]
	v_lshl_add_u64 v[254:255], v[252:253], 0, s[26:27]
	global_load_lds_dwordx4 v[254:255], off
	s_add_u32 m0, m0, 0x2000
	v_mfma_f32_16x16x32_bf16 v[92:95], v[156:159], v[176:179], v[92:95]
	v_mfma_f32_16x16x32_bf16 v[76:79], v[160:163], v[176:179], v[76:79]
	s_waitcnt lgkmcnt(6)
	v_mfma_f32_16x16x32_bf16 v[120:123], v[148:151], v[184:187], v[120:123]
	v_lshl_add_u64 v[254:255], v[252:253], 0, s[30:31]
	global_load_lds_dwordx4 v[254:255], off
	s_add_u32 m0, m0, 0x2000
	v_mfma_f32_16x16x32_bf16 v[104:107], v[152:155], v[184:187], v[104:107]
	v_mfma_f32_16x16x32_bf16 v[88:91], v[156:159], v[184:187], v[88:91]
	v_mfma_f32_16x16x32_bf16 v[72:75], v[160:163], v[184:187], v[72:75]
	v_lshl_add_u64 v[254:255], v[252:253], 0, s[36:37]
	global_load_lds_dwordx4 v[254:255], off
	s_add_u32 m0, m0, 0x2000
	s_waitcnt lgkmcnt(5)
	v_mfma_f32_16x16x32_bf16 v[116:119], v[148:151], v[188:191], v[116:119]
	v_mfma_f32_16x16x32_bf16 v[100:103], v[152:155], v[188:191], v[100:103]
	v_mfma_f32_16x16x32_bf16 v[84:87], v[156:159], v[188:191], v[84:87]
	v_lshl_add_u64 v[254:255], v[252:253], 0, s[40:41]
	global_load_lds_dwordx4 v[254:255], off
	v_mfma_f32_16x16x32_bf16 v[68:71], v[160:163], v[188:191], v[68:71]
	s_waitcnt lgkmcnt(1)
	v_mfma_f32_16x16x32_bf16 v[112:115], v[148:151], v[192:195], v[112:115]
	ds_read_b128 v[148:151], v196 offset:1024
	v_mfma_f32_16x16x32_bf16 v[96:99], v[152:155], v[192:195], v[96:99]
	ds_read_b128 v[152:155], v197 offset:1024
	v_mfma_f32_16x16x32_bf16 v[80:83], v[156:159], v[192:195], v[80:83]
	ds_read_b128 v[156:159], v198 offset:1024
	v_mfma_f32_16x16x32_bf16 v[64:67], v[160:163], v[192:195], v[64:67]
	ds_read_b128 v[160:163], v199 offset:1024
	v_mfma_f32_16x16x32_bf16 v[60:63], v[164:167], v[176:179], v[60:63]
	v_mfma_f32_16x16x32_bf16 v[44:47], v[168:171], v[176:179], v[44:47]
	v_mfma_f32_16x16x32_bf16 v[28:31], v[172:175], v[176:179], v[28:31]
	s_waitcnt lgkmcnt(4)
	v_mfma_f32_16x16x32_bf16 v[12:15], v[180:183], v[176:179], v[12:15]
	ds_read_b128 v[176:179], v250 offset:33792
	v_mfma_f32_16x16x32_bf16 v[56:59], v[164:167], v[184:187], v[56:59]
	v_mfma_f32_16x16x32_bf16 v[40:43], v[168:171], v[184:187], v[40:43]
	v_mfma_f32_16x16x32_bf16 v[24:27], v[172:175], v[184:187], v[24:27]
	v_mfma_f32_16x16x32_bf16 v[8:11], v[180:183], v[184:187], v[8:11]
	ds_read_b128 v[184:187], v250 offset:35840
	v_mfma_f32_16x16x32_bf16 v[52:55], v[164:167], v[188:191], v[52:55]
	v_mfma_f32_16x16x32_bf16 v[36:39], v[168:171], v[188:191], v[36:39]
	v_mfma_f32_16x16x32_bf16 v[20:23], v[172:175], v[188:191], v[20:23]
	v_mfma_f32_16x16x32_bf16 v[4:7], v[180:183], v[188:191], v[4:7]
	ds_read_b128 v[188:191], v250 offset:37888
	v_mfma_f32_16x16x32_bf16 v[48:51], v[164:167], v[192:195], v[48:51]
	ds_read_b128 v[164:167], v200 offset:1024
	v_mfma_f32_16x16x32_bf16 v[32:35], v[168:171], v[192:195], v[32:35]
	ds_read_b128 v[168:171], v201 offset:1024
	v_mfma_f32_16x16x32_bf16 v[16:19], v[172:175], v[192:195], v[16:19]
	ds_read_b128 v[172:175], v202 offset:1024
	v_mfma_f32_16x16x32_bf16 v[0:3], v[180:183], v[192:195], v[0:3]
	ds_read_b128 v[192:195], v250 offset:39936
	ds_read_b128 v[180:183], v203 offset:1024
	s_waitcnt lgkmcnt(7)
	v_mfma_f32_16x16x32_bf16 v[124:127], v[148:151], v[176:179], v[124:127]
	v_mfma_f32_16x16x32_bf16 v[108:111], v[152:155], v[176:179], v[108:111]
	v_mfma_f32_16x16x32_bf16 v[92:95], v[156:159], v[176:179], v[92:95]
	v_mfma_f32_16x16x32_bf16 v[76:79], v[160:163], v[176:179], v[76:79]
	s_waitcnt lgkmcnt(6)
	v_mfma_f32_16x16x32_bf16 v[120:123], v[148:151], v[184:187], v[120:123]
	v_mfma_f32_16x16x32_bf16 v[104:107], v[152:155], v[184:187], v[104:107]
	v_mfma_f32_16x16x32_bf16 v[88:91], v[156:159], v[184:187], v[88:91]
	v_mfma_f32_16x16x32_bf16 v[72:75], v[160:163], v[184:187], v[72:75]
	s_waitcnt lgkmcnt(5)
	v_mfma_f32_16x16x32_bf16 v[116:119], v[148:151], v[188:191], v[116:119]
	v_mfma_f32_16x16x32_bf16 v[100:103], v[152:155], v[188:191], v[100:103]
	v_mfma_f32_16x16x32_bf16 v[84:87], v[156:159], v[188:191], v[84:87]
	v_mfma_f32_16x16x32_bf16 v[68:71], v[160:163], v[188:191], v[68:71]
	s_waitcnt lgkmcnt(1)
	v_mfma_f32_16x16x32_bf16 v[112:115], v[148:151], v[192:195], v[112:115]
	v_mfma_f32_16x16x32_bf16 v[96:99], v[152:155], v[192:195], v[96:99]
	v_mfma_f32_16x16x32_bf16 v[80:83], v[156:159], v[192:195], v[80:83]
	v_mfma_f32_16x16x32_bf16 v[64:67], v[160:163], v[192:195], v[64:67]
	s_add_u32 s0, s0, 0x80
	s_addc_u32 s1, s1, 0
	s_add_i32 s17, s17, 0x10000
	s_cmpk_lg_i32 s0, 0x780
	s_waitcnt vmcnt(0) lgkmcnt(0)
	s_barrier
; #define WAIT_V(n) asm volatile("s_waitcnt vmcnt(%0)" ::"n"(n) : "memory")
; template <bool PRO>
; __device__ __forceinline__ void gemm_mainloop(const u16* __restrict__ Ab, const u16* __restrict__ Bb, int K,
;                                               f32x4 (&acc)[8][4]) {
;     ...
;   const int nt = K / BK;
;   if (PRO) GLDS_STAGE(0, 0);
;   WAIT_V(0);
;   __syncthreads();
;   for (int t = 0; t < nt; ++t) {
;     int cur = t & 1;
;     if (t + 1 < nt) GLDS_STAGE(cur ^ 1, t + 1);
;     __builtin_amdgcn_sched_barrier(0);
;     KSTEP(cur, 0);
;     KSTEP(cur, 1);
;     WAIT_V(0);
;     __syncthreads();
;   }
	s_cbranch_scc0 .Lpipe_exit_3045
	s_and_b32 s19, s17, 0x10000
	v_or_b32_e32 v247, s19, v138
	v_or_b32_e32 v248, s19, v139
	v_add_u32_e32 v196, v247, v146
	v_add_u32_e32 v197, v248, v144
	v_mfma_f32_16x16x32_bf16 v[60:63], v[164:167], v[176:179], v[60:63]
	v_add_u32_e32 v198, v248, v147
	v_add_u32_e32 v199, v248, v145
	v_add_u32_e32 v200, v248, v143
	v_add_u32_e32 v201, v248, v142
	v_mfma_f32_16x16x32_bf16 v[44:47], v[168:171], v[176:179], v[44:47]
	v_add_u32_e32 v202, v248, v141
	v_add_u32_e32 v203, v248, v140
	v_add_u32_e32 v249, v247, v136
	v_or_b32_e32 v250, s19, v135
	v_mfma_f32_16x16x32_bf16 v[28:31], v[172:175], v[176:179], v[28:31]
	ds_read_b128 v[148:151], v196
	ds_read_b128 v[152:155], v197
	v_mfma_f32_16x16x32_bf16 v[12:15], v[180:183], v[176:179], v[12:15]
	ds_read_b128 v[156:159], v198
	ds_read_b128 v[160:163], v199
	v_mfma_f32_16x16x32_bf16 v[56:59], v[164:167], v[184:187], v[56:59]
	ds_read_b128 v[176:179], v249 offset:32768
	s_xor_b32 s50, s19, 0x10000
	v_add_u32_e32 v251, s50, v137
	v_mfma_f32_16x16x32_bf16 v[40:43], v[168:171], v[184:187], v[40:43]
	v_lshl_add_u64 v[252:253], v[128:129], 0, s[0:1]
	v_readfirstlane_b32 s50, v251
	s_mov_b32 m0, s50
	v_mfma_f32_16x16x32_bf16 v[24:27], v[172:175], v[184:187], v[24:27]
	v_lshl_add_u64 v[254:255], v[252:253], 0, s[24:25]
	global_load_lds_dwordx4 v[254:255], off
	s_add_u32 m0, m0, 0x2000
	v_mfma_f32_16x16x32_bf16 v[8:11], v[180:183], v[184:187], v[8:11]
	ds_read_b128 v[184:187], v249 offset:34816
	v_mfma_f32_16x16x32_bf16 v[52:55], v[164:167], v[188:191], v[52:55]
	v_lshl_add_u64 v[254:255], v[252:253], 0, s[28:29]
	global_load_lds_dwordx4 v[254:255], off
	s_add_u32 m0, m0, 0x2000
	v_mfma_f32_16x16x32_bf16 v[36:39], v[168:171], v[188:191], v[36:39]
	v_mfma_f32_16x16x32_bf16 v[20:23], v[172:175], v[188:191], v[20:23]
	v_lshl_add_u64 v[254:255], v[252:253], 0, s[34:35]
	global_load_lds_dwordx4 v[254:255], off
	s_add_u32 m0, m0, 0x2000
	v_mfma_f32_16x16x32_bf16 v[4:7], v[180:183], v[188:191], v[4:7]
	ds_read_b128 v[188:191], v249 offset:36864
	v_mfma_f32_16x16x32_bf16 v[48:51], v[164:167], v[192:195], v[48:51]
	ds_read_b128 v[164:167], v200
	v_lshl_add_u64 v[254:255], v[252:253], 0, s[38:39]
	global_load_lds_dwordx4 v[254:255], off
	s_add_u32 m0, m0, 0x2000
	v_mfma_f32_16x16x32_bf16 v[32:35], v[168:171], v[192:195], v[32:35]
	ds_read_b128 v[168:171], v201
	v_mfma_f32_16x16x32_bf16 v[16:19], v[172:175], v[192:195], v[16:19]
	ds_read_b128 v[172:175], v202
	v_mfma_f32_16x16x32_bf16 v[0:3], v[180:183], v[192:195], v[0:3]
	ds_read_b128 v[192:195], v249 offset:38912
	ds_read_b128 v[180:183], v203
	s_branch .LBB0_3045

; #define WAIT_V(n) asm volatile("s_waitcnt vmcnt(%0)" ::"n"(n) : "memory")
; template <bool PRO>
; __device__ __forceinline__ void gemm_mainloop(const u16* __restrict__ Ab, const u16* __restrict__ Bb, int K,
;                                               f32x4 (&acc)[8][4]) {
;     ...
;   const int nt = K / BK;
;   if (PRO) GLDS_STAGE(0, 0);
;   WAIT_V(0);
;   __syncthreads();
;   for (int t = 0; t < nt; ++t) {
;     int cur = t & 1;
;     if (t + 1 < nt) GLDS_STAGE(cur ^ 1, t + 1);
;     __builtin_amdgcn_sched_barrier(0);
;     KSTEP(cur, 0);
;     KSTEP(cur, 1);
;     WAIT_V(0);
;     __syncthreads();
;   }
.LBB0_3143:
	s_waitcnt lgkmcnt(7)
	v_mfma_f32_16x16x32_bf16 v[124:127], v[150:153], v[178:181], v[124:127]
	v_mfma_f32_16x16x32_bf16 v[108:111], v[154:157], v[178:181], v[108:111]
	v_lshl_add_u64 v[252:253], v[132:133], 0, s[0:1]
	v_lshl_add_u64 v[254:255], v[252:253], 0, s[36:37]
	global_load_lds_dwordx4 v[254:255], off
	s_add_u32 m0, m0, 0x2000
	v_mfma_f32_16x16x32_bf16 v[92:95], v[158:161], v[178:181], v[92:95]
	v_mfma_f32_16x16x32_bf16 v[76:79], v[162:165], v[178:181], v[76:79]
	s_waitcnt lgkmcnt(6)
	v_mfma_f32_16x16x32_bf16 v[120:123], v[150:153], v[186:189], v[120:123]
	v_lshl_add_u64 v[254:255], v[252:253], 0, s[40:41]
	global_load_lds_dwordx4 v[254:255], off
	s_add_u32 m0, m0, 0x2000
	v_mfma_f32_16x16x32_bf16 v[104:107], v[154:157], v[186:189], v[104:107]
	v_mfma_f32_16x16x32_bf16 v[88:91], v[158:161], v[186:189], v[88:91]
	v_mfma_f32_16x16x32_bf16 v[72:75], v[162:165], v[186:189], v[72:75]
	v_lshl_add_u64 v[254:255], v[252:253], 0, s[44:45]
	global_load_lds_dwordx4 v[254:255], off
	s_add_u32 m0, m0, 0x2000
	s_waitcnt lgkmcnt(5)
	v_mfma_f32_16x16x32_bf16 v[116:119], v[150:153], v[190:193], v[116:119]
	v_mfma_f32_16x16x32_bf16 v[100:103], v[154:157], v[190:193], v[100:103]
	v_mfma_f32_16x16x32_bf16 v[84:87], v[158:161], v[190:193], v[84:87]
	v_lshl_add_u64 v[254:255], v[252:253], 0, s[50:51]
	global_load_lds_dwordx4 v[254:255], off
	v_mfma_f32_16x16x32_bf16 v[68:71], v[162:165], v[190:193], v[68:71]
	s_waitcnt lgkmcnt(1)
	v_mfma_f32_16x16x32_bf16 v[112:115], v[150:153], v[194:197], v[112:115]
	ds_read_b128 v[150:153], v198 offset:1024
	v_mfma_f32_16x16x32_bf16 v[96:99], v[154:157], v[194:197], v[96:99]
	ds_read_b128 v[154:157], v199 offset:1024
	v_mfma_f32_16x16x32_bf16 v[80:83], v[158:161], v[194:197], v[80:83]
	ds_read_b128 v[158:161], v200 offset:1024
	v_mfma_f32_16x16x32_bf16 v[64:67], v[162:165], v[194:197], v[64:67]
	ds_read_b128 v[162:165], v201 offset:1024
	v_mfma_f32_16x16x32_bf16 v[60:63], v[166:169], v[178:181], v[60:63]
	v_mfma_f32_16x16x32_bf16 v[44:47], v[170:173], v[178:181], v[44:47]
	v_mfma_f32_16x16x32_bf16 v[28:31], v[174:177], v[178:181], v[28:31]
	s_waitcnt lgkmcnt(4)
	v_mfma_f32_16x16x32_bf16 v[12:15], v[182:185], v[178:181], v[12:15]
	ds_read_b128 v[178:181], v149 offset:33792
	v_mfma_f32_16x16x32_bf16 v[56:59], v[166:169], v[186:189], v[56:59]
	v_mfma_f32_16x16x32_bf16 v[40:43], v[170:173], v[186:189], v[40:43]
	v_mfma_f32_16x16x32_bf16 v[24:27], v[174:177], v[186:189], v[24:27]
	v_mfma_f32_16x16x32_bf16 v[8:11], v[182:185], v[186:189], v[8:11]
	ds_read_b128 v[186:189], v149 offset:35840
	v_mfma_f32_16x16x32_bf16 v[52:55], v[166:169], v[190:193], v[52:55]
	v_mfma_f32_16x16x32_bf16 v[36:39], v[170:173], v[190:193], v[36:39]
	v_mfma_f32_16x16x32_bf16 v[20:23], v[174:177], v[190:193], v[20:23]
	v_mfma_f32_16x16x32_bf16 v[4:7], v[182:185], v[190:193], v[4:7]
	ds_read_b128 v[190:193], v149 offset:37888
	v_mfma_f32_16x16x32_bf16 v[48:51], v[166:169], v[194:197], v[48:51]
	ds_read_b128 v[166:169], v202 offset:1024
	v_mfma_f32_16x16x32_bf16 v[32:35], v[170:173], v[194:197], v[32:35]
	ds_read_b128 v[170:173], v203 offset:1024
	v_mfma_f32_16x16x32_bf16 v[16:19], v[174:177], v[194:197], v[16:19]
	ds_read_b128 v[174:177], v205 offset:1024
	v_mfma_f32_16x16x32_bf16 v[0:3], v[182:185], v[194:197], v[0:3]
	ds_read_b128 v[194:197], v149 offset:39936
	ds_read_b128 v[182:185], v206 offset:1024
	s_waitcnt lgkmcnt(7)
	v_mfma_f32_16x16x32_bf16 v[124:127], v[150:153], v[178:181], v[124:127]
	v_mfma_f32_16x16x32_bf16 v[108:111], v[154:157], v[178:181], v[108:111]
	v_mfma_f32_16x16x32_bf16 v[92:95], v[158:161], v[178:181], v[92:95]
	v_mfma_f32_16x16x32_bf16 v[76:79], v[162:165], v[178:181], v[76:79]
	s_waitcnt lgkmcnt(6)
	v_mfma_f32_16x16x32_bf16 v[120:123], v[150:153], v[186:189], v[120:123]
	v_mfma_f32_16x16x32_bf16 v[104:107], v[154:157], v[186:189], v[104:107]
	v_mfma_f32_16x16x32_bf16 v[88:91], v[158:161], v[186:189], v[88:91]
	v_mfma_f32_16x16x32_bf16 v[72:75], v[162:165], v[186:189], v[72:75]
	s_waitcnt lgkmcnt(5)
	v_mfma_f32_16x16x32_bf16 v[116:119], v[150:153], v[190:193], v[116:119]
	v_mfma_f32_16x16x32_bf16 v[100:103], v[154:157], v[190:193], v[100:103]
	v_mfma_f32_16x16x32_bf16 v[84:87], v[158:161], v[190:193], v[84:87]
	v_mfma_f32_16x16x32_bf16 v[68:71], v[162:165], v[190:193], v[68:71]
	s_waitcnt lgkmcnt(1)
	v_mfma_f32_16x16x32_bf16 v[112:115], v[150:153], v[194:197], v[112:115]
	v_mfma_f32_16x16x32_bf16 v[96:99], v[154:157], v[194:197], v[96:99]
	v_mfma_f32_16x16x32_bf16 v[80:83], v[158:161], v[194:197], v[80:83]
	v_mfma_f32_16x16x32_bf16 v[64:67], v[162:165], v[194:197], v[64:67]
	s_add_i32 s6, s6, 0x10000
	s_add_u32 s0, s0, 0x80
	s_addc_u32 s1, s1, 0
	s_cmpk_lg_i32 s0, 0x780
	s_waitcnt vmcnt(0) lgkmcnt(0)
	s_barrier
; #define WAIT_V(n) asm volatile("s_waitcnt vmcnt(%0)" ::"n"(n) : "memory")
; template <bool PRO>
; __device__ __forceinline__ void gemm_mainloop(const u16* __restrict__ Ab, const u16* __restrict__ Bb, int K,
;                                               f32x4 (&acc)[8][4]) {
;     ...
;   const int nt = K / BK;
;   if (PRO) GLDS_STAGE(0, 0);
;   WAIT_V(0);
;   __syncthreads();
;   for (int t = 0; t < nt; ++t) {
;     int cur = t & 1;
;     if (t + 1 < nt) GLDS_STAGE(cur ^ 1, t + 1);
;     __builtin_amdgcn_sched_barrier(0);
;     KSTEP(cur, 0);
;     KSTEP(cur, 1);
;     WAIT_V(0);
;     __syncthreads();
;   }
	s_cbranch_scc0 .Lpipe_exit_3143
	s_and_b32 s7, s6, 0x10000
	v_or_b32_e32 v247, s7, v139
	v_or_b32_e32 v248, s7, v140
	v_add_u32_e32 v198, v247, v147
	v_add_u32_e32 v199, v248, v145
	v_mfma_f32_16x16x32_bf16 v[60:63], v[166:169], v[178:181], v[60:63]
	v_add_u32_e32 v200, v248, v148
	v_add_u32_e32 v201, v248, v146
	v_add_u32_e32 v202, v248, v144
	v_add_u32_e32 v203, v248, v143
	v_mfma_f32_16x16x32_bf16 v[44:47], v[170:173], v[178:181], v[44:47]
	v_add_u32_e32 v205, v248, v142
	v_add_u32_e32 v206, v248, v141
	v_add_u32_e32 v249, v247, v137
	v_or_b32_e32 v149, s7, v128
	v_mfma_f32_16x16x32_bf16 v[28:31], v[174:177], v[178:181], v[28:31]
	ds_read_b128 v[150:153], v198
	ds_read_b128 v[154:157], v199
	v_mfma_f32_16x16x32_bf16 v[12:15], v[182:185], v[178:181], v[12:15]
	ds_read_b128 v[158:161], v200
	ds_read_b128 v[162:165], v201
	v_mfma_f32_16x16x32_bf16 v[56:59], v[166:169], v[186:189], v[56:59]
	ds_read_b128 v[178:181], v249 offset:32768
	s_xor_b32 s8, s7, 0x10000
	v_add_u32_e32 v250, s8, v138
	v_mfma_f32_16x16x32_bf16 v[40:43], v[170:173], v[186:189], v[40:43]
	v_lshl_add_u64 v[252:253], v[130:131], 0, s[0:1]
	v_readfirstlane_b32 s8, v250
	s_mov_b32 m0, s8
	v_mfma_f32_16x16x32_bf16 v[24:27], v[174:177], v[186:189], v[24:27]
	v_lshl_add_u64 v[254:255], v[252:253], 0, s[34:35]
	global_load_lds_dwordx4 v[254:255], off
	s_add_u32 m0, m0, 0x2000
	v_mfma_f32_16x16x32_bf16 v[8:11], v[182:185], v[186:189], v[8:11]
	ds_read_b128 v[186:189], v249 offset:34816
	v_mfma_f32_16x16x32_bf16 v[52:55], v[166:169], v[190:193], v[52:55]
	v_lshl_add_u64 v[254:255], v[252:253], 0, s[38:39]
	global_load_lds_dwordx4 v[254:255], off
	s_add_u32 m0, m0, 0x2000
	v_mfma_f32_16x16x32_bf16 v[36:39], v[170:173], v[190:193], v[36:39]
	v_mfma_f32_16x16x32_bf16 v[20:23], v[174:177], v[190:193], v[20:23]
	v_lshl_add_u64 v[254:255], v[252:253], 0, s[42:43]
	global_load_lds_dwordx4 v[254:255], off
	s_add_u32 m0, m0, 0x2000
	v_mfma_f32_16x16x32_bf16 v[4:7], v[182:185], v[190:193], v[4:7]
	ds_read_b128 v[190:193], v249 offset:36864
	v_mfma_f32_16x16x32_bf16 v[48:51], v[166:169], v[194:197], v[48:51]
	ds_read_b128 v[166:169], v202
	v_lshl_add_u64 v[254:255], v[252:253], 0, s[46:47]
	global_load_lds_dwordx4 v[254:255], off
	s_add_u32 m0, m0, 0x2000
	v_mfma_f32_16x16x32_bf16 v[32:35], v[170:173], v[194:197], v[32:35]
	ds_read_b128 v[170:173], v203
	v_mfma_f32_16x16x32_bf16 v[16:19], v[174:177], v[194:197], v[16:19]
	ds_read_b128 v[174:177], v205
	v_mfma_f32_16x16x32_bf16 v[0:3], v[182:185], v[194:197], v[0:3]
	ds_read_b128 v[194:197], v249 offset:38912
	ds_read_b128 v[182:185], v206
	s_branch .LBB0_3143

; #define WAIT_V(n) asm volatile("s_waitcnt vmcnt(%0)" ::"n"(n) : "memory")
; template <bool PRO>
; __device__ __forceinline__ void gemm_mainloop(const u16* __restrict__ Ab, const u16* __restrict__ Bb, int K,
;                                               f32x4 (&acc)[8][4]) {
;     ...
;   const int nt = K / BK;
;   if (PRO) GLDS_STAGE(0, 0);
;   WAIT_V(0);
;   __syncthreads();
;   for (int t = 0; t < nt; ++t) {
;     int cur = t & 1;
;     if (t + 1 < nt) GLDS_STAGE(cur ^ 1, t + 1);
;     __builtin_amdgcn_sched_barrier(0);
;     KSTEP(cur, 0);
;     KSTEP(cur, 1);
;     WAIT_V(0);
;     __syncthreads();
;   }
.LBB0_3163:
	s_waitcnt lgkmcnt(7)
	v_mfma_f32_16x16x32_bf16 v[124:127], v[150:153], v[178:181], v[124:127]
	v_mfma_f32_16x16x32_bf16 v[108:111], v[154:157], v[178:181], v[108:111]
	v_lshl_add_u64 v[252:253], v[130:131], 0, s[0:1]
	v_lshl_add_u64 v[254:255], v[252:253], 0, s[16:17]
	global_load_lds_dwordx4 v[254:255], off
	s_add_u32 m0, m0, 0x2000
	v_mfma_f32_16x16x32_bf16 v[92:95], v[158:161], v[178:181], v[92:95]
	v_mfma_f32_16x16x32_bf16 v[76:79], v[162:165], v[178:181], v[76:79]
	s_waitcnt lgkmcnt(6)
	v_mfma_f32_16x16x32_bf16 v[120:123], v[150:153], v[186:189], v[120:123]
	v_lshl_add_u64 v[254:255], v[252:253], 0, s[20:21]
	global_load_lds_dwordx4 v[254:255], off
	s_add_u32 m0, m0, 0x2000
	v_mfma_f32_16x16x32_bf16 v[104:107], v[154:157], v[186:189], v[104:107]
	v_mfma_f32_16x16x32_bf16 v[88:91], v[158:161], v[186:189], v[88:91]
	v_mfma_f32_16x16x32_bf16 v[72:75], v[162:165], v[186:189], v[72:75]
	v_lshl_add_u64 v[254:255], v[252:253], 0, s[24:25]
	global_load_lds_dwordx4 v[254:255], off
	s_add_u32 m0, m0, 0x2000
	s_waitcnt lgkmcnt(5)
	v_mfma_f32_16x16x32_bf16 v[116:119], v[150:153], v[190:193], v[116:119]
	v_mfma_f32_16x16x32_bf16 v[100:103], v[154:157], v[190:193], v[100:103]
	v_mfma_f32_16x16x32_bf16 v[84:87], v[158:161], v[190:193], v[84:87]
	v_lshl_add_u64 v[254:255], v[252:253], 0, s[28:29]
	global_load_lds_dwordx4 v[254:255], off
	v_mfma_f32_16x16x32_bf16 v[68:71], v[162:165], v[190:193], v[68:71]
	s_waitcnt lgkmcnt(1)
	v_mfma_f32_16x16x32_bf16 v[112:115], v[150:153], v[194:197], v[112:115]
	ds_read_b128 v[150:153], v198 offset:1024
	v_mfma_f32_16x16x32_bf16 v[96:99], v[154:157], v[194:197], v[96:99]
	ds_read_b128 v[154:157], v199 offset:1024
	v_mfma_f32_16x16x32_bf16 v[80:83], v[158:161], v[194:197], v[80:83]
	ds_read_b128 v[158:161], v200 offset:1024
	v_mfma_f32_16x16x32_bf16 v[64:67], v[162:165], v[194:197], v[64:67]
	ds_read_b128 v[162:165], v201 offset:1024
	v_mfma_f32_16x16x32_bf16 v[60:63], v[166:169], v[178:181], v[60:63]
	v_mfma_f32_16x16x32_bf16 v[44:47], v[170:173], v[178:181], v[44:47]
	v_mfma_f32_16x16x32_bf16 v[28:31], v[174:177], v[178:181], v[28:31]
	s_waitcnt lgkmcnt(4)
	v_mfma_f32_16x16x32_bf16 v[12:15], v[182:185], v[178:181], v[12:15]
	ds_read_b128 v[178:181], v149 offset:33792
	v_mfma_f32_16x16x32_bf16 v[56:59], v[166:169], v[186:189], v[56:59]
	v_mfma_f32_16x16x32_bf16 v[40:43], v[170:173], v[186:189], v[40:43]
	v_mfma_f32_16x16x32_bf16 v[24:27], v[174:177], v[186:189], v[24:27]
	v_mfma_f32_16x16x32_bf16 v[8:11], v[182:185], v[186:189], v[8:11]
	ds_read_b128 v[186:189], v149 offset:35840
	v_mfma_f32_16x16x32_bf16 v[52:55], v[166:169], v[190:193], v[52:55]
	v_mfma_f32_16x16x32_bf16 v[36:39], v[170:173], v[190:193], v[36:39]
	v_mfma_f32_16x16x32_bf16 v[20:23], v[174:177], v[190:193], v[20:23]
	v_mfma_f32_16x16x32_bf16 v[4:7], v[182:185], v[190:193], v[4:7]
	ds_read_b128 v[190:193], v149 offset:37888
	v_mfma_f32_16x16x32_bf16 v[48:51], v[166:169], v[194:197], v[48:51]
	ds_read_b128 v[166:169], v202 offset:1024
	v_mfma_f32_16x16x32_bf16 v[32:35], v[170:173], v[194:197], v[32:35]
	ds_read_b128 v[170:173], v203 offset:1024
	v_mfma_f32_16x16x32_bf16 v[16:19], v[174:177], v[194:197], v[16:19]
	ds_read_b128 v[174:177], v205 offset:1024
	v_mfma_f32_16x16x32_bf16 v[0:3], v[182:185], v[194:197], v[0:3]
	ds_read_b128 v[194:197], v149 offset:39936
	ds_read_b128 v[182:185], v206 offset:1024
	s_waitcnt lgkmcnt(7)
	v_mfma_f32_16x16x32_bf16 v[124:127], v[150:153], v[178:181], v[124:127]
	v_mfma_f32_16x16x32_bf16 v[108:111], v[154:157], v[178:181], v[108:111]
	v_mfma_f32_16x16x32_bf16 v[92:95], v[158:161], v[178:181], v[92:95]
	v_mfma_f32_16x16x32_bf16 v[76:79], v[162:165], v[178:181], v[76:79]
	s_waitcnt lgkmcnt(6)
	v_mfma_f32_16x16x32_bf16 v[120:123], v[150:153], v[186:189], v[120:123]
	v_mfma_f32_16x16x32_bf16 v[104:107], v[154:157], v[186:189], v[104:107]
	v_mfma_f32_16x16x32_bf16 v[88:91], v[158:161], v[186:189], v[88:91]
	v_mfma_f32_16x16x32_bf16 v[72:75], v[162:165], v[186:189], v[72:75]
	s_waitcnt lgkmcnt(5)
	v_mfma_f32_16x16x32_bf16 v[116:119], v[150:153], v[190:193], v[116:119]
	v_mfma_f32_16x16x32_bf16 v[100:103], v[154:157], v[190:193], v[100:103]
	v_mfma_f32_16x16x32_bf16 v[84:87], v[158:161], v[190:193], v[84:87]
	v_mfma_f32_16x16x32_bf16 v[68:71], v[162:165], v[190:193], v[68:71]
	s_waitcnt lgkmcnt(1)
	v_mfma_f32_16x16x32_bf16 v[112:115], v[150:153], v[194:197], v[112:115]
	v_mfma_f32_16x16x32_bf16 v[96:99], v[154:157], v[194:197], v[96:99]
	v_mfma_f32_16x16x32_bf16 v[80:83], v[158:161], v[194:197], v[80:83]
	v_mfma_f32_16x16x32_bf16 v[64:67], v[162:165], v[194:197], v[64:67]
	s_add_u32 s0, s0, 0x80
	s_addc_u32 s1, s1, 0
	s_add_i32 s38, s38, 0x10000
	s_cmpk_lg_i32 s0, 0x1580
	s_waitcnt vmcnt(0) lgkmcnt(0)
	s_barrier
; #define WAIT_V(n) asm volatile("s_waitcnt vmcnt(%0)" ::"n"(n) : "memory")
; template <bool PRO>
; __device__ __forceinline__ void gemm_mainloop(const u16* __restrict__ Ab, const u16* __restrict__ Bb, int K,
;                                               f32x4 (&acc)[8][4]) {
;     ...
;   const int nt = K / BK;
;   if (PRO) GLDS_STAGE(0, 0);
;   WAIT_V(0);
;   __syncthreads();
;   for (int t = 0; t < nt; ++t) {
;     int cur = t & 1;
;     if (t + 1 < nt) GLDS_STAGE(cur ^ 1, t + 1);
;     __builtin_amdgcn_sched_barrier(0);
;     KSTEP(cur, 0);
;     KSTEP(cur, 1);
;     WAIT_V(0);
;     __syncthreads();
;   }
	s_cbranch_scc0 .Lpipe_exit_3163
	s_and_b32 s39, s38, 0x10000
	v_or_b32_e32 v247, s39, v139
	v_or_b32_e32 v248, s39, v140
	v_add_u32_e32 v198, v247, v147
	v_add_u32_e32 v199, v248, v145
	v_mfma_f32_16x16x32_bf16 v[60:63], v[166:169], v[178:181], v[60:63]
	v_add_u32_e32 v200, v248, v148
	v_add_u32_e32 v201, v248, v146
	v_add_u32_e32 v202, v248, v144
	v_add_u32_e32 v203, v248, v143
	v_mfma_f32_16x16x32_bf16 v[44:47], v[170:173], v[178:181], v[44:47]
	v_add_u32_e32 v205, v248, v142
	v_add_u32_e32 v206, v248, v141
	v_add_u32_e32 v249, v247, v137
	v_or_b32_e32 v149, s39, v136
	v_mfma_f32_16x16x32_bf16 v[28:31], v[174:177], v[178:181], v[28:31]
	ds_read_b128 v[150:153], v198
	ds_read_b128 v[154:157], v199
	v_mfma_f32_16x16x32_bf16 v[12:15], v[182:185], v[178:181], v[12:15]
	ds_read_b128 v[158:161], v200
	ds_read_b128 v[162:165], v201
	v_mfma_f32_16x16x32_bf16 v[56:59], v[166:169], v[186:189], v[56:59]
	ds_read_b128 v[178:181], v249 offset:32768
	s_xor_b32 s53, s39, 0x10000
	v_add_u32_e32 v250, s53, v138
	v_mfma_f32_16x16x32_bf16 v[40:43], v[170:173], v[186:189], v[40:43]
	v_lshl_add_u64 v[252:253], v[128:129], 0, s[0:1]
	v_readfirstlane_b32 s53, v250
	s_mov_b32 m0, s53
	v_mfma_f32_16x16x32_bf16 v[24:27], v[174:177], v[186:189], v[24:27]
	v_lshl_add_u64 v[254:255], v[252:253], 0, s[14:15]
	global_load_lds_dwordx4 v[254:255], off
	s_add_u32 m0, m0, 0x2000
	v_mfma_f32_16x16x32_bf16 v[8:11], v[182:185], v[186:189], v[8:11]
	ds_read_b128 v[186:189], v249 offset:34816
	v_mfma_f32_16x16x32_bf16 v[52:55], v[166:169], v[190:193], v[52:55]
	v_lshl_add_u64 v[254:255], v[252:253], 0, s[18:19]
	global_load_lds_dwordx4 v[254:255], off
	s_add_u32 m0, m0, 0x2000
	v_mfma_f32_16x16x32_bf16 v[36:39], v[170:173], v[190:193], v[36:39]
	v_mfma_f32_16x16x32_bf16 v[20:23], v[174:177], v[190:193], v[20:23]
	v_lshl_add_u64 v[254:255], v[252:253], 0, s[22:23]
	global_load_lds_dwordx4 v[254:255], off
	s_add_u32 m0, m0, 0x2000
	v_mfma_f32_16x16x32_bf16 v[4:7], v[182:185], v[190:193], v[4:7]
	ds_read_b128 v[190:193], v249 offset:36864
	v_mfma_f32_16x16x32_bf16 v[48:51], v[166:169], v[194:197], v[48:51]
	ds_read_b128 v[166:169], v202
	v_lshl_add_u64 v[254:255], v[252:253], 0, s[26:27]
	global_load_lds_dwordx4 v[254:255], off
	s_add_u32 m0, m0, 0x2000
	v_mfma_f32_16x16x32_bf16 v[32:35], v[170:173], v[194:197], v[32:35]
	ds_read_b128 v[170:173], v203
	v_mfma_f32_16x16x32_bf16 v[16:19], v[174:177], v[194:197], v[16:19]
	ds_read_b128 v[174:177], v205
	v_mfma_f32_16x16x32_bf16 v[0:3], v[182:185], v[194:197], v[0:3]
	ds_read_b128 v[194:197], v249 offset:38912
	ds_read_b128 v[182:185], v206
	s_branch .LBB0_3163

; #define WAIT_V(n) asm volatile("s_waitcnt vmcnt(%0)" ::"n"(n) : "memory")
; template <bool PRO>
; __device__ __forceinline__ void gemm_mainloop(const u16* __restrict__ Ab, const u16* __restrict__ Bb, int K,
;                                               f32x4 (&acc)[8][4]) {
;     ...
;   const int nt = K / BK;
;   if (PRO) GLDS_STAGE(0, 0);
;   WAIT_V(0);
;   __syncthreads();
;   for (int t = 0; t < nt; ++t) {
;     int cur = t & 1;
;     if (t + 1 < nt) GLDS_STAGE(cur ^ 1, t + 1);
;     __builtin_amdgcn_sched_barrier(0);
;     KSTEP(cur, 0);
;     KSTEP(cur, 1);
;     WAIT_V(0);
;     __syncthreads();
;   }
.LBB0_3275:
	s_waitcnt lgkmcnt(7)
	v_mfma_f32_16x16x32_bf16 v[124:127], v[150:153], v[178:181], v[124:127]
	v_mfma_f32_16x16x32_bf16 v[108:111], v[154:157], v[178:181], v[108:111]
	v_lshl_add_u64 v[252:253], v[130:131], 0, s[0:1]
	v_lshl_add_u64 v[254:255], v[252:253], 0, s[28:29]
	global_load_lds_dwordx4 v[254:255], off
	s_add_u32 m0, m0, 0x2000
	v_mfma_f32_16x16x32_bf16 v[92:95], v[158:161], v[178:181], v[92:95]
	v_mfma_f32_16x16x32_bf16 v[76:79], v[162:165], v[178:181], v[76:79]
	s_waitcnt lgkmcnt(6)
	v_mfma_f32_16x16x32_bf16 v[120:123], v[150:153], v[186:189], v[120:123]
	v_lshl_add_u64 v[254:255], v[252:253], 0, s[34:35]
	global_load_lds_dwordx4 v[254:255], off
	s_add_u32 m0, m0, 0x2000
	v_mfma_f32_16x16x32_bf16 v[104:107], v[154:157], v[186:189], v[104:107]
	v_mfma_f32_16x16x32_bf16 v[88:91], v[158:161], v[186:189], v[88:91]
	v_mfma_f32_16x16x32_bf16 v[72:75], v[162:165], v[186:189], v[72:75]
	v_lshl_add_u64 v[254:255], v[252:253], 0, s[38:39]
	global_load_lds_dwordx4 v[254:255], off
	s_add_u32 m0, m0, 0x2000
	s_waitcnt lgkmcnt(5)
	v_mfma_f32_16x16x32_bf16 v[116:119], v[150:153], v[190:193], v[116:119]
	v_mfma_f32_16x16x32_bf16 v[100:103], v[154:157], v[190:193], v[100:103]
	v_mfma_f32_16x16x32_bf16 v[84:87], v[158:161], v[190:193], v[84:87]
	v_lshl_add_u64 v[254:255], v[252:253], 0, s[42:43]
	global_load_lds_dwordx4 v[254:255], off
	v_mfma_f32_16x16x32_bf16 v[68:71], v[162:165], v[190:193], v[68:71]
	s_waitcnt lgkmcnt(1)
	v_mfma_f32_16x16x32_bf16 v[112:115], v[150:153], v[194:197], v[112:115]
	ds_read_b128 v[150:153], v198 offset:1024
	v_mfma_f32_16x16x32_bf16 v[96:99], v[154:157], v[194:197], v[96:99]
	ds_read_b128 v[154:157], v199 offset:1024
	v_mfma_f32_16x16x32_bf16 v[80:83], v[158:161], v[194:197], v[80:83]
	ds_read_b128 v[158:161], v200 offset:1024
	v_mfma_f32_16x16x32_bf16 v[64:67], v[162:165], v[194:197], v[64:67]
	ds_read_b128 v[162:165], v201 offset:1024
	v_mfma_f32_16x16x32_bf16 v[60:63], v[166:169], v[178:181], v[60:63]
	v_mfma_f32_16x16x32_bf16 v[44:47], v[170:173], v[178:181], v[44:47]
	v_mfma_f32_16x16x32_bf16 v[28:31], v[174:177], v[178:181], v[28:31]
	s_waitcnt lgkmcnt(4)
	v_mfma_f32_16x16x32_bf16 v[12:15], v[182:185], v[178:181], v[12:15]
	ds_read_b128 v[178:181], v149 offset:33792
	v_mfma_f32_16x16x32_bf16 v[56:59], v[166:169], v[186:189], v[56:59]
	v_mfma_f32_16x16x32_bf16 v[40:43], v[170:173], v[186:189], v[40:43]
	v_mfma_f32_16x16x32_bf16 v[24:27], v[174:177], v[186:189], v[24:27]
	v_mfma_f32_16x16x32_bf16 v[8:11], v[182:185], v[186:189], v[8:11]
	ds_read_b128 v[186:189], v149 offset:35840
	v_mfma_f32_16x16x32_bf16 v[52:55], v[166:169], v[190:193], v[52:55]
	v_mfma_f32_16x16x32_bf16 v[36:39], v[170:173], v[190:193], v[36:39]
	v_mfma_f32_16x16x32_bf16 v[20:23], v[174:177], v[190:193], v[20:23]
	v_mfma_f32_16x16x32_bf16 v[4:7], v[182:185], v[190:193], v[4:7]
	ds_read_b128 v[190:193], v149 offset:37888
	v_mfma_f32_16x16x32_bf16 v[48:51], v[166:169], v[194:197], v[48:51]
	ds_read_b128 v[166:169], v202 offset:1024
	v_mfma_f32_16x16x32_bf16 v[32:35], v[170:173], v[194:197], v[32:35]
	ds_read_b128 v[170:173], v203 offset:1024
	v_mfma_f32_16x16x32_bf16 v[16:19], v[174:177], v[194:197], v[16:19]
	ds_read_b128 v[174:177], v205 offset:1024
	v_mfma_f32_16x16x32_bf16 v[0:3], v[182:185], v[194:197], v[0:3]
	ds_read_b128 v[194:197], v149 offset:39936
	ds_read_b128 v[182:185], v206 offset:1024
	s_waitcnt lgkmcnt(7)
	v_mfma_f32_16x16x32_bf16 v[124:127], v[150:153], v[178:181], v[124:127]
	v_mfma_f32_16x16x32_bf16 v[108:111], v[154:157], v[178:181], v[108:111]
	v_mfma_f32_16x16x32_bf16 v[92:95], v[158:161], v[178:181], v[92:95]
	v_mfma_f32_16x16x32_bf16 v[76:79], v[162:165], v[178:181], v[76:79]
	s_waitcnt lgkmcnt(6)
	v_mfma_f32_16x16x32_bf16 v[120:123], v[150:153], v[186:189], v[120:123]
	v_mfma_f32_16x16x32_bf16 v[104:107], v[154:157], v[186:189], v[104:107]
	v_mfma_f32_16x16x32_bf16 v[88:91], v[158:161], v[186:189], v[88:91]
	v_mfma_f32_16x16x32_bf16 v[72:75], v[162:165], v[186:189], v[72:75]
	s_waitcnt lgkmcnt(5)
	v_mfma_f32_16x16x32_bf16 v[116:119], v[150:153], v[190:193], v[116:119]
	v_mfma_f32_16x16x32_bf16 v[100:103], v[154:157], v[190:193], v[100:103]
	v_mfma_f32_16x16x32_bf16 v[84:87], v[158:161], v[190:193], v[84:87]
	v_mfma_f32_16x16x32_bf16 v[68:71], v[162:165], v[190:193], v[68:71]
	s_waitcnt lgkmcnt(1)
	v_mfma_f32_16x16x32_bf16 v[112:115], v[150:153], v[194:197], v[112:115]
	v_mfma_f32_16x16x32_bf16 v[96:99], v[154:157], v[194:197], v[96:99]
	v_mfma_f32_16x16x32_bf16 v[80:83], v[158:161], v[194:197], v[80:83]
	v_mfma_f32_16x16x32_bf16 v[64:67], v[162:165], v[194:197], v[64:67]
	s_add_i32 s6, s6, 0x10000
	s_add_u32 s0, s0, 0x80
	s_addc_u32 s1, s1, 0
	s_cmpk_lg_i32 s0, 0x780
	s_waitcnt vmcnt(0) lgkmcnt(0)
	s_barrier
; #define WAIT_V(n) asm volatile("s_waitcnt vmcnt(%0)" ::"n"(n) : "memory")
; template <bool PRO>
; __device__ __forceinline__ void gemm_mainloop(const u16* __restrict__ Ab, const u16* __restrict__ Bb, int K,
;                                               f32x4 (&acc)[8][4]) {
;     ...
;   const int nt = K / BK;
;   if (PRO) GLDS_STAGE(0, 0);
;   WAIT_V(0);
;   __syncthreads();
;   for (int t = 0; t < nt; ++t) {
;     int cur = t & 1;
;     if (t + 1 < nt) GLDS_STAGE(cur ^ 1, t + 1);
;     __builtin_amdgcn_sched_barrier(0);
;     KSTEP(cur, 0);
;     KSTEP(cur, 1);
;     WAIT_V(0);
;     __syncthreads();
;   }
	s_cbranch_scc0 .Lpipe_exit_3275
	s_and_b32 s7, s6, 0x10000
	v_or_b32_e32 v247, s7, v139
	v_or_b32_e32 v248, s7, v140
	v_add_u32_e32 v198, v247, v147
	v_add_u32_e32 v199, v248, v145
	v_mfma_f32_16x16x32_bf16 v[60:63], v[166:169], v[178:181], v[60:63]
	v_add_u32_e32 v200, v248, v148
	v_add_u32_e32 v201, v248, v146
	v_add_u32_e32 v202, v248, v144
	v_add_u32_e32 v203, v248, v143
	v_mfma_f32_16x16x32_bf16 v[44:47], v[170:173], v[178:181], v[44:47]
	v_add_u32_e32 v205, v248, v142
	v_add_u32_e32 v206, v248, v141
	v_add_u32_e32 v249, v247, v137
	v_or_b32_e32 v149, s7, v136
	v_mfma_f32_16x16x32_bf16 v[28:31], v[174:177], v[178:181], v[28:31]
	ds_read_b128 v[150:153], v198
	ds_read_b128 v[154:157], v199
	v_mfma_f32_16x16x32_bf16 v[12:15], v[182:185], v[178:181], v[12:15]
	ds_read_b128 v[158:161], v200
	ds_read_b128 v[162:165], v201
	v_mfma_f32_16x16x32_bf16 v[56:59], v[166:169], v[186:189], v[56:59]
	ds_read_b128 v[178:181], v249 offset:32768
	s_xor_b32 s19, s7, 0x10000
	v_add_u32_e32 v250, s19, v138
	v_mfma_f32_16x16x32_bf16 v[40:43], v[170:173], v[186:189], v[40:43]
	v_lshl_add_u64 v[252:253], v[128:129], 0, s[0:1]
	v_readfirstlane_b32 s19, v250
	s_mov_b32 m0, s19
	v_mfma_f32_16x16x32_bf16 v[24:27], v[174:177], v[186:189], v[24:27]
	v_lshl_add_u64 v[254:255], v[252:253], 0, s[26:27]
	global_load_lds_dwordx4 v[254:255], off
	s_add_u32 m0, m0, 0x2000
	v_mfma_f32_16x16x32_bf16 v[8:11], v[182:185], v[186:189], v[8:11]
	ds_read_b128 v[186:189], v249 offset:34816
	v_mfma_f32_16x16x32_bf16 v[52:55], v[166:169], v[190:193], v[52:55]
	v_lshl_add_u64 v[254:255], v[252:253], 0, s[30:31]
	global_load_lds_dwordx4 v[254:255], off
	s_add_u32 m0, m0, 0x2000
	v_mfma_f32_16x16x32_bf16 v[36:39], v[170:173], v[190:193], v[36:39]
	v_mfma_f32_16x16x32_bf16 v[20:23], v[174:177], v[190:193], v[20:23]
	v_lshl_add_u64 v[254:255], v[252:253], 0, s[36:37]
	global_load_lds_dwordx4 v[254:255], off
	s_add_u32 m0, m0, 0x2000
	v_mfma_f32_16x16x32_bf16 v[4:7], v[182:185], v[190:193], v[4:7]
	ds_read_b128 v[190:193], v249 offset:36864
	v_mfma_f32_16x16x32_bf16 v[48:51], v[166:169], v[194:197], v[48:51]
	ds_read_b128 v[166:169], v202
	v_lshl_add_u64 v[254:255], v[252:253], 0, s[40:41]
	global_load_lds_dwordx4 v[254:255], off
	s_add_u32 m0, m0, 0x2000
	v_mfma_f32_16x16x32_bf16 v[32:35], v[170:173], v[194:197], v[32:35]
	ds_read_b128 v[170:173], v203
	v_mfma_f32_16x16x32_bf16 v[16:19], v[174:177], v[194:197], v[16:19]
	ds_read_b128 v[174:177], v205
	v_mfma_f32_16x16x32_bf16 v[0:3], v[182:185], v[194:197], v[0:3]
	ds_read_b128 v[194:197], v249 offset:38912
	ds_read_b128 v[182:185], v206
	s_branch .LBB0_3275
